# all per-phase s_setprio flips in the GEMM loops removed (A/B of the doc's setprio lever)
# speedup vs baseline: 1.0284x; 1.0284x over previous
; #define PG8_STAGE(bufoff, gbase, voff) do { _Pragma("unroll") for (int _i = 0; _i < 2; ++_i) \
;         __builtin_amdgcn_global_load_lds((const unsigned*)((const char*)(gbase) + (voff)[_i]), (LAS unsigned*)(lds + (bufoff) + ldsw + _i * 8192), 16, 0, 0); } while (0)
; #define PG8_LDA(dst, b, h) do { _Pragma("unroll") for (int m = 0; m < 4; ++m) _Pragma("unroll") for (int k = 0; k < 2; ++k) dst[m][k] = *(const LAS h8*)(lds + PG8_SA(b, h) + aoff + m * 2048 + k * 1024); } while (0)
; #define PG8_LDB(dst, b, h) do { _Pragma("unroll") for (int n = 0; n < 2; ++n) _Pragma("unroll") for (int k = 0; k < 2; ++k) dst[n][k] = *(const LAS h8*)(lds + PG8_SB(b, h) + boff + n * 2048 + k * 1024); } while (0)
; #define PG8_WAIT_V(n) asm volatile("s_waitcnt vmcnt(" #n ")" ::: "memory")
; #define PG8_WAIT_L(n) asm volatile("s_waitcnt lgkmcnt(" #n ")" ::: "memory")
; #define PG8_BAR __builtin_amdgcn_s_barrier()
; #define PG8_SCHED __builtin_amdgcn_sched_barrier(0)
; template <class Epi>
; __device__ __forceinline__ void gemm_phase(LAS unsigned char* lds, const Gemm g, const StaticOrder& S, const Epi& E, const int tid) {
;     ...
;         for (int t = 0; t < nt; t += 2) {
;             const bool last = (t == nt - 2);
;             const char* a1 = cA + (size_t)(t + 1) * kstep;
;             const char* a2 = last ? nA : cA + (size_t)(t + 2) * kstep; const char* b2 = last ? nB : cB + (size_t)(t + 2) * kstep;
;             const char* a3 = a2 + kstep; const char* b3 = b2 + kstep;
;             if constexpr (Epi::HAS_MID) { if (t == (nt >> 1)) E.mid(acc, cur, wr, wc, fr, fq); }
;             PG8_LDB(B0, 0, 0); PG8_SCHED; PG8_LDA(At, 0, 0); PG8_STAGE(PG8_SA(1, 1), a1 + hstep, voffA);
;             PG8_WAIT_L(8); PG8_BAR; PG8_WAIT_L(0); PG8_MMA(0, 0, At, B0); PG8_BAR; PG8_SCHED;
;             PG8_LDB(B1, 0, 1); PG8_STAGE(PG8_SB(0, 0), b2, voffB);
;             PG8_BAR; PG8_WAIT_L(0); PG8_MMA(0, 1, At, B1); PG8_BAR;
;             PG8_LDA(At, 0, 1); PG8_STAGE(PG8_SA(0, 0), a2, voffA);
;             PG8_BAR; PG8_WAIT_L(0); PG8_MMA(1, 0, At, B0); PG8_BAR; PG8_SCHED;
;             PG8_STAGE(PG8_SB(0, 1), b2 + hstepB, voffB);
;             PG8_WAIT_V(6); PG8_BAR; PG8_MMA(1, 1, At, B1); PG8_BAR;
.LBB0_332:
	s_add_u32 s18, s14, 0xfff80080
	s_addc_u32 s19, s15, -1
	s_add_i32 s55, 0, 0x10000
	v_add_u32_e32 v157, s55, v140
	ds_read_b128 v[144:147], v157
	ds_read_b128 v[162:165], v157 offset:1024
	ds_read_b128 v[166:169], v157 offset:2048
	ds_read_b128 v[170:173], v157 offset:3072
	s_cmp_eq_u32 s54, 28
	s_cselect_b32 s23, s9, s19
	s_cselect_b32 s22, s50, s18
	s_cselect_b32 s19, s1, s53
	s_cselect_b32 s18, s51, s52
	v_lshl_add_u64 v[178:179], s[14:15], 0, v[136:137]
	s_add_i32 m0, s39, 0xc000
	ds_read_b128 v[174:177], v143
	ds_read_b128 v[190:193], v143 offset:1024
	ds_read_b128 v[194:197], v143 offset:2048
	ds_read_b128 v[198:201], v143 offset:3072
	ds_read_b128 v[202:205], v143 offset:4096
	ds_read_b128 v[206:209], v143 offset:5120
	ds_read_b128 v[210:213], v143 offset:6144
	ds_read_b128 v[214:217], v143 offset:7168
	global_load_lds_dwordx4 v[178:179], off
	v_lshl_add_u64 v[178:179], s[14:15], 0, v[138:139]
	s_add_i32 m0, s39, 0xe000
	s_nop 0
	global_load_lds_dwordx4 v[178:179], off
	s_waitcnt lgkmcnt(8)
	s_barrier
	s_waitcnt lgkmcnt(0)
	s_waitcnt lgkmcnt(0)
	v_mfma_f32_16x16x32_bf16 v[124:127], v[144:147], v[174:177], v[124:127]
	v_mfma_f32_16x16x32_bf16 v[128:131], v[166:169], v[174:177], v[128:131]
	v_mfma_f32_16x16x32_bf16 v[108:111], v[144:147], v[194:197], v[108:111]
	v_mfma_f32_16x16x32_bf16 v[112:115], v[166:169], v[194:197], v[112:115]
	v_mfma_f32_16x16x32_bf16 v[92:95], v[144:147], v[202:205], v[92:95]
	v_mfma_f32_16x16x32_bf16 v[96:99], v[166:169], v[202:205], v[96:99]
	v_mfma_f32_16x16x32_bf16 v[76:79], v[144:147], v[210:213], v[76:79]
	v_mfma_f32_16x16x32_bf16 v[80:83], v[166:169], v[210:213], v[80:83]
	v_mfma_f32_16x16x32_bf16 v[124:127], v[162:165], v[190:193], v[124:127]
	v_mfma_f32_16x16x32_bf16 v[128:131], v[170:173], v[190:193], v[128:131]
	v_mfma_f32_16x16x32_bf16 v[108:111], v[162:165], v[198:201], v[108:111]
	v_mfma_f32_16x16x32_bf16 v[112:115], v[170:173], v[198:201], v[112:115]
	v_mfma_f32_16x16x32_bf16 v[92:95], v[162:165], v[206:209], v[92:95]
	v_mfma_f32_16x16x32_bf16 v[96:99], v[170:173], v[206:209], v[96:99]
	v_mfma_f32_16x16x32_bf16 v[76:79], v[162:165], v[214:217], v[76:79]
	v_mfma_f32_16x16x32_bf16 v[80:83], v[170:173], v[214:217], v[80:83]
	s_barrier
	s_add_i32 s58, 0, 0x14000
	s_add_i32 s55, s55, s38
	v_add_u32_e32 v157, s58, v140
	v_lshl_add_u64 v[178:179], s[18:19], 0, v[2:3]
	s_mov_b32 m0, s55
	ds_read_b128 v[218:221], v157
	ds_read_b128 v[222:225], v157 offset:1024
	ds_read_b128 v[226:229], v157 offset:2048
	ds_read_b128 v[230:233], v157 offset:3072
	global_load_lds_dwordx4 v[178:179], off
	v_lshl_add_u64 v[234:235], s[18:19], 0, v[0:1]
	s_add_i32 m0, s55, 0x2000
	s_nop 0
	global_load_lds_dwordx4 v[234:235], off
	s_barrier
	s_waitcnt lgkmcnt(0)
	s_waitcnt lgkmcnt(0)
	v_mfma_f32_16x16x32_bf16 v[116:119], v[218:221], v[174:177], v[116:119]
	v_mfma_f32_16x16x32_bf16 v[120:123], v[226:229], v[174:177], v[120:123]
	v_mfma_f32_16x16x32_bf16 v[100:103], v[218:221], v[194:197], v[100:103]
	v_mfma_f32_16x16x32_bf16 v[104:107], v[226:229], v[194:197], v[104:107]
	v_mfma_f32_16x16x32_bf16 v[84:87], v[218:221], v[202:205], v[84:87]
	v_mfma_f32_16x16x32_bf16 v[88:91], v[226:229], v[202:205], v[88:91]
	v_mfma_f32_16x16x32_bf16 v[68:71], v[218:221], v[210:213], v[68:71]
	v_mfma_f32_16x16x32_bf16 v[72:75], v[226:229], v[210:213], v[72:75]
	v_mfma_f32_16x16x32_bf16 v[116:119], v[222:225], v[190:193], v[116:119]
	v_mfma_f32_16x16x32_bf16 v[120:123], v[230:233], v[190:193], v[120:123]
	v_mfma_f32_16x16x32_bf16 v[100:103], v[222:225], v[198:201], v[100:103]
	v_mfma_f32_16x16x32_bf16 v[104:107], v[230:233], v[198:201], v[104:107]
	v_mfma_f32_16x16x32_bf16 v[84:87], v[222:225], v[206:209], v[84:87]
	v_mfma_f32_16x16x32_bf16 v[88:91], v[230:233], v[206:209], v[88:91]
	v_mfma_f32_16x16x32_bf16 v[68:71], v[222:225], v[214:217], v[68:71]
	v_mfma_f32_16x16x32_bf16 v[72:75], v[230:233], v[214:217], v[72:75]
	s_mov_b32 m0, s39
	v_lshl_add_u64 v[236:237], s[22:23], 0, v[134:135]
	s_barrier
	ds_read_b128 v[174:177], v143 offset:16384
	ds_read_b128 v[190:193], v143 offset:17408
	ds_read_b128 v[194:197], v143 offset:18432
	ds_read_b128 v[198:201], v143 offset:19456
	ds_read_b128 v[202:205], v143 offset:20480
	ds_read_b128 v[206:209], v143 offset:21504
	ds_read_b128 v[210:213], v143 offset:22528
	ds_read_b128 v[214:217], v143 offset:23552
	global_load_lds_dwordx4 v[236:237], off
	v_lshl_add_u64 v[238:239], s[22:23], 0, v[132:133]
	s_mov_b32 m0, s40
	s_nop 0
	global_load_lds_dwordx4 v[238:239], off
	s_barrier
	s_waitcnt lgkmcnt(0)
	s_waitcnt lgkmcnt(0)
	v_mfma_f32_16x16x32_bf16 v[60:63], v[144:147], v[174:177], v[60:63]
	v_mfma_f32_16x16x32_bf16 v[64:67], v[166:169], v[174:177], v[64:67]
	v_mfma_f32_16x16x32_bf16 v[44:47], v[144:147], v[194:197], v[44:47]
	v_mfma_f32_16x16x32_bf16 v[48:51], v[166:169], v[194:197], v[48:51]
	v_mfma_f32_16x16x32_bf16 v[28:31], v[144:147], v[202:205], v[28:31]
	v_mfma_f32_16x16x32_bf16 v[32:35], v[166:169], v[202:205], v[32:35]
	v_mfma_f32_16x16x32_bf16 v[12:15], v[144:147], v[210:213], v[12:15]
	v_mfma_f32_16x16x32_bf16 v[16:19], v[166:169], v[210:213], v[16:19]
	v_mfma_f32_16x16x32_bf16 v[60:63], v[162:165], v[190:193], v[60:63]
	v_mfma_f32_16x16x32_bf16 v[64:67], v[170:173], v[190:193], v[64:67]
	v_mfma_f32_16x16x32_bf16 v[44:47], v[162:165], v[198:201], v[44:47]
	v_mfma_f32_16x16x32_bf16 v[48:51], v[170:173], v[198:201], v[48:51]
	v_mfma_f32_16x16x32_bf16 v[28:31], v[162:165], v[206:209], v[28:31]
	v_mfma_f32_16x16x32_bf16 v[32:35], v[170:173], v[206:209], v[32:35]
	v_mfma_f32_16x16x32_bf16 v[12:15], v[162:165], v[214:217], v[12:15]
	v_mfma_f32_16x16x32_bf16 v[16:19], v[170:173], v[214:217], v[16:19]
	s_barrier
; #define PG8_STAGE(bufoff, gbase, voff) do { _Pragma("unroll") for (int _i = 0; _i < 2; ++_i) \
;         __builtin_amdgcn_global_load_lds((const unsigned*)((const char*)(gbase) + (voff)[_i]), (LAS unsigned*)(lds + (bufoff) + ldsw + _i * 8192), 16, 0, 0); } while (0)
; #define PG8_LDA(dst, b, h) do { _Pragma("unroll") for (int m = 0; m < 4; ++m) _Pragma("unroll") for (int k = 0; k < 2; ++k) dst[m][k] = *(const LAS h8*)(lds + PG8_SA(b, h) + aoff + m * 2048 + k * 1024); } while (0)
; #define PG8_LDB(dst, b, h) do { _Pragma("unroll") for (int n = 0; n < 2; ++n) _Pragma("unroll") for (int k = 0; k < 2; ++k) dst[n][k] = *(const LAS h8*)(lds + PG8_SB(b, h) + boff + n * 2048 + k * 1024); } while (0)
; #define PG8_WAIT_V(n) asm volatile("s_waitcnt vmcnt(" #n ")" ::: "memory")
; #define PG8_WAIT_L(n) asm volatile("s_waitcnt lgkmcnt(" #n ")" ::: "memory")
; #define PG8_BAR __builtin_amdgcn_s_barrier()
; #define PG8_SCHED __builtin_amdgcn_sched_barrier(0)
; template <class Epi>
; __device__ __forceinline__ void gemm_phase(LAS unsigned char* lds, const Gemm g, const StaticOrder& S, const Epi& E, const int tid) {
;     ...
;             PG8_STAGE(PG8_SB(0, 1), b2 + hstepB, voffB);
;             PG8_WAIT_V(6); PG8_BAR; PG8_MMA(1, 1, At, B1); PG8_BAR;
;             PG8_LDB(B0, 1, 0); PG8_SCHED; PG8_LDA(At, 1, 0); PG8_STAGE(PG8_SA(0, 1), a2 + hstep, voffA);
;             PG8_WAIT_L(8); PG8_BAR; PG8_WAIT_L(0); PG8_MMA(0, 0, At, B0); PG8_BAR; PG8_SCHED;
;             PG8_LDB(B1, 1, 1); PG8_STAGE(PG8_SB(1, 0), b3, voffB);
;             PG8_BAR; PG8_WAIT_L(0); PG8_MMA(0, 1, At, B1); PG8_BAR;
;             PG8_LDA(At, 1, 1); PG8_STAGE(PG8_SA(1, 0), a3, voffA);
;             PG8_BAR; PG8_WAIT_L(0); PG8_MMA(1, 0, At, B0); PG8_BAR; PG8_SCHED;
	s_add_u32 s56, s18, 0x20000
	s_addc_u32 s57, s19, 0
	s_add_i32 s55, s58, s38
	v_lshl_add_u64 v[144:145], s[56:57], 0, v[2:3]
	s_mov_b32 m0, s55
	s_nop 0
	global_load_lds_dwordx4 v[144:145], off
	v_lshl_add_u64 v[144:145], s[56:57], 0, v[0:1]
	s_add_i32 m0, s55, 0x2000
	s_nop 0
	global_load_lds_dwordx4 v[144:145], off
	s_waitcnt vmcnt(6)
	s_barrier
	v_mfma_f32_16x16x32_bf16 v[52:55], v[218:221], v[174:177], v[52:55]
	v_mfma_f32_16x16x32_bf16 v[56:59], v[226:229], v[174:177], v[56:59]
	v_mfma_f32_16x16x32_bf16 v[36:39], v[218:221], v[194:197], v[36:39]
	v_mfma_f32_16x16x32_bf16 v[40:43], v[226:229], v[194:197], v[40:43]
	v_mfma_f32_16x16x32_bf16 v[20:23], v[218:221], v[202:205], v[20:23]
	v_mfma_f32_16x16x32_bf16 v[24:27], v[226:229], v[202:205], v[24:27]
	v_mfma_f32_16x16x32_bf16 v[8:11], v[218:221], v[210:213], v[8:11]
	v_mfma_f32_16x16x32_bf16 v[4:7], v[226:229], v[210:213], v[4:7]
	v_mfma_f32_16x16x32_bf16 v[52:55], v[222:225], v[190:193], v[52:55]
	v_mfma_f32_16x16x32_bf16 v[56:59], v[230:233], v[190:193], v[56:59]
	v_mfma_f32_16x16x32_bf16 v[36:39], v[222:225], v[198:201], v[36:39]
	v_mfma_f32_16x16x32_bf16 v[40:43], v[230:233], v[198:201], v[40:43]
	v_mfma_f32_16x16x32_bf16 v[20:23], v[222:225], v[206:209], v[20:23]
	v_mfma_f32_16x16x32_bf16 v[24:27], v[230:233], v[206:209], v[24:27]
	v_mfma_f32_16x16x32_bf16 v[8:11], v[222:225], v[214:217], v[8:11]
	v_mfma_f32_16x16x32_bf16 v[4:7], v[230:233], v[214:217], v[4:7]
	s_add_i32 s55, 0, 0x18000
	v_add_u32_e32 v157, s55, v140
	s_barrier
	ds_read_b128 v[144:147], v157
	ds_read_b128 v[162:165], v157 offset:1024
	ds_read_b128 v[166:169], v157 offset:2048
	ds_read_b128 v[170:173], v157 offset:3072
	s_add_u32 s22, s22, 0x80000
	s_addc_u32 s23, s23, 0
	s_mov_b32 m0, s41
	v_lshl_add_u64 v[218:219], s[22:23], 0, v[134:135]
	ds_read_b128 v[174:177], v143 offset:32768
	ds_read_b128 v[190:193], v143 offset:33792
	ds_read_b128 v[194:197], v143 offset:34816
	ds_read_b128 v[198:201], v143 offset:35840
	ds_read_b128 v[202:205], v143 offset:36864
	ds_read_b128 v[206:209], v143 offset:37888
	ds_read_b128 v[210:213], v143 offset:38912
	ds_read_b128 v[214:217], v143 offset:39936
	global_load_lds_dwordx4 v[218:219], off
	v_lshl_add_u64 v[218:219], s[22:23], 0, v[132:133]
	s_mov_b32 m0, s42
	s_nop 0
	global_load_lds_dwordx4 v[218:219], off
	s_waitcnt lgkmcnt(8)
	s_barrier
	s_waitcnt lgkmcnt(0)
	s_waitcnt lgkmcnt(0)
	v_mfma_f32_16x16x32_bf16 v[124:127], v[144:147], v[174:177], v[124:127]
	v_mfma_f32_16x16x32_bf16 v[128:131], v[166:169], v[174:177], v[128:131]
	v_mfma_f32_16x16x32_bf16 v[108:111], v[144:147], v[194:197], v[108:111]
	v_mfma_f32_16x16x32_bf16 v[112:115], v[166:169], v[194:197], v[112:115]
	v_mfma_f32_16x16x32_bf16 v[92:95], v[144:147], v[202:205], v[92:95]
	v_mfma_f32_16x16x32_bf16 v[96:99], v[166:169], v[202:205], v[96:99]
	v_mfma_f32_16x16x32_bf16 v[76:79], v[144:147], v[210:213], v[76:79]
	v_mfma_f32_16x16x32_bf16 v[80:83], v[166:169], v[210:213], v[80:83]
	v_mfma_f32_16x16x32_bf16 v[124:127], v[162:165], v[190:193], v[124:127]
	v_mfma_f32_16x16x32_bf16 v[128:131], v[170:173], v[190:193], v[128:131]
	v_mfma_f32_16x16x32_bf16 v[108:111], v[162:165], v[198:201], v[108:111]
	v_mfma_f32_16x16x32_bf16 v[112:115], v[170:173], v[198:201], v[112:115]
	v_mfma_f32_16x16x32_bf16 v[92:95], v[162:165], v[206:209], v[92:95]
	v_mfma_f32_16x16x32_bf16 v[96:99], v[170:173], v[206:209], v[96:99]
	v_mfma_f32_16x16x32_bf16 v[76:79], v[162:165], v[214:217], v[76:79]
	v_mfma_f32_16x16x32_bf16 v[80:83], v[170:173], v[214:217], v[80:83]
	s_barrier
	s_add_i32 s22, 0, 0x1c000
	s_add_i32 s23, s55, s38
	v_add_u32_e32 v157, s22, v140
	v_lshl_add_u64 v[178:179], v[178:179], 0, s[30:31]
	s_mov_b32 m0, s23
	ds_read_b128 v[218:221], v157
	ds_read_b128 v[222:225], v157 offset:1024
	ds_read_b128 v[226:229], v157 offset:2048
	ds_read_b128 v[230:233], v157 offset:3072
	global_load_lds_dwordx4 v[178:179], off
	v_lshl_add_u64 v[178:179], v[234:235], 0, s[30:31]
	s_add_i32 m0, s23, 0x2000
	s_nop 0
	global_load_lds_dwordx4 v[178:179], off
	s_barrier
	s_waitcnt lgkmcnt(0)
	s_waitcnt lgkmcnt(0)
	v_mfma_f32_16x16x32_bf16 v[116:119], v[218:221], v[174:177], v[116:119]
	v_mfma_f32_16x16x32_bf16 v[120:123], v[226:229], v[174:177], v[120:123]
	v_mfma_f32_16x16x32_bf16 v[100:103], v[218:221], v[194:197], v[100:103]
	v_mfma_f32_16x16x32_bf16 v[104:107], v[226:229], v[194:197], v[104:107]
	v_mfma_f32_16x16x32_bf16 v[84:87], v[218:221], v[202:205], v[84:87]
	v_mfma_f32_16x16x32_bf16 v[88:91], v[226:229], v[202:205], v[88:91]
	v_mfma_f32_16x16x32_bf16 v[68:71], v[218:221], v[210:213], v[68:71]
	v_mfma_f32_16x16x32_bf16 v[72:75], v[226:229], v[210:213], v[72:75]
	v_mfma_f32_16x16x32_bf16 v[116:119], v[222:225], v[190:193], v[116:119]
	v_mfma_f32_16x16x32_bf16 v[120:123], v[230:233], v[190:193], v[120:123]
	v_mfma_f32_16x16x32_bf16 v[100:103], v[222:225], v[198:201], v[100:103]
	v_mfma_f32_16x16x32_bf16 v[104:107], v[230:233], v[198:201], v[104:107]
	v_mfma_f32_16x16x32_bf16 v[84:87], v[222:225], v[206:209], v[84:87]
	v_mfma_f32_16x16x32_bf16 v[88:91], v[230:233], v[206:209], v[88:91]
	v_mfma_f32_16x16x32_bf16 v[68:71], v[222:225], v[214:217], v[68:71]
	v_mfma_f32_16x16x32_bf16 v[72:75], v[230:233], v[214:217], v[72:75]
	s_mov_b32 m0, s43
	v_lshl_add_u64 v[178:179], v[236:237], 0, s[30:31]
	s_barrier
	ds_read_b128 v[174:177], v143 offset:49152
	ds_read_b128 v[190:193], v143 offset:50176
	ds_read_b128 v[194:197], v143 offset:51200
	ds_read_b128 v[198:201], v143 offset:52224
	ds_read_b128 v[202:205], v143 offset:53248
	ds_read_b128 v[206:209], v143 offset:54272
	ds_read_b128 v[210:213], v143 offset:55296
	ds_read_b128 v[214:217], v143 offset:56320
	global_load_lds_dwordx4 v[178:179], off
	v_lshl_add_u64 v[178:179], v[238:239], 0, s[30:31]
	s_mov_b32 m0, s46
	s_nop 0
	global_load_lds_dwordx4 v[178:179], off
	s_barrier
; #define PG8_STAGE(bufoff, gbase, voff) do { _Pragma("unroll") for (int _i = 0; _i < 2; ++_i) \
;         __builtin_amdgcn_global_load_lds((const unsigned*)((const char*)(gbase) + (voff)[_i]), (LAS unsigned*)(lds + (bufoff) + ldsw + _i * 8192), 16, 0, 0); } while (0)
; #define PG8_WAIT_V(n) asm volatile("s_waitcnt vmcnt(" #n ")" ::: "memory")
; #define PG8_WAIT_L(n) asm volatile("s_waitcnt lgkmcnt(" #n ")" ::: "memory")
; #define PG8_BAR __builtin_amdgcn_s_barrier()
; #define PG8_SCHED __builtin_amdgcn_sched_barrier(0)
; template <class Epi>
; __device__ __forceinline__ void gemm_phase(LAS unsigned char* lds, const Gemm g, const StaticOrder& S, const Epi& E, const int tid) {
;     ...
;             PG8_BAR; PG8_WAIT_L(0); PG8_MMA(1, 0, At, B0); PG8_BAR; PG8_SCHED;
;             PG8_STAGE(PG8_SB(1, 1), b3 + hstepB, voffB);
;             PG8_WAIT_V(6); PG8_BAR; PG8_MMA(1, 1, At, B1); PG8_BAR;
;         }
;         E(acc, cur, wr, wc, fr, fq);
;     __device__ __forceinline__ void operator()(f32x4 (&acc)[2][2][4][2], const pg8::Unit& u, int wr, int wc, int fr, int fq) const {
;         const bool hi = fr >= 8;
;         const int row0 = u.pm * 256 + wr * 64 + (fr & 7), col = u.pn * 256 + wc * 64 + fq * 8 + (hi ? 32 : 0);
; #pragma unroll
;         for (int ai = 0; ai < 2; ++ai)
; #pragma unroll
;             for (int m = 0; m < 4; ++m) {
;                 const h8 x0 = pack8(acc[ai][0][m][0], acc[ai][0][m][1]), x1 = pack8(acc[ai][1][m][0], acc[ai][1][m][1]);
;                 const i32x4 snd = hi ? __builtin_bit_cast(i32x4, x0) : __builtin_bit_cast(i32x4, x1);
;                 i32x4 rcv;
; #pragma unroll
;                 for (int d = 0; d < 4; ++d) rcv[d] = __builtin_amdgcn_update_dpp(0, snd[d], 0x128  , 0xF, 0xF, false);
;                 const h8 rv = __builtin_bit_cast(h8, rcv);
;                 const h8 vA = hi ? rv : x0;
;                 const h8 vB = hi ? x1 : rv;
;                 half_t* rowp = O + (size_t)(row0 + ai * 128 + m * 16) * NIN + col;
;                 __builtin_nontemporal_store(vA, (h8*)rowp); __builtin_nontemporal_store(vB, (h8*)(rowp + (size_t)8 * NIN)); }
;     }
	s_waitcnt lgkmcnt(0)
	s_waitcnt lgkmcnt(0)
	v_mfma_f32_16x16x32_bf16 v[60:63], v[144:147], v[174:177], v[60:63]
	v_mfma_f32_16x16x32_bf16 v[64:67], v[166:169], v[174:177], v[64:67]
	v_mfma_f32_16x16x32_bf16 v[44:47], v[144:147], v[194:197], v[44:47]
	v_mfma_f32_16x16x32_bf16 v[48:51], v[166:169], v[194:197], v[48:51]
	v_mfma_f32_16x16x32_bf16 v[28:31], v[144:147], v[202:205], v[28:31]
	v_mfma_f32_16x16x32_bf16 v[32:35], v[166:169], v[202:205], v[32:35]
	v_mfma_f32_16x16x32_bf16 v[12:15], v[144:147], v[210:213], v[12:15]
	v_mfma_f32_16x16x32_bf16 v[16:19], v[166:169], v[210:213], v[16:19]
	v_mfma_f32_16x16x32_bf16 v[60:63], v[162:165], v[190:193], v[60:63]
	v_mfma_f32_16x16x32_bf16 v[64:67], v[170:173], v[190:193], v[64:67]
	v_mfma_f32_16x16x32_bf16 v[44:47], v[162:165], v[198:201], v[44:47]
	v_mfma_f32_16x16x32_bf16 v[48:51], v[170:173], v[198:201], v[48:51]
	v_mfma_f32_16x16x32_bf16 v[28:31], v[162:165], v[206:209], v[28:31]
	v_mfma_f32_16x16x32_bf16 v[32:35], v[170:173], v[206:209], v[32:35]
	v_mfma_f32_16x16x32_bf16 v[12:15], v[162:165], v[214:217], v[12:15]
	v_mfma_f32_16x16x32_bf16 v[16:19], v[170:173], v[214:217], v[16:19]
	s_barrier
	s_add_u32 s18, s18, 0x20080
	s_addc_u32 s19, s19, 0
	s_add_i32 s22, s22, s38
	v_lshl_add_u64 v[144:145], s[18:19], 0, v[2:3]
	s_mov_b32 m0, s22
	s_nop 0
	global_load_lds_dwordx4 v[144:145], off
	v_lshl_add_u64 v[144:145], s[18:19], 0, v[0:1]
	s_add_i32 m0, s22, 0x2000
	s_nop 0
	global_load_lds_dwordx4 v[144:145], off
	s_waitcnt vmcnt(6)
	s_barrier
	v_mfma_f32_16x16x32_bf16 v[52:55], v[218:221], v[174:177], v[52:55]
	v_mfma_f32_16x16x32_bf16 v[56:59], v[226:229], v[174:177], v[56:59]
	v_mfma_f32_16x16x32_bf16 v[36:39], v[218:221], v[194:197], v[36:39]
	v_mfma_f32_16x16x32_bf16 v[40:43], v[226:229], v[194:197], v[40:43]
	v_mfma_f32_16x16x32_bf16 v[20:23], v[218:221], v[202:205], v[20:23]
	v_mfma_f32_16x16x32_bf16 v[24:27], v[226:229], v[202:205], v[24:27]
	v_mfma_f32_16x16x32_bf16 v[8:11], v[218:221], v[210:213], v[8:11]
	v_mfma_f32_16x16x32_bf16 v[4:7], v[226:229], v[210:213], v[4:7]
	v_mfma_f32_16x16x32_bf16 v[52:55], v[222:225], v[190:193], v[52:55]
	v_mfma_f32_16x16x32_bf16 v[56:59], v[230:233], v[190:193], v[56:59]
	v_mfma_f32_16x16x32_bf16 v[36:39], v[222:225], v[198:201], v[36:39]
	v_mfma_f32_16x16x32_bf16 v[40:43], v[230:233], v[198:201], v[40:43]
	v_mfma_f32_16x16x32_bf16 v[20:23], v[222:225], v[206:209], v[20:23]
	v_mfma_f32_16x16x32_bf16 v[24:27], v[230:233], v[206:209], v[24:27]
	v_mfma_f32_16x16x32_bf16 v[8:11], v[222:225], v[214:217], v[8:11]
	v_mfma_f32_16x16x32_bf16 v[4:7], v[230:233], v[214:217], v[4:7]
	s_add_i32 s54, s54, 2
	s_add_u32 s14, s14, 0x100
	s_addc_u32 s15, s15, 0
	s_add_u32 s52, s52, 0x100
	s_addc_u32 s53, s53, 0
	s_cmp_gt_u32 s54, 29
	s_barrier
	s_cbranch_scc0 .LBB0_332
	v_cvt_pk_f16_f32 v124, v124, v125
	v_cvt_pk_f16_f32 v116, v116, v117
	v_cvt_pk_f16_f32 v130, v130, v131
	v_cvt_pk_f16_f32 v131, v122, v123
	v_cvt_pk_f16_f32 v128, v128, v129
	v_cvt_pk_f16_f32 v129, v120, v121
	v_cvt_pk_f16_f32 v121, v126, v127
	v_cvt_pk_f16_f32 v118, v118, v119
	v_cndmask_b32_e64 v117, v116, v124, s[4:5]
	v_mov_b32_e32 v147, v3
	v_cndmask_b32_e64 v122, v131, v130, s[4:5]
	v_cndmask_b32_e64 v119, v118, v121, s[4:5]
	v_mov_b32_dpp v147, v117 row_ror:8 row_mask:0xf bank_mask:0xf
	v_mov_b32_e32 v117, v3
	v_mov_b32_e32 v125, v3
	v_lshl_or_b32 v144, s48, 8, v142
	v_cndmask_b32_e64 v120, v129, v128, s[4:5]
	v_mov_b32_dpp v117, v119 row_ror:8 row_mask:0xf bank_mask:0xf
	v_mov_b32_e32 v119, v3
	v_mov_b32_dpp v125, v122 row_ror:8 row_mask:0xf bank_mask:0xf
	v_lshl_add_u32 v146, s49, 8, v141
	v_ashrrev_i32_e32 v145, 31, v144
	v_mov_b32_dpp v119, v120 row_ror:8 row_mask:0xf bank_mask:0xf
	v_cndmask_b32_e64 v123, v130, v125, s[4:5]
	v_cndmask_b32_e64 v121, v121, v117, s[4:5]
	v_cndmask_b32_e64 v120, v124, v147, s[4:5]
	v_cndmask_b32_e64 v127, v125, v131, s[4:5]
	v_cndmask_b32_e64 v125, v117, v118, s[4:5]
	v_cndmask_b32_e64 v124, v147, v116, s[4:5]
	v_mov_b64_e32 v[116:117], s[36:37]
	v_cndmask_b32_e64 v122, v128, v119, s[4:5]
	v_cndmask_b32_e64 v126, v119, v129, s[4:5]
	v_mad_i64_i32 v[128:129], s[14:15], v146, s35, v[116:117]
	v_lshlrev_b64 v[118:119], 1, v[144:145]
	v_lshl_add_u64 v[128:129], v[128:129], 0, v[118:119]
	s_mov_b32 s1, 0x3c000
	global_store_dwordx4 v[128:129], v[120:123], off nt
	v_cvt_pk_f16_f32 v112, v112, v113
	v_cvt_pk_f16_f32 v104, v104, v105
	v_add_co_u32_e32 v120, vcc, s1, v128
	v_cvt_pk_f16_f32 v108, v108, v109
	s_nop 0
	v_addc_co_u32_e32 v121, vcc, 0, v129, vcc
	v_cvt_pk_f16_f32 v109, v100, v101
	global_store_dwordx4 v[120:121], v[124:127], off nt
	v_cvt_pk_f16_f32 v114, v114, v115
	v_cvt_pk_f16_f32 v106, v106, v107
	v_cndmask_b32_e64 v105, v104, v112, s[4:5]
	v_cndmask_b32_e64 v100, v109, v108, s[4:5]
	v_mov_b32_e32 v113, v3
	v_mov_b32_e32 v120, v3
	v_cndmask_b32_e64 v107, v106, v114, s[4:5]
	v_cvt_pk_f16_f32 v110, v110, v111
	v_cvt_pk_f16_f32 v111, v102, v103
	v_mov_b32_dpp v113, v100 row_ror:8 row_mask:0xf bank_mask:0xf
	v_mov_b32_dpp v120, v105 row_ror:8 row_mask:0xf bank_mask:0xf
	v_mov_b32_e32 v105, v3
	v_cndmask_b32_e64 v102, v111, v110, s[4:5]
	v_mov_b32_e32 v115, v3
	v_mov_b32_dpp v105, v107 row_ror:8 row_mask:0xf bank_mask:0xf
	v_cndmask_b32_e64 v100, v108, v113, s[4:5]
	v_or_b32_e32 v108, 16, v146
	v_mov_b32_dpp v115, v102 row_ror:8 row_mask:0xf bank_mask:0xf
	v_cndmask_b32_e64 v107, v105, v106, s[4:5]
	v_cndmask_b32_e64 v106, v120, v104, s[4:5]
	v_cndmask_b32_e64 v104, v113, v109, s[4:5]
	v_mad_i64_i32 v[108:109], s[14:15], v108, s35, v[116:117]
	v_cndmask_b32_e64 v103, v114, v105, s[4:5]
	v_cndmask_b32_e64 v102, v112, v120, s[4:5]
	v_cndmask_b32_e64 v101, v110, v115, s[4:5]
;     __device__ __forceinline__ void operator()(f32x4 (&acc)[2][2][4][2], const pg8::Unit& u, int wr, int wc, int fr, int fq) const {
;     ...
;             for (int m = 0; m < 4; ++m) {
;                 const h8 x0 = pack8(acc[ai][0][m][0], acc[ai][0][m][1]), x1 = pack8(acc[ai][1][m][0], acc[ai][1][m][1]);
;                 const i32x4 snd = hi ? __builtin_bit_cast(i32x4, x0) : __builtin_bit_cast(i32x4, x1);
;                 i32x4 rcv;
; #pragma unroll
;                 for (int d = 0; d < 4; ++d) rcv[d] = __builtin_amdgcn_update_dpp(0, snd[d], 0x128  , 0xF, 0xF, false);
;                 const h8 rv = __builtin_bit_cast(h8, rcv);
;                 const h8 vA = hi ? rv : x0;
;                 const h8 vB = hi ? x1 : rv;
;                 half_t* rowp = O + (size_t)(row0 + ai * 128 + m * 16) * NIN + col;
;                 __builtin_nontemporal_store(vA, (h8*)rowp); __builtin_nontemporal_store(vB, (h8*)(rowp + (size_t)8 * NIN)); }
	v_lshl_add_u64 v[108:109], v[108:109], 0, v[118:119]
	global_store_dwordx4 v[108:109], v[100:103], off nt
	v_cndmask_b32_e64 v105, v115, v111, s[4:5]
	v_cvt_pk_f16_f32 v96, v96, v97
	v_add_co_u32_e32 v100, vcc, s1, v108
	v_cvt_pk_f16_f32 v88, v88, v89
	s_nop 0
	v_addc_co_u32_e32 v101, vcc, 0, v109, vcc
	v_cvt_pk_f16_f32 v92, v92, v93
	v_cvt_pk_f16_f32 v93, v84, v85
	global_store_dwordx4 v[100:101], v[104:107], off nt
	v_cvt_pk_f16_f32 v98, v98, v99
	v_cvt_pk_f16_f32 v90, v90, v91
	v_cndmask_b32_e64 v89, v88, v96, s[4:5]
	v_cndmask_b32_e64 v84, v93, v92, s[4:5]
	v_mov_b32_e32 v97, v3
	v_mov_b32_e32 v100, v3
	v_cndmask_b32_e64 v91, v90, v98, s[4:5]
	v_cvt_pk_f16_f32 v94, v94, v95
	v_cvt_pk_f16_f32 v95, v86, v87
	v_mov_b32_dpp v97, v84 row_ror:8 row_mask:0xf bank_mask:0xf
	v_mov_b32_dpp v100, v89 row_ror:8 row_mask:0xf bank_mask:0xf
	v_mov_b32_e32 v89, v3
	v_cndmask_b32_e64 v86, v95, v94, s[4:5]
	v_mov_b32_e32 v99, v3
	v_mov_b32_dpp v89, v91 row_ror:8 row_mask:0xf bank_mask:0xf
	v_cndmask_b32_e64 v84, v92, v97, s[4:5]
	v_or_b32_e32 v92, 32, v146
	v_mov_b32_dpp v99, v86 row_ror:8 row_mask:0xf bank_mask:0xf
	v_cndmask_b32_e64 v91, v89, v90, s[4:5]
	v_cndmask_b32_e64 v90, v100, v88, s[4:5]
	v_cndmask_b32_e64 v88, v97, v93, s[4:5]
	v_mad_i64_i32 v[92:93], s[14:15], v92, s35, v[116:117]
	v_cndmask_b32_e64 v87, v98, v89, s[4:5]
	v_cndmask_b32_e64 v86, v96, v100, s[4:5]
	v_cndmask_b32_e64 v85, v94, v99, s[4:5]
	v_lshl_add_u64 v[92:93], v[92:93], 0, v[118:119]
	global_store_dwordx4 v[92:93], v[84:87], off nt
	v_cndmask_b32_e64 v89, v99, v95, s[4:5]
	v_cvt_pk_f16_f32 v80, v80, v81
	v_add_co_u32_e32 v84, vcc, s1, v92
	v_cvt_pk_f16_f32 v72, v72, v73
	s_nop 0
	v_addc_co_u32_e32 v85, vcc, 0, v93, vcc
	v_cvt_pk_f16_f32 v76, v76, v77
	v_cvt_pk_f16_f32 v77, v68, v69
	global_store_dwordx4 v[84:85], v[88:91], off nt
	v_cvt_pk_f16_f32 v82, v82, v83
	v_cvt_pk_f16_f32 v74, v74, v75
	v_cndmask_b32_e64 v73, v72, v80, s[4:5]
	v_cndmask_b32_e64 v68, v77, v76, s[4:5]
	v_mov_b32_e32 v81, v3
	v_mov_b32_e32 v84, v3
	v_cndmask_b32_e64 v75, v74, v82, s[4:5]
	v_cvt_pk_f16_f32 v78, v78, v79
	v_cvt_pk_f16_f32 v79, v70, v71
	v_mov_b32_dpp v81, v68 row_ror:8 row_mask:0xf bank_mask:0xf
	v_mov_b32_dpp v84, v73 row_ror:8 row_mask:0xf bank_mask:0xf
	v_mov_b32_e32 v73, v3
	v_cndmask_b32_e64 v70, v79, v78, s[4:5]
	v_mov_b32_e32 v83, v3
	v_mov_b32_dpp v73, v75 row_ror:8 row_mask:0xf bank_mask:0xf
	v_cndmask_b32_e64 v68, v76, v81, s[4:5]
	v_or_b32_e32 v76, 48, v146
	v_mov_b32_dpp v83, v70 row_ror:8 row_mask:0xf bank_mask:0xf
	v_cndmask_b32_e64 v75, v73, v74, s[4:5]
	v_cndmask_b32_e64 v74, v84, v72, s[4:5]
	v_cndmask_b32_e64 v72, v81, v77, s[4:5]
	v_mad_i64_i32 v[76:77], s[14:15], v76, s35, v[116:117]
	v_cndmask_b32_e64 v71, v82, v73, s[4:5]
	v_cndmask_b32_e64 v70, v80, v84, s[4:5]
	v_cndmask_b32_e64 v69, v78, v83, s[4:5]
	v_lshl_add_u64 v[76:77], v[76:77], 0, v[118:119]
	global_store_dwordx4 v[76:77], v[68:71], off nt
	v_cndmask_b32_e64 v73, v83, v79, s[4:5]
	v_cvt_pk_f16_f32 v64, v64, v65
	v_add_co_u32_e32 v68, vcc, s1, v76
	v_cvt_pk_f16_f32 v56, v56, v57
	s_nop 0
	v_addc_co_u32_e32 v69, vcc, 0, v77, vcc
	global_store_dwordx4 v[68:69], v[72:75], off nt
	v_cvt_pk_f16_f32 v66, v66, v67
	v_cvt_pk_f16_f32 v58, v58, v59
	v_cndmask_b32_e64 v57, v56, v64, s[4:5]
	v_cvt_pk_f16_f32 v60, v60, v61
	v_cvt_pk_f16_f32 v61, v52, v53
	v_mov_b32_e32 v69, v3
	v_cndmask_b32_e64 v59, v58, v66, s[4:5]
	v_cvt_pk_f16_f32 v62, v62, v63
	v_cvt_pk_f16_f32 v63, v54, v55
	v_cndmask_b32_e64 v52, v61, v60, s[4:5]
	v_mov_b32_e32 v65, v3
	v_mov_b32_dpp v69, v57 row_ror:8 row_mask:0xf bank_mask:0xf
	v_mov_b32_e32 v57, v3
	v_add_u32_e32 v68, 0x80, v146
	v_cndmask_b32_e64 v54, v63, v62, s[4:5]
	v_mov_b32_dpp v65, v52 row_ror:8 row_mask:0xf bank_mask:0xf
	v_mov_b32_e32 v67, v3
	v_mov_b32_dpp v57, v59 row_ror:8 row_mask:0xf bank_mask:0xf
	v_cndmask_b32_e64 v52, v60, v65, s[4:5]
	v_mov_b32_dpp v67, v54 row_ror:8 row_mask:0xf bank_mask:0xf
	v_cndmask_b32_e64 v59, v57, v58, s[4:5]
	v_cndmask_b32_e64 v58, v69, v56, s[4:5]
	v_cndmask_b32_e64 v56, v65, v61, s[4:5]
	v_mad_i64_i32 v[60:61], s[14:15], v68, s35, v[116:117]
	v_cndmask_b32_e64 v55, v66, v57, s[4:5]
	v_cndmask_b32_e64 v54, v64, v69, s[4:5]
	v_cndmask_b32_e64 v53, v62, v67, s[4:5]
	v_lshl_add_u64 v[60:61], v[60:61], 0, v[118:119]
	global_store_dwordx4 v[60:61], v[52:55], off nt
	v_cndmask_b32_e64 v57, v67, v63, s[4:5]
	v_cvt_pk_f16_f32 v48, v48, v49
	v_add_co_u32_e32 v52, vcc, s1, v60
	v_cvt_pk_f16_f32 v40, v40, v41
	s_nop 0
	v_addc_co_u32_e32 v53, vcc, 0, v61, vcc
	v_cvt_pk_f16_f32 v44, v44, v45
; template <class Epi>
; __device__ __forceinline__ void gemm_phase(LAS unsigned char* lds, const Gemm g, const StaticOrder& S, const Epi& E, const int tid) {
;     ...
;         if (!has_next) break;
;     __device__ __forceinline__ void operator()(f32x4 (&acc)[2][2][4][2], const pg8::Unit& u, int wr, int wc, int fr, int fq) const {
;     ...
;             for (int m = 0; m < 4; ++m) {
;                 const h8 x0 = pack8(acc[ai][0][m][0], acc[ai][0][m][1]), x1 = pack8(acc[ai][1][m][0], acc[ai][1][m][1]);
;                 const i32x4 snd = hi ? __builtin_bit_cast(i32x4, x0) : __builtin_bit_cast(i32x4, x1);
;                 i32x4 rcv;
; #pragma unroll
;                 for (int d = 0; d < 4; ++d) rcv[d] = __builtin_amdgcn_update_dpp(0, snd[d], 0x128  , 0xF, 0xF, false);
;                 const h8 rv = __builtin_bit_cast(h8, rcv);
;                 const h8 vA = hi ? rv : x0;
;                 const h8 vB = hi ? x1 : rv;
;                 half_t* rowp = O + (size_t)(row0 + ai * 128 + m * 16) * NIN + col;
;                 __builtin_nontemporal_store(vA, (h8*)rowp); __builtin_nontemporal_store(vB, (h8*)(rowp + (size_t)8 * NIN)); }
;     }
	v_cvt_pk_f16_f32 v45, v36, v37
	global_store_dwordx4 v[52:53], v[56:59], off nt
	v_cvt_pk_f16_f32 v50, v50, v51
	v_cvt_pk_f16_f32 v42, v42, v43
	v_cndmask_b32_e64 v41, v40, v48, s[4:5]
	v_cndmask_b32_e64 v36, v45, v44, s[4:5]
	v_mov_b32_e32 v49, v3
	v_mov_b32_e32 v52, v3
	v_cndmask_b32_e64 v43, v42, v50, s[4:5]
	v_cvt_pk_f16_f32 v46, v46, v47
	v_cvt_pk_f16_f32 v47, v38, v39
	v_mov_b32_dpp v49, v36 row_ror:8 row_mask:0xf bank_mask:0xf
	v_mov_b32_dpp v52, v41 row_ror:8 row_mask:0xf bank_mask:0xf
	v_mov_b32_e32 v41, v3
	v_cndmask_b32_e64 v38, v47, v46, s[4:5]
	v_mov_b32_e32 v51, v3
	v_mov_b32_dpp v41, v43 row_ror:8 row_mask:0xf bank_mask:0xf
	v_cndmask_b32_e64 v36, v44, v49, s[4:5]
	v_add_u32_e32 v44, 0x90, v146
	v_mov_b32_dpp v51, v38 row_ror:8 row_mask:0xf bank_mask:0xf
	v_cndmask_b32_e64 v43, v41, v42, s[4:5]
	v_cndmask_b32_e64 v42, v52, v40, s[4:5]
	v_cndmask_b32_e64 v40, v49, v45, s[4:5]
	v_mad_i64_i32 v[44:45], s[14:15], v44, s35, v[116:117]
	v_cndmask_b32_e64 v39, v50, v41, s[4:5]
	v_cndmask_b32_e64 v38, v48, v52, s[4:5]
	v_cndmask_b32_e64 v37, v46, v51, s[4:5]
	v_lshl_add_u64 v[44:45], v[44:45], 0, v[118:119]
	global_store_dwordx4 v[44:45], v[36:39], off nt
	v_cndmask_b32_e64 v41, v51, v47, s[4:5]
	v_cvt_pk_f16_f32 v32, v32, v33
	v_add_co_u32_e32 v36, vcc, s1, v44
	v_cvt_pk_f16_f32 v24, v24, v25
	s_nop 0
	v_addc_co_u32_e32 v37, vcc, 0, v45, vcc
	v_cvt_pk_f16_f32 v28, v28, v29
	v_cvt_pk_f16_f32 v29, v20, v21
	global_store_dwordx4 v[36:37], v[40:43], off nt
	v_cvt_pk_f16_f32 v34, v34, v35
	v_cvt_pk_f16_f32 v26, v26, v27
	v_cndmask_b32_e64 v25, v24, v32, s[4:5]
	v_cndmask_b32_e64 v20, v29, v28, s[4:5]
	v_mov_b32_e32 v33, v3
	v_mov_b32_e32 v36, v3
	v_cndmask_b32_e64 v27, v26, v34, s[4:5]
	v_cvt_pk_f16_f32 v30, v30, v31
	v_cvt_pk_f16_f32 v31, v22, v23
	v_mov_b32_dpp v33, v20 row_ror:8 row_mask:0xf bank_mask:0xf
	v_mov_b32_dpp v36, v25 row_ror:8 row_mask:0xf bank_mask:0xf
	v_mov_b32_e32 v25, v3
	v_cvt_pk_f16_f32 v16, v16, v17
	v_cvt_pk_f16_f32 v17, v4, v5
	v_cvt_pk_f16_f32 v5, v14, v15
	v_cvt_pk_f16_f32 v14, v10, v11
	v_cvt_pk_f16_f32 v10, v12, v13
	v_cvt_pk_f16_f32 v8, v8, v9
	v_cndmask_b32_e64 v22, v31, v30, s[4:5]
	v_mov_b32_e32 v35, v3
	v_mov_b32_dpp v25, v27 row_ror:8 row_mask:0xf bank_mask:0xf
	v_cndmask_b32_e64 v20, v28, v33, s[4:5]
	v_add_u32_e32 v28, 0xa0, v146
	v_cndmask_b32_e64 v9, v8, v10, s[4:5]
	v_mov_b32_e32 v12, v3
	v_mov_b32_dpp v35, v22 row_ror:8 row_mask:0xf bank_mask:0xf
	v_cndmask_b32_e64 v27, v25, v26, s[4:5]
	v_cndmask_b32_e64 v26, v36, v24, s[4:5]
	v_cndmask_b32_e64 v24, v33, v29, s[4:5]
	v_mad_i64_i32 v[28:29], s[14:15], v28, s35, v[116:117]
	v_cvt_pk_f16_f32 v18, v18, v19
	v_cvt_pk_f16_f32 v19, v6, v7
	v_cndmask_b32_e64 v4, v17, v16, s[4:5]
	v_mov_b32_dpp v12, v9 row_ror:8 row_mask:0xf bank_mask:0xf
	v_mov_b32_e32 v13, v3
	v_cndmask_b32_e64 v23, v34, v25, s[4:5]
	v_cndmask_b32_e64 v22, v32, v36, s[4:5]
	v_cndmask_b32_e64 v21, v30, v35, s[4:5]
	v_lshl_add_u64 v[28:29], v[28:29], 0, v[118:119]
	v_cndmask_b32_e64 v6, v19, v18, s[4:5]
	v_cndmask_b32_e64 v7, v14, v5, s[4:5]
	v_mov_b32_e32 v9, v3
	v_mov_b32_dpp v13, v4 row_ror:8 row_mask:0xf bank_mask:0xf
	v_mov_b32_e32 v11, v3
	v_cndmask_b32_e64 v4, v10, v12, s[4:5]
	v_cndmask_b32_e64 v8, v12, v8, s[4:5]
	v_add_u32_e32 v12, 0xb0, v146
	global_store_dwordx4 v[28:29], v[20:23], off nt
	v_mov_b32_dpp v9, v7 row_ror:8 row_mask:0xf bank_mask:0xf
	v_mov_b32_dpp v11, v6 row_ror:8 row_mask:0xf bank_mask:0xf
	v_add_co_u32_e32 v20, vcc, s1, v28
	v_cndmask_b32_e64 v6, v16, v13, s[4:5]
	v_cndmask_b32_e64 v10, v13, v17, s[4:5]
	v_mad_i64_i32 v[12:13], s[14:15], v12, s35, v[116:117]
	v_addc_co_u32_e32 v21, vcc, 0, v29, vcc
	v_cndmask_b32_e64 v7, v18, v11, s[4:5]
	v_cndmask_b32_e64 v5, v5, v9, s[4:5]
	v_lshl_add_u64 v[12:13], v[12:13], 0, v[118:119]
	global_store_dwordx4 v[12:13], v[4:7], off nt
	v_cndmask_b32_e64 v25, v35, v31, s[4:5]
	v_cndmask_b32_e64 v11, v11, v19, s[4:5]
	v_add_co_u32_e32 v4, vcc, 0x3c000, v12
	v_cndmask_b32_e64 v9, v9, v14, s[4:5]
	s_nop 0
	v_addc_co_u32_e32 v5, vcc, 0, v13, vcc
	s_and_b64 vcc, exec, s[6:7]
	s_mov_b32 s48, s0
	s_mov_b32 s49, s8
	s_mov_b64 s[18:19], s[12:13]
	s_mov_b64 s[14:15], s[10:11]
	global_store_dwordx4 v[20:21], v[24:27], off nt
	global_store_dwordx4 v[4:5], v[8:11], off nt
	s_cbranch_vccz .LBB0_329
	s_waitcnt vmcnt(0)
	v_readlane_b32 s42, v251, 7
	v_readlane_b32 s46, v251, 9
	v_readlane_b32 s48, v251, 13
	s_cmpk_gt_u32 s20, 0xff
	v_readlane_b32 s43, v251, 8
	v_readlane_b32 s47, v251, 10
	v_readlane_b32 s49, v251, 14
	s_cbranch_scc1 .LBB0_336
	s_barrier

; #define PG8_STAGE(bufoff, gbase, voff) do { _Pragma("unroll") for (int _i = 0; _i < 2; ++_i) \
;         __builtin_amdgcn_global_load_lds((const unsigned*)((const char*)(gbase) + (voff)[_i]), (LAS unsigned*)(lds + (bufoff) + ldsw + _i * 8192), 16, 0, 0); } while (0)
; #define PG8_LDA(dst, b, h) do { _Pragma("unroll") for (int m = 0; m < 4; ++m) _Pragma("unroll") for (int k = 0; k < 2; ++k) dst[m][k] = *(const LAS h8*)(lds + PG8_SA(b, h) + aoff + m * 2048 + k * 1024); } while (0)
; #define PG8_LDB(dst, b, h) do { _Pragma("unroll") for (int n = 0; n < 2; ++n) _Pragma("unroll") for (int k = 0; k < 2; ++k) dst[n][k] = *(const LAS h8*)(lds + PG8_SB(b, h) + boff + n * 2048 + k * 1024); } while (0)
; #define PG8_WAIT_V(n) asm volatile("s_waitcnt vmcnt(" #n ")" ::: "memory")
; #define PG8_WAIT_L(n) asm volatile("s_waitcnt lgkmcnt(" #n ")" ::: "memory")
; #define PG8_BAR __builtin_amdgcn_s_barrier()
; #define PG8_SCHED __builtin_amdgcn_sched_barrier(0)
; template <class Epi>
; __device__ __forceinline__ void gemm_phase(LAS unsigned char* lds, const Gemm g, const StaticOrder& S, const Epi& E, const int tid) {
;     ...
;         for (int t = 0; t < nt; t += 2) {
;             const bool last = (t == nt - 2);
;             const char* a1 = cA + (size_t)(t + 1) * kstep;
;             const char* a2 = last ? nA : cA + (size_t)(t + 2) * kstep; const char* b2 = last ? nB : cB + (size_t)(t + 2) * kstep;
;             const char* a3 = a2 + kstep; const char* b3 = b2 + kstep;
;             if constexpr (Epi::HAS_MID) { if (t == (nt >> 1)) E.mid(acc, cur, wr, wc, fr, fq); }
;             PG8_LDB(B0, 0, 0); PG8_SCHED; PG8_LDA(At, 0, 0); PG8_STAGE(PG8_SA(1, 1), a1 + hstep, voffA);
;             PG8_WAIT_L(8); PG8_BAR; PG8_WAIT_L(0); PG8_MMA(0, 0, At, B0); PG8_BAR; PG8_SCHED;
;             PG8_LDB(B1, 0, 1); PG8_STAGE(PG8_SB(0, 0), b2, voffB);
;             PG8_BAR; PG8_WAIT_L(0); PG8_MMA(0, 1, At, B1); PG8_BAR;
;             PG8_LDA(At, 0, 1); PG8_STAGE(PG8_SA(0, 0), a2, voffA);
;             PG8_BAR; PG8_WAIT_L(0); PG8_MMA(1, 0, At, B0); PG8_BAR; PG8_SCHED;
;             PG8_STAGE(PG8_SB(0, 1), b2 + hstepB, voffB);
;             PG8_WAIT_V(6); PG8_BAR; PG8_MMA(1, 1, At, B1); PG8_BAR;
.LBB0_594:
	s_add_u32 s14, s10, s12
	s_addc_u32 s15, s11, s13
	s_add_u32 s14, s14, 0x100
	s_addc_u32 s15, s15, 0
	s_add_u32 s55, s52, s12
	s_addc_u32 s56, s53, s13
	s_cmpk_eq_i32 s12, 0x1f00
	s_cselect_b32 s19, s5, s15
	s_cselect_b32 s18, s50, s14
	s_cselect_b32 s15, s1, s56
	s_cselect_b32 s14, s51, s55
	s_add_i32 s55, 0, 0x10000
	v_add_u32_e32 v0, s55, v189
	ds_read_b128 v[132:135], v0
	ds_read_b128 v[136:139], v0 offset:1024
	ds_read_b128 v[176:179], v0 offset:2048
	ds_read_b128 v[192:195], v0 offset:3072
	v_lshl_add_u64 v[0:1], v[172:173], 0, s[12:13]
	s_add_i32 m0, s25, 0xc000
	ds_read_b128 v[196:199], v191
	ds_read_b128 v[200:203], v191 offset:1024
	ds_read_b128 v[204:207], v191 offset:2048
	ds_read_b128 v[208:211], v191 offset:3072
	ds_read_b128 v[212:215], v191 offset:4096
	ds_read_b128 v[216:219], v191 offset:5120
	ds_read_b128 v[220:223], v191 offset:6144
	ds_read_b128 v[224:227], v191 offset:7168
	global_load_lds_dwordx4 v[0:1], off
	v_lshl_add_u64 v[0:1], v[174:175], 0, s[12:13]
	s_add_i32 m0, s25, 0xe000
	s_nop 0
	global_load_lds_dwordx4 v[0:1], off
	s_waitcnt lgkmcnt(8)
	s_barrier
	s_waitcnt lgkmcnt(0)
	s_waitcnt lgkmcnt(0)
	v_mfma_f32_16x16x32_bf16 v[128:131], v[132:135], v[196:199], v[128:131]
	v_mfma_f32_16x16x32_bf16 v[124:127], v[176:179], v[196:199], v[124:127]
	v_mfma_f32_16x16x32_bf16 v[112:115], v[132:135], v[204:207], v[112:115]
	v_mfma_f32_16x16x32_bf16 v[108:111], v[176:179], v[204:207], v[108:111]
	v_mfma_f32_16x16x32_bf16 v[96:99], v[132:135], v[212:215], v[96:99]
	v_mfma_f32_16x16x32_bf16 v[92:95], v[176:179], v[212:215], v[92:95]
	v_mfma_f32_16x16x32_bf16 v[80:83], v[132:135], v[220:223], v[80:83]
	v_mfma_f32_16x16x32_bf16 v[76:79], v[176:179], v[220:223], v[76:79]
	v_mfma_f32_16x16x32_bf16 v[128:131], v[136:139], v[200:203], v[128:131]
	v_mfma_f32_16x16x32_bf16 v[124:127], v[192:195], v[200:203], v[124:127]
	v_mfma_f32_16x16x32_bf16 v[112:115], v[136:139], v[208:211], v[112:115]
	v_mfma_f32_16x16x32_bf16 v[108:111], v[192:195], v[208:211], v[108:111]
	v_mfma_f32_16x16x32_bf16 v[96:99], v[136:139], v[216:219], v[96:99]
	v_mfma_f32_16x16x32_bf16 v[92:95], v[192:195], v[216:219], v[92:95]
	v_mfma_f32_16x16x32_bf16 v[80:83], v[136:139], v[224:227], v[80:83]
	v_mfma_f32_16x16x32_bf16 v[76:79], v[192:195], v[224:227], v[76:79]
	s_barrier
	s_add_i32 s58, 0, 0x14000
	v_add_u32_e32 v0, s58, v189
	s_add_i32 s55, s55, s24
	ds_read_b128 v[228:231], v0
	ds_read_b128 v[232:235], v0 offset:1024
	ds_read_b128 v[236:239], v0 offset:2048
	ds_read_b128 v[240:243], v0 offset:3072
	v_lshl_add_u64 v[0:1], s[14:15], 0, v[144:145]
	s_mov_b32 m0, s55
	v_lshl_add_u64 v[244:245], s[14:15], 0, v[140:141]
	global_load_lds_dwordx4 v[0:1], off
	s_add_i32 m0, s55, 0x2000
	s_nop 0
	global_load_lds_dwordx4 v[244:245], off
	s_barrier
	s_waitcnt lgkmcnt(0)
	s_waitcnt lgkmcnt(0)
	v_mfma_f32_16x16x32_bf16 v[120:123], v[228:231], v[196:199], v[120:123]
	v_mfma_f32_16x16x32_bf16 v[116:119], v[236:239], v[196:199], v[116:119]
	v_mfma_f32_16x16x32_bf16 v[104:107], v[228:231], v[204:207], v[104:107]
	v_mfma_f32_16x16x32_bf16 v[100:103], v[236:239], v[204:207], v[100:103]
	v_mfma_f32_16x16x32_bf16 v[88:91], v[228:231], v[212:215], v[88:91]
	v_mfma_f32_16x16x32_bf16 v[84:87], v[236:239], v[212:215], v[84:87]
	v_mfma_f32_16x16x32_bf16 v[72:75], v[228:231], v[220:223], v[72:75]
	v_mfma_f32_16x16x32_bf16 v[68:71], v[236:239], v[220:223], v[68:71]
	v_mfma_f32_16x16x32_bf16 v[120:123], v[232:235], v[200:203], v[120:123]
	v_mfma_f32_16x16x32_bf16 v[116:119], v[240:243], v[200:203], v[116:119]
	v_mfma_f32_16x16x32_bf16 v[104:107], v[232:235], v[208:211], v[104:107]
	v_mfma_f32_16x16x32_bf16 v[100:103], v[240:243], v[208:211], v[100:103]
	v_mfma_f32_16x16x32_bf16 v[88:91], v[232:235], v[216:219], v[88:91]
	v_mfma_f32_16x16x32_bf16 v[84:87], v[240:243], v[216:219], v[84:87]
	v_mfma_f32_16x16x32_bf16 v[72:75], v[232:235], v[224:227], v[72:75]
	v_mfma_f32_16x16x32_bf16 v[68:71], v[240:243], v[224:227], v[68:71]
	s_mov_b32 m0, s25
	v_lshl_add_u64 v[246:247], s[18:19], 0, v[146:147]
	s_barrier
	ds_read_b128 v[196:199], v191 offset:16384
	ds_read_b128 v[200:203], v191 offset:17408
	ds_read_b128 v[204:207], v191 offset:18432
	ds_read_b128 v[208:211], v191 offset:19456
	ds_read_b128 v[212:215], v191 offset:20480
	ds_read_b128 v[216:219], v191 offset:21504
	ds_read_b128 v[220:223], v191 offset:22528
	ds_read_b128 v[224:227], v191 offset:23552
	global_load_lds_dwordx4 v[246:247], off
	v_lshl_add_u64 v[248:249], s[18:19], 0, v[142:143]
	s_mov_b32 m0, s42
	s_nop 0
	global_load_lds_dwordx4 v[248:249], off
	s_barrier
	s_waitcnt lgkmcnt(0)
	s_waitcnt lgkmcnt(0)
	v_mfma_f32_16x16x32_bf16 v[64:67], v[132:135], v[196:199], v[64:67]
	v_mfma_f32_16x16x32_bf16 v[60:63], v[176:179], v[196:199], v[60:63]
	v_mfma_f32_16x16x32_bf16 v[48:51], v[132:135], v[204:207], v[48:51]
	v_mfma_f32_16x16x32_bf16 v[44:47], v[176:179], v[204:207], v[44:47]
	v_mfma_f32_16x16x32_bf16 v[32:35], v[132:135], v[212:215], v[32:35]
	v_mfma_f32_16x16x32_bf16 v[28:31], v[176:179], v[212:215], v[28:31]
	v_mfma_f32_16x16x32_bf16 v[16:19], v[132:135], v[220:223], v[16:19]
	v_mfma_f32_16x16x32_bf16 v[12:15], v[176:179], v[220:223], v[12:15]
	v_mfma_f32_16x16x32_bf16 v[64:67], v[136:139], v[200:203], v[64:67]
	v_mfma_f32_16x16x32_bf16 v[60:63], v[192:195], v[200:203], v[60:63]
	v_mfma_f32_16x16x32_bf16 v[48:51], v[136:139], v[208:211], v[48:51]
	v_mfma_f32_16x16x32_bf16 v[44:47], v[192:195], v[208:211], v[44:47]
	v_mfma_f32_16x16x32_bf16 v[32:35], v[136:139], v[216:219], v[32:35]
	v_mfma_f32_16x16x32_bf16 v[28:31], v[192:195], v[216:219], v[28:31]
	v_mfma_f32_16x16x32_bf16 v[16:19], v[136:139], v[224:227], v[16:19]
	v_mfma_f32_16x16x32_bf16 v[12:15], v[192:195], v[224:227], v[12:15]
	s_barrier
; #define PG8_STAGE(bufoff, gbase, voff) do { _Pragma("unroll") for (int _i = 0; _i < 2; ++_i) \
;         __builtin_amdgcn_global_load_lds((const unsigned*)((const char*)(gbase) + (voff)[_i]), (LAS unsigned*)(lds + (bufoff) + ldsw + _i * 8192), 16, 0, 0); } while (0)
; #define PG8_LDA(dst, b, h) do { _Pragma("unroll") for (int m = 0; m < 4; ++m) _Pragma("unroll") for (int k = 0; k < 2; ++k) dst[m][k] = *(const LAS h8*)(lds + PG8_SA(b, h) + aoff + m * 2048 + k * 1024); } while (0)
; #define PG8_LDB(dst, b, h) do { _Pragma("unroll") for (int n = 0; n < 2; ++n) _Pragma("unroll") for (int k = 0; k < 2; ++k) dst[n][k] = *(const LAS h8*)(lds + PG8_SB(b, h) + boff + n * 2048 + k * 1024); } while (0)
; #define PG8_WAIT_V(n) asm volatile("s_waitcnt vmcnt(" #n ")" ::: "memory")
; #define PG8_WAIT_L(n) asm volatile("s_waitcnt lgkmcnt(" #n ")" ::: "memory")
; #define PG8_BAR __builtin_amdgcn_s_barrier()
; #define PG8_SCHED __builtin_amdgcn_sched_barrier(0)
; template <class Epi>
; __device__ __forceinline__ void gemm_phase(LAS unsigned char* lds, const Gemm g, const StaticOrder& S, const Epi& E, const int tid) {
;     ...
;             PG8_STAGE(PG8_SB(0, 1), b2 + hstepB, voffB);
;             PG8_WAIT_V(6); PG8_BAR; PG8_MMA(1, 1, At, B1); PG8_BAR;
;             PG8_LDB(B0, 1, 0); PG8_SCHED; PG8_LDA(At, 1, 0); PG8_STAGE(PG8_SA(0, 1), a2 + hstep, voffA);
;             PG8_WAIT_L(8); PG8_BAR; PG8_WAIT_L(0); PG8_MMA(0, 0, At, B0); PG8_BAR; PG8_SCHED;
;             PG8_LDB(B1, 1, 1); PG8_STAGE(PG8_SB(1, 0), b3, voffB);
;             PG8_BAR; PG8_WAIT_L(0); PG8_MMA(0, 1, At, B1); PG8_BAR;
;             PG8_LDA(At, 1, 1); PG8_STAGE(PG8_SA(1, 0), a3, voffA);
;             PG8_BAR; PG8_WAIT_L(0); PG8_MMA(1, 0, At, B0); PG8_BAR; PG8_SCHED;
	s_add_u32 s56, s14, 0x100000
	s_addc_u32 s57, s15, 0
	s_add_i32 s55, s58, s24
	v_lshl_add_u64 v[132:133], s[56:57], 0, v[144:145]
	s_mov_b32 m0, s55
	s_nop 0
	global_load_lds_dwordx4 v[132:133], off
	v_lshl_add_u64 v[132:133], s[56:57], 0, v[140:141]
	s_add_i32 m0, s55, 0x2000
	s_nop 0
	global_load_lds_dwordx4 v[132:133], off
	s_waitcnt vmcnt(6)
	s_barrier
	v_mfma_f32_16x16x32_bf16 v[56:59], v[228:231], v[196:199], v[56:59]
	v_mfma_f32_16x16x32_bf16 v[52:55], v[236:239], v[196:199], v[52:55]
	v_mfma_f32_16x16x32_bf16 v[40:43], v[228:231], v[204:207], v[40:43]
	v_mfma_f32_16x16x32_bf16 v[36:39], v[236:239], v[204:207], v[36:39]
	v_mfma_f32_16x16x32_bf16 v[24:27], v[228:231], v[212:215], v[24:27]
	v_mfma_f32_16x16x32_bf16 v[20:23], v[236:239], v[212:215], v[20:23]
	v_mfma_f32_16x16x32_bf16 v[8:11], v[228:231], v[220:223], v[8:11]
	v_mfma_f32_16x16x32_bf16 v[4:7], v[236:239], v[220:223], v[4:7]
	v_mfma_f32_16x16x32_bf16 v[56:59], v[232:235], v[200:203], v[56:59]
	v_mfma_f32_16x16x32_bf16 v[52:55], v[240:243], v[200:203], v[52:55]
	v_mfma_f32_16x16x32_bf16 v[40:43], v[232:235], v[208:211], v[40:43]
	v_mfma_f32_16x16x32_bf16 v[36:39], v[240:243], v[208:211], v[36:39]
	v_mfma_f32_16x16x32_bf16 v[24:27], v[232:235], v[216:219], v[24:27]
	v_mfma_f32_16x16x32_bf16 v[20:23], v[240:243], v[216:219], v[20:23]
	v_mfma_f32_16x16x32_bf16 v[8:11], v[232:235], v[224:227], v[8:11]
	v_mfma_f32_16x16x32_bf16 v[4:7], v[240:243], v[224:227], v[4:7]
	s_add_i32 s55, 0, 0x18000
	v_add_u32_e32 v2, s55, v189
	s_barrier
	ds_read_b128 v[132:135], v2
	ds_read_b128 v[136:139], v2 offset:1024
	ds_read_b128 v[176:179], v2 offset:2048
	ds_read_b128 v[192:195], v2 offset:3072
	s_add_u32 s18, s18, 0x100000
	s_addc_u32 s19, s19, 0
	s_mov_b32 m0, s43
	v_lshl_add_u64 v[228:229], s[18:19], 0, v[146:147]
	ds_read_b128 v[196:199], v191 offset:32768
	ds_read_b128 v[200:203], v191 offset:33792
	ds_read_b128 v[204:207], v191 offset:34816
	ds_read_b128 v[208:211], v191 offset:35840
	ds_read_b128 v[212:215], v191 offset:36864
	ds_read_b128 v[216:219], v191 offset:37888
	ds_read_b128 v[220:223], v191 offset:38912
	ds_read_b128 v[224:227], v191 offset:39936
	global_load_lds_dwordx4 v[228:229], off
	v_lshl_add_u64 v[228:229], s[18:19], 0, v[142:143]
	s_mov_b32 m0, s46
	s_nop 0
	global_load_lds_dwordx4 v[228:229], off
	s_waitcnt lgkmcnt(8)
	s_barrier
	s_waitcnt lgkmcnt(0)
	s_waitcnt lgkmcnt(0)
	v_mfma_f32_16x16x32_bf16 v[128:131], v[132:135], v[196:199], v[128:131]
	v_mfma_f32_16x16x32_bf16 v[124:127], v[176:179], v[196:199], v[124:127]
	v_mfma_f32_16x16x32_bf16 v[112:115], v[132:135], v[204:207], v[112:115]
	v_mfma_f32_16x16x32_bf16 v[108:111], v[176:179], v[204:207], v[108:111]
	v_mfma_f32_16x16x32_bf16 v[96:99], v[132:135], v[212:215], v[96:99]
	v_mfma_f32_16x16x32_bf16 v[92:95], v[176:179], v[212:215], v[92:95]
	v_mfma_f32_16x16x32_bf16 v[80:83], v[132:135], v[220:223], v[80:83]
	v_mfma_f32_16x16x32_bf16 v[76:79], v[176:179], v[220:223], v[76:79]
	v_mfma_f32_16x16x32_bf16 v[128:131], v[136:139], v[200:203], v[128:131]
	v_mfma_f32_16x16x32_bf16 v[124:127], v[192:195], v[200:203], v[124:127]
	v_mfma_f32_16x16x32_bf16 v[112:115], v[136:139], v[208:211], v[112:115]
	v_mfma_f32_16x16x32_bf16 v[108:111], v[192:195], v[208:211], v[108:111]
	v_mfma_f32_16x16x32_bf16 v[96:99], v[136:139], v[216:219], v[96:99]
	v_mfma_f32_16x16x32_bf16 v[92:95], v[192:195], v[216:219], v[92:95]
	v_mfma_f32_16x16x32_bf16 v[80:83], v[136:139], v[224:227], v[80:83]
	v_mfma_f32_16x16x32_bf16 v[76:79], v[192:195], v[224:227], v[76:79]
	s_barrier
	s_add_i32 s18, 0, 0x1c000
	s_add_i32 s19, s55, s24
	v_add_u32_e32 v2, s18, v189
	v_lshl_add_u64 v[0:1], v[0:1], 0, s[30:31]
	s_mov_b32 m0, s19
	ds_read_b128 v[228:231], v2
	ds_read_b128 v[232:235], v2 offset:1024
	ds_read_b128 v[236:239], v2 offset:2048
	ds_read_b128 v[240:243], v2 offset:3072
	global_load_lds_dwordx4 v[0:1], off
	v_lshl_add_u64 v[0:1], v[244:245], 0, s[30:31]
	s_add_i32 m0, s19, 0x2000
	s_nop 0
	global_load_lds_dwordx4 v[0:1], off
	s_barrier
; #define PG8_STAGE(bufoff, gbase, voff) do { _Pragma("unroll") for (int _i = 0; _i < 2; ++_i) \
;         __builtin_amdgcn_global_load_lds((const unsigned*)((const char*)(gbase) + (voff)[_i]), (LAS unsigned*)(lds + (bufoff) + ldsw + _i * 8192), 16, 0, 0); } while (0)
; #define PG8_LDA(dst, b, h) do { _Pragma("unroll") for (int m = 0; m < 4; ++m) _Pragma("unroll") for (int k = 0; k < 2; ++k) dst[m][k] = *(const LAS h8*)(lds + PG8_SA(b, h) + aoff + m * 2048 + k * 1024); } while (0)
; #define PG8_LDB(dst, b, h) do { _Pragma("unroll") for (int n = 0; n < 2; ++n) _Pragma("unroll") for (int k = 0; k < 2; ++k) dst[n][k] = *(const LAS h8*)(lds + PG8_SB(b, h) + boff + n * 2048 + k * 1024); } while (0)
; #define PG8_WAIT_V(n) asm volatile("s_waitcnt vmcnt(" #n ")" ::: "memory")
; #define PG8_WAIT_L(n) asm volatile("s_waitcnt lgkmcnt(" #n ")" ::: "memory")
; #define PG8_BAR __builtin_amdgcn_s_barrier()
; #define PG8_SCHED __builtin_amdgcn_sched_barrier(0)
; template <class Epi>
; __device__ __forceinline__ void gemm_phase(LAS unsigned char* lds, const Gemm g, const StaticOrder& S, const Epi& E, const int tid) {
;     ...
;             PG8_WAIT_V(6); PG8_BAR; PG8_MMA(1, 1, At, B1); PG8_BAR;
;             PG8_LDB(B0, 1, 0); PG8_SCHED; PG8_LDA(At, 1, 0); PG8_STAGE(PG8_SA(0, 1), a2 + hstep, voffA);
;             PG8_WAIT_L(8); PG8_BAR; PG8_WAIT_L(0); PG8_MMA(0, 0, At, B0); PG8_BAR; PG8_SCHED;
;             PG8_LDB(B1, 1, 1); PG8_STAGE(PG8_SB(1, 0), b3, voffB);
;             PG8_BAR; PG8_WAIT_L(0); PG8_MMA(0, 1, At, B1); PG8_BAR;
;             PG8_LDA(At, 1, 1); PG8_STAGE(PG8_SA(1, 0), a3, voffA);
;             PG8_BAR; PG8_WAIT_L(0); PG8_MMA(1, 0, At, B0); PG8_BAR; PG8_SCHED;
;             PG8_STAGE(PG8_SB(1, 1), b3 + hstepB, voffB);
;             PG8_WAIT_V(6); PG8_BAR; PG8_MMA(1, 1, At, B1); PG8_BAR;
	s_waitcnt lgkmcnt(0)
	s_waitcnt lgkmcnt(0)
	v_mfma_f32_16x16x32_bf16 v[120:123], v[228:231], v[196:199], v[120:123]
	v_mfma_f32_16x16x32_bf16 v[116:119], v[236:239], v[196:199], v[116:119]
	v_mfma_f32_16x16x32_bf16 v[104:107], v[228:231], v[204:207], v[104:107]
	v_mfma_f32_16x16x32_bf16 v[100:103], v[236:239], v[204:207], v[100:103]
	v_mfma_f32_16x16x32_bf16 v[88:91], v[228:231], v[212:215], v[88:91]
	v_mfma_f32_16x16x32_bf16 v[84:87], v[236:239], v[212:215], v[84:87]
	v_mfma_f32_16x16x32_bf16 v[72:75], v[228:231], v[220:223], v[72:75]
	v_mfma_f32_16x16x32_bf16 v[68:71], v[236:239], v[220:223], v[68:71]
	v_mfma_f32_16x16x32_bf16 v[120:123], v[232:235], v[200:203], v[120:123]
	v_mfma_f32_16x16x32_bf16 v[116:119], v[240:243], v[200:203], v[116:119]
	v_mfma_f32_16x16x32_bf16 v[104:107], v[232:235], v[208:211], v[104:107]
	v_mfma_f32_16x16x32_bf16 v[100:103], v[240:243], v[208:211], v[100:103]
	v_mfma_f32_16x16x32_bf16 v[88:91], v[232:235], v[216:219], v[88:91]
	v_mfma_f32_16x16x32_bf16 v[84:87], v[240:243], v[216:219], v[84:87]
	v_mfma_f32_16x16x32_bf16 v[72:75], v[232:235], v[224:227], v[72:75]
	v_mfma_f32_16x16x32_bf16 v[68:71], v[240:243], v[224:227], v[68:71]
	s_mov_b32 m0, s47
	v_lshl_add_u64 v[0:1], v[246:247], 0, s[30:31]
	s_barrier
	ds_read_b128 v[196:199], v191 offset:49152
	ds_read_b128 v[200:203], v191 offset:50176
	ds_read_b128 v[204:207], v191 offset:51200
	ds_read_b128 v[208:211], v191 offset:52224
	ds_read_b128 v[212:215], v191 offset:53248
	ds_read_b128 v[216:219], v191 offset:54272
	ds_read_b128 v[220:223], v191 offset:55296
	ds_read_b128 v[224:227], v191 offset:56320
	global_load_lds_dwordx4 v[0:1], off
	v_lshl_add_u64 v[0:1], v[248:249], 0, s[30:31]
	s_mov_b32 m0, s48
	s_nop 0
	global_load_lds_dwordx4 v[0:1], off
	s_barrier
	s_waitcnt lgkmcnt(0)
	s_waitcnt lgkmcnt(0)
	v_mfma_f32_16x16x32_bf16 v[64:67], v[132:135], v[196:199], v[64:67]
	v_mfma_f32_16x16x32_bf16 v[60:63], v[176:179], v[196:199], v[60:63]
	v_mfma_f32_16x16x32_bf16 v[48:51], v[132:135], v[204:207], v[48:51]
	v_mfma_f32_16x16x32_bf16 v[44:47], v[176:179], v[204:207], v[44:47]
	v_mfma_f32_16x16x32_bf16 v[32:35], v[132:135], v[212:215], v[32:35]
	v_mfma_f32_16x16x32_bf16 v[28:31], v[176:179], v[212:215], v[28:31]
	v_mfma_f32_16x16x32_bf16 v[16:19], v[132:135], v[220:223], v[16:19]
	v_mfma_f32_16x16x32_bf16 v[12:15], v[176:179], v[220:223], v[12:15]
	v_mfma_f32_16x16x32_bf16 v[64:67], v[136:139], v[200:203], v[64:67]
	v_mfma_f32_16x16x32_bf16 v[60:63], v[192:195], v[200:203], v[60:63]
	v_mfma_f32_16x16x32_bf16 v[48:51], v[136:139], v[208:211], v[48:51]
	v_mfma_f32_16x16x32_bf16 v[44:47], v[192:195], v[208:211], v[44:47]
	v_mfma_f32_16x16x32_bf16 v[32:35], v[136:139], v[216:219], v[32:35]
	v_mfma_f32_16x16x32_bf16 v[28:31], v[192:195], v[216:219], v[28:31]
	v_mfma_f32_16x16x32_bf16 v[16:19], v[136:139], v[224:227], v[16:19]
	v_mfma_f32_16x16x32_bf16 v[12:15], v[192:195], v[224:227], v[12:15]
	s_barrier
	s_add_u32 s14, s14, 0x100080
	s_addc_u32 s15, s15, 0
	s_add_i32 s18, s18, s24
	v_lshl_add_u64 v[0:1], s[14:15], 0, v[144:145]
	s_mov_b32 m0, s18
	s_nop 0
	global_load_lds_dwordx4 v[0:1], off
	v_lshl_add_u64 v[0:1], s[14:15], 0, v[140:141]
	s_add_i32 m0, s18, 0x2000
	s_nop 0
	global_load_lds_dwordx4 v[0:1], off
	s_waitcnt vmcnt(6)
	s_barrier
	v_mfma_f32_16x16x32_bf16 v[56:59], v[228:231], v[196:199], v[56:59]
	v_mfma_f32_16x16x32_bf16 v[52:55], v[236:239], v[196:199], v[52:55]
	v_mfma_f32_16x16x32_bf16 v[40:43], v[228:231], v[204:207], v[40:43]
	v_mfma_f32_16x16x32_bf16 v[36:39], v[236:239], v[204:207], v[36:39]
	v_mfma_f32_16x16x32_bf16 v[24:27], v[228:231], v[212:215], v[24:27]
	v_mfma_f32_16x16x32_bf16 v[20:23], v[236:239], v[212:215], v[20:23]
	v_mfma_f32_16x16x32_bf16 v[8:11], v[228:231], v[220:223], v[8:11]
	v_mfma_f32_16x16x32_bf16 v[4:7], v[236:239], v[220:223], v[4:7]
	v_mfma_f32_16x16x32_bf16 v[56:59], v[232:235], v[200:203], v[56:59]
	v_mfma_f32_16x16x32_bf16 v[52:55], v[240:243], v[200:203], v[52:55]
	v_mfma_f32_16x16x32_bf16 v[40:43], v[232:235], v[208:211], v[40:43]
	v_mfma_f32_16x16x32_bf16 v[36:39], v[240:243], v[208:211], v[36:39]
	v_mfma_f32_16x16x32_bf16 v[24:27], v[232:235], v[216:219], v[24:27]
	v_mfma_f32_16x16x32_bf16 v[20:23], v[240:243], v[216:219], v[20:23]
	v_mfma_f32_16x16x32_bf16 v[8:11], v[232:235], v[224:227], v[8:11]
	v_mfma_f32_16x16x32_bf16 v[4:7], v[240:243], v[224:227], v[4:7]
	s_add_i32 s54, s54, 2
	s_add_u32 s12, s12, 0x100
	s_addc_u32 s13, s13, 0
	s_cmp_gt_u32 s54, 61
	s_barrier
	s_cbranch_scc1 .LBB0_586

; #define PG8_STAGE(bufoff, gbase, voff) do { _Pragma("unroll") for (int _i = 0; _i < 2; ++_i) \
;         __builtin_amdgcn_global_load_lds((const unsigned*)((const char*)(gbase) + (voff)[_i]), (LAS unsigned*)(lds + (bufoff) + ldsw + _i * 8192), 16, 0, 0); } while (0)
; #define PG8_LDA(dst, b, h) do { _Pragma("unroll") for (int m = 0; m < 4; ++m) _Pragma("unroll") for (int k = 0; k < 2; ++k) dst[m][k] = *(const LAS h8*)(lds + PG8_SA(b, h) + aoff + m * 2048 + k * 1024); } while (0)
; #define PG8_LDB(dst, b, h) do { _Pragma("unroll") for (int n = 0; n < 2; ++n) _Pragma("unroll") for (int k = 0; k < 2; ++k) dst[n][k] = *(const LAS h8*)(lds + PG8_SB(b, h) + boff + n * 2048 + k * 1024); } while (0)
; #define PG8_WAIT_L(n) asm volatile("s_waitcnt lgkmcnt(" #n ")" ::: "memory")
; #define PG8_BAR __builtin_amdgcn_s_barrier()
; #define PG8_SCHED __builtin_amdgcn_sched_barrier(0)
; template <class Epi>
; __device__ __forceinline__ void gemm_phase(LAS unsigned char* lds, const Gemm g, const StaticOrder& S, const Epi& E, const int tid) {
;     ...
;         for (int t = 0; t < nt; t += 2) {
;             const bool last = (t == nt - 2);
;             const char* a1 = cA + (size_t)(t + 1) * kstep;
;             const char* a2 = last ? nA : cA + (size_t)(t + 2) * kstep; const char* b2 = last ? nB : cB + (size_t)(t + 2) * kstep;
;             const char* a3 = a2 + kstep; const char* b3 = b2 + kstep;
;             if constexpr (Epi::HAS_MID) { if (t == (nt >> 1)) E.mid(acc, cur, wr, wc, fr, fq); }
;             PG8_LDB(B0, 0, 0); PG8_SCHED; PG8_LDA(At, 0, 0); PG8_STAGE(PG8_SA(1, 1), a1 + hstep, voffA);
;             PG8_WAIT_L(8); PG8_BAR; PG8_WAIT_L(0); PG8_MMA(0, 0, At, B0); PG8_BAR; PG8_SCHED;
;             PG8_LDB(B1, 0, 1); PG8_STAGE(PG8_SB(0, 0), b2, voffB);
;             PG8_BAR; PG8_WAIT_L(0); PG8_MMA(0, 1, At, B1); PG8_BAR;
.LBB0_660:
	s_add_u32 s14, s12, 0xfff80080
	s_addc_u32 s15, s13, -1
	s_add_i32 s57, 0, 0x10000
	v_add_u32_e32 v64, s57, v190
	ds_read_b128 v[28:31], v64
	ds_read_b128 v[32:35], v64 offset:1024
	ds_read_b128 v[60:63], v64 offset:2048
	ds_read_b128 v[64:67], v64 offset:3072
	s_cmp_eq_u32 s56, 28
	s_cselect_b32 s19, s7, s15
	s_cselect_b32 s18, s52, s14
	s_cselect_b32 s15, s1, s55
	s_cselect_b32 s14, s53, s54
	v_lshl_add_u64 v[174:175], s[12:13], 0, v[166:167]
	s_add_i32 m0, s41, 0xc000
	ds_read_b128 v[170:173], v192
	ds_read_b128 v[194:197], v192 offset:1024
	ds_read_b128 v[198:201], v192 offset:2048
	ds_read_b128 v[202:205], v192 offset:3072
	ds_read_b128 v[206:209], v192 offset:4096
	ds_read_b128 v[210:213], v192 offset:5120
	ds_read_b128 v[214:217], v192 offset:6144
	ds_read_b128 v[218:221], v192 offset:7168
	global_load_lds_dwordx4 v[174:175], off
	v_lshl_add_u64 v[174:175], s[12:13], 0, v[168:169]
	s_add_i32 m0, s41, 0xe000
	s_nop 0
	global_load_lds_dwordx4 v[174:175], off
	s_waitcnt lgkmcnt(8)
	s_barrier
	s_waitcnt lgkmcnt(0)
	s_waitcnt lgkmcnt(0)
	v_mfma_f32_16x16x32_bf16 v[144:147], v[28:31], v[170:173], v[144:147]
	v_mfma_f32_16x16x32_bf16 v[140:143], v[60:63], v[170:173], v[140:143]
	v_mfma_f32_16x16x32_bf16 v[128:131], v[28:31], v[198:201], v[128:131]
	v_mfma_f32_16x16x32_bf16 v[124:127], v[60:63], v[198:201], v[124:127]
	v_mfma_f32_16x16x32_bf16 v[112:115], v[28:31], v[206:209], v[112:115]
	v_mfma_f32_16x16x32_bf16 v[108:111], v[60:63], v[206:209], v[108:111]
	v_mfma_f32_16x16x32_bf16 v[96:99], v[28:31], v[214:217], v[96:99]
	v_mfma_f32_16x16x32_bf16 v[92:95], v[60:63], v[214:217], v[92:95]
	v_mfma_f32_16x16x32_bf16 v[144:147], v[32:35], v[194:197], v[144:147]
	v_mfma_f32_16x16x32_bf16 v[140:143], v[64:67], v[194:197], v[140:143]
	v_mfma_f32_16x16x32_bf16 v[128:131], v[32:35], v[202:205], v[128:131]
	v_mfma_f32_16x16x32_bf16 v[124:127], v[64:67], v[202:205], v[124:127]
	v_mfma_f32_16x16x32_bf16 v[112:115], v[32:35], v[210:213], v[112:115]
	v_mfma_f32_16x16x32_bf16 v[108:111], v[64:67], v[210:213], v[108:111]
	v_mfma_f32_16x16x32_bf16 v[96:99], v[32:35], v[218:221], v[96:99]
	v_mfma_f32_16x16x32_bf16 v[92:95], v[64:67], v[218:221], v[92:95]
	s_barrier
	s_add_i32 s60, 0, 0x14000
	v_add_u32_e32 v174, s60, v190
	s_add_i32 s57, s57, s40
	ds_read_b128 v[222:225], v174
	ds_read_b128 v[226:229], v174 offset:1024
	ds_read_b128 v[230:233], v174 offset:2048
	ds_read_b128 v[234:237], v174 offset:3072
	v_lshl_add_u64 v[174:175], s[14:15], 0, v[2:3]
	s_mov_b32 m0, s57
	v_lshl_add_u64 v[238:239], s[14:15], 0, v[0:1]
	global_load_lds_dwordx4 v[174:175], off
	s_add_i32 m0, s57, 0x2000
	s_nop 0
	global_load_lds_dwordx4 v[238:239], off
	s_barrier
	s_waitcnt lgkmcnt(0)
	s_waitcnt lgkmcnt(0)
	v_mfma_f32_16x16x32_bf16 v[136:139], v[222:225], v[170:173], v[136:139]
	v_mfma_f32_16x16x32_bf16 v[132:135], v[230:233], v[170:173], v[132:135]
	v_mfma_f32_16x16x32_bf16 v[120:123], v[222:225], v[198:201], v[120:123]
	v_mfma_f32_16x16x32_bf16 v[116:119], v[230:233], v[198:201], v[116:119]
	v_mfma_f32_16x16x32_bf16 v[104:107], v[222:225], v[206:209], v[104:107]
	v_mfma_f32_16x16x32_bf16 v[100:103], v[230:233], v[206:209], v[100:103]
	v_mfma_f32_16x16x32_bf16 v[88:91], v[222:225], v[214:217], v[88:91]
	v_mfma_f32_16x16x32_bf16 v[84:87], v[230:233], v[214:217], v[84:87]
	v_mfma_f32_16x16x32_bf16 v[136:139], v[226:229], v[194:197], v[136:139]
	v_mfma_f32_16x16x32_bf16 v[132:135], v[234:237], v[194:197], v[132:135]
	v_mfma_f32_16x16x32_bf16 v[120:123], v[226:229], v[202:205], v[120:123]
	v_mfma_f32_16x16x32_bf16 v[116:119], v[234:237], v[202:205], v[116:119]
	v_mfma_f32_16x16x32_bf16 v[104:107], v[226:229], v[210:213], v[104:107]
	v_mfma_f32_16x16x32_bf16 v[100:103], v[234:237], v[210:213], v[100:103]
	v_mfma_f32_16x16x32_bf16 v[88:91], v[226:229], v[218:221], v[88:91]
	v_mfma_f32_16x16x32_bf16 v[84:87], v[234:237], v[218:221], v[84:87]
	s_mov_b32 m0, s41
	v_lshl_add_u64 v[240:241], s[18:19], 0, v[164:165]
	s_barrier
	ds_read_b128 v[170:173], v192 offset:16384
	ds_read_b128 v[194:197], v192 offset:17408
	ds_read_b128 v[198:201], v192 offset:18432
	ds_read_b128 v[202:205], v192 offset:19456
	ds_read_b128 v[206:209], v192 offset:20480
	ds_read_b128 v[210:213], v192 offset:21504
	ds_read_b128 v[214:217], v192 offset:22528
	ds_read_b128 v[218:221], v192 offset:23552
	global_load_lds_dwordx4 v[240:241], off
	v_lshl_add_u64 v[242:243], s[18:19], 0, v[162:163]
	s_mov_b32 m0, s42
	s_nop 0
	global_load_lds_dwordx4 v[242:243], off
	s_barrier
	s_waitcnt lgkmcnt(0)
	s_waitcnt lgkmcnt(0)
	v_mfma_f32_16x16x32_bf16 v[80:83], v[28:31], v[170:173], v[80:83]
	v_mfma_f32_16x16x32_bf16 v[76:79], v[60:63], v[170:173], v[76:79]
	v_mfma_f32_16x16x32_bf16 v[56:59], v[28:31], v[198:201], v[56:59]
	v_mfma_f32_16x16x32_bf16 v[52:55], v[60:63], v[198:201], v[52:55]
	v_mfma_f32_16x16x32_bf16 v[40:43], v[28:31], v[206:209], v[40:43]
	v_mfma_f32_16x16x32_bf16 v[36:39], v[60:63], v[206:209], v[36:39]
	v_mfma_f32_16x16x32_bf16 v[16:19], v[28:31], v[214:217], v[16:19]
	v_mfma_f32_16x16x32_bf16 v[12:15], v[60:63], v[214:217], v[12:15]
	v_mfma_f32_16x16x32_bf16 v[80:83], v[32:35], v[194:197], v[80:83]
	v_mfma_f32_16x16x32_bf16 v[76:79], v[64:67], v[194:197], v[76:79]
	v_mfma_f32_16x16x32_bf16 v[56:59], v[32:35], v[202:205], v[56:59]
	v_mfma_f32_16x16x32_bf16 v[52:55], v[64:67], v[202:205], v[52:55]
	v_mfma_f32_16x16x32_bf16 v[40:43], v[32:35], v[210:213], v[40:43]
	v_mfma_f32_16x16x32_bf16 v[36:39], v[64:67], v[210:213], v[36:39]
	v_mfma_f32_16x16x32_bf16 v[16:19], v[32:35], v[218:221], v[16:19]
	v_mfma_f32_16x16x32_bf16 v[12:15], v[64:67], v[218:221], v[12:15]
	s_barrier
; #define PG8_STAGE(bufoff, gbase, voff) do { _Pragma("unroll") for (int _i = 0; _i < 2; ++_i) \
;         __builtin_amdgcn_global_load_lds((const unsigned*)((const char*)(gbase) + (voff)[_i]), (LAS unsigned*)(lds + (bufoff) + ldsw + _i * 8192), 16, 0, 0); } while (0)
; #define PG8_LDA(dst, b, h) do { _Pragma("unroll") for (int m = 0; m < 4; ++m) _Pragma("unroll") for (int k = 0; k < 2; ++k) dst[m][k] = *(const LAS h8*)(lds + PG8_SA(b, h) + aoff + m * 2048 + k * 1024); } while (0)
; #define PG8_LDB(dst, b, h) do { _Pragma("unroll") for (int n = 0; n < 2; ++n) _Pragma("unroll") for (int k = 0; k < 2; ++k) dst[n][k] = *(const LAS h8*)(lds + PG8_SB(b, h) + boff + n * 2048 + k * 1024); } while (0)
; #define PG8_WAIT_V(n) asm volatile("s_waitcnt vmcnt(" #n ")" ::: "memory")
; #define PG8_WAIT_L(n) asm volatile("s_waitcnt lgkmcnt(" #n ")" ::: "memory")
; #define PG8_BAR __builtin_amdgcn_s_barrier()
; #define PG8_SCHED __builtin_amdgcn_sched_barrier(0)
; template <class Epi>
; __device__ __forceinline__ void gemm_phase(LAS unsigned char* lds, const Gemm g, const StaticOrder& S, const Epi& E, const int tid) {
;     ...
;             PG8_STAGE(PG8_SB(0, 1), b2 + hstepB, voffB);
;             PG8_WAIT_V(6); PG8_BAR; PG8_MMA(1, 1, At, B1); PG8_BAR;
;             PG8_LDB(B0, 1, 0); PG8_SCHED; PG8_LDA(At, 1, 0); PG8_STAGE(PG8_SA(0, 1), a2 + hstep, voffA);
;             PG8_WAIT_L(8); PG8_BAR; PG8_WAIT_L(0); PG8_MMA(0, 0, At, B0); PG8_BAR; PG8_SCHED;
;             PG8_LDB(B1, 1, 1); PG8_STAGE(PG8_SB(1, 0), b3, voffB);
;             PG8_BAR; PG8_WAIT_L(0); PG8_MMA(0, 1, At, B1); PG8_BAR;
;             PG8_LDA(At, 1, 1); PG8_STAGE(PG8_SA(1, 0), a3, voffA);
;             PG8_BAR; PG8_WAIT_L(0); PG8_MMA(1, 0, At, B0); PG8_BAR; PG8_SCHED;
;             PG8_STAGE(PG8_SB(1, 1), b3 + hstepB, voffB);
	s_add_u32 s58, s14, 0x80000
	s_addc_u32 s59, s15, 0
	s_add_i32 s57, s60, s40
	v_lshl_add_u64 v[28:29], s[58:59], 0, v[2:3]
	s_mov_b32 m0, s57
	s_nop 0
	global_load_lds_dwordx4 v[28:29], off
	v_lshl_add_u64 v[28:29], s[58:59], 0, v[0:1]
	s_add_i32 m0, s57, 0x2000
	s_nop 0
	global_load_lds_dwordx4 v[28:29], off
	s_waitcnt vmcnt(6)
	s_barrier
	v_mfma_f32_16x16x32_bf16 v[48:51], v[222:225], v[198:201], v[48:51]
	v_mfma_f32_16x16x32_bf16 v[44:47], v[230:233], v[198:201], v[44:47]
	v_mfma_f32_16x16x32_bf16 v[24:27], v[222:225], v[206:209], v[24:27]
	v_mfma_f32_16x16x32_bf16 v[20:23], v[230:233], v[206:209], v[20:23]
	v_mfma_f32_16x16x32_bf16 v[8:11], v[222:225], v[214:217], v[8:11]
	v_mfma_f32_16x16x32_bf16 v[4:7], v[230:233], v[214:217], v[4:7]
	v_mfma_f32_16x16x32_bf16 v[28:31], v[222:225], v[170:173], v[72:75]
	v_mfma_f32_16x16x32_bf16 v[32:35], v[230:233], v[170:173], v[68:71]
	v_mfma_f32_16x16x32_bf16 v[48:51], v[226:229], v[202:205], v[48:51]
	v_mfma_f32_16x16x32_bf16 v[44:47], v[234:237], v[202:205], v[44:47]
	v_mfma_f32_16x16x32_bf16 v[24:27], v[226:229], v[210:213], v[24:27]
	v_mfma_f32_16x16x32_bf16 v[20:23], v[234:237], v[210:213], v[20:23]
	v_mfma_f32_16x16x32_bf16 v[8:11], v[226:229], v[218:221], v[8:11]
	v_mfma_f32_16x16x32_bf16 v[4:7], v[234:237], v[218:221], v[4:7]
	v_mfma_f32_16x16x32_bf16 v[28:31], v[226:229], v[194:197], v[28:31]
	v_mfma_f32_16x16x32_bf16 v[32:35], v[234:237], v[194:197], v[32:35]
	s_add_i32 s57, 0, 0x18000
	v_add_u32_e32 v72, s57, v190
	s_barrier
	ds_read_b128 v[60:63], v72
	ds_read_b128 v[64:67], v72 offset:1024
	ds_read_b128 v[68:71], v72 offset:2048
	ds_read_b128 v[72:75], v72 offset:3072
	s_add_u32 s18, s18, 0x80000
	s_addc_u32 s19, s19, 0
	s_mov_b32 m0, s43
	v_lshl_add_u64 v[222:223], s[18:19], 0, v[164:165]
	ds_read_b128 v[170:173], v192 offset:32768
	ds_read_b128 v[194:197], v192 offset:33792
	ds_read_b128 v[198:201], v192 offset:34816
	ds_read_b128 v[202:205], v192 offset:35840
	ds_read_b128 v[206:209], v192 offset:36864
	ds_read_b128 v[210:213], v192 offset:37888
	ds_read_b128 v[214:217], v192 offset:38912
	ds_read_b128 v[218:221], v192 offset:39936
	global_load_lds_dwordx4 v[222:223], off
	v_lshl_add_u64 v[222:223], s[18:19], 0, v[162:163]
	s_mov_b32 m0, s46
	s_nop 0
	global_load_lds_dwordx4 v[222:223], off
	s_waitcnt lgkmcnt(8)
	s_barrier
	s_waitcnt lgkmcnt(0)
	s_waitcnt lgkmcnt(0)
	v_mfma_f32_16x16x32_bf16 v[144:147], v[60:63], v[170:173], v[144:147]
	v_mfma_f32_16x16x32_bf16 v[140:143], v[68:71], v[170:173], v[140:143]
	v_mfma_f32_16x16x32_bf16 v[128:131], v[60:63], v[198:201], v[128:131]
	v_mfma_f32_16x16x32_bf16 v[124:127], v[68:71], v[198:201], v[124:127]
	v_mfma_f32_16x16x32_bf16 v[112:115], v[60:63], v[206:209], v[112:115]
	v_mfma_f32_16x16x32_bf16 v[108:111], v[68:71], v[206:209], v[108:111]
	v_mfma_f32_16x16x32_bf16 v[96:99], v[60:63], v[214:217], v[96:99]
	v_mfma_f32_16x16x32_bf16 v[92:95], v[68:71], v[214:217], v[92:95]
	v_mfma_f32_16x16x32_bf16 v[144:147], v[64:67], v[194:197], v[144:147]
	v_mfma_f32_16x16x32_bf16 v[140:143], v[72:75], v[194:197], v[140:143]
	v_mfma_f32_16x16x32_bf16 v[128:131], v[64:67], v[202:205], v[128:131]
	v_mfma_f32_16x16x32_bf16 v[124:127], v[72:75], v[202:205], v[124:127]
	v_mfma_f32_16x16x32_bf16 v[112:115], v[64:67], v[210:213], v[112:115]
	v_mfma_f32_16x16x32_bf16 v[108:111], v[72:75], v[210:213], v[108:111]
	v_mfma_f32_16x16x32_bf16 v[96:99], v[64:67], v[218:221], v[96:99]
	v_mfma_f32_16x16x32_bf16 v[92:95], v[72:75], v[218:221], v[92:95]
	s_barrier
	s_add_i32 s18, 0, 0x1c000
	s_add_i32 s19, s57, s40
	v_add_u32_e32 v193, s18, v190
	v_lshl_add_u64 v[174:175], v[174:175], 0, s[30:31]
	s_mov_b32 m0, s19
	ds_read_b128 v[222:225], v193
	ds_read_b128 v[226:229], v193 offset:1024
	ds_read_b128 v[230:233], v193 offset:2048
	ds_read_b128 v[234:237], v193 offset:3072
	global_load_lds_dwordx4 v[174:175], off
	v_lshl_add_u64 v[174:175], v[238:239], 0, s[30:31]
	s_add_i32 m0, s19, 0x2000
	s_nop 0
	global_load_lds_dwordx4 v[174:175], off
	s_barrier
	s_waitcnt lgkmcnt(0)
	s_waitcnt lgkmcnt(0)
	v_mfma_f32_16x16x32_bf16 v[136:139], v[222:225], v[170:173], v[136:139]
	v_mfma_f32_16x16x32_bf16 v[132:135], v[230:233], v[170:173], v[132:135]
	v_mfma_f32_16x16x32_bf16 v[120:123], v[222:225], v[198:201], v[120:123]
	v_mfma_f32_16x16x32_bf16 v[116:119], v[230:233], v[198:201], v[116:119]
	v_mfma_f32_16x16x32_bf16 v[104:107], v[222:225], v[206:209], v[104:107]
	v_mfma_f32_16x16x32_bf16 v[100:103], v[230:233], v[206:209], v[100:103]
	v_mfma_f32_16x16x32_bf16 v[88:91], v[222:225], v[214:217], v[88:91]
	v_mfma_f32_16x16x32_bf16 v[84:87], v[230:233], v[214:217], v[84:87]
	v_mfma_f32_16x16x32_bf16 v[136:139], v[226:229], v[194:197], v[136:139]
	v_mfma_f32_16x16x32_bf16 v[132:135], v[234:237], v[194:197], v[132:135]
	v_mfma_f32_16x16x32_bf16 v[120:123], v[226:229], v[202:205], v[120:123]
	v_mfma_f32_16x16x32_bf16 v[116:119], v[234:237], v[202:205], v[116:119]
	v_mfma_f32_16x16x32_bf16 v[104:107], v[226:229], v[210:213], v[104:107]
	v_mfma_f32_16x16x32_bf16 v[100:103], v[234:237], v[210:213], v[100:103]
	v_mfma_f32_16x16x32_bf16 v[88:91], v[226:229], v[218:221], v[88:91]
	v_mfma_f32_16x16x32_bf16 v[84:87], v[234:237], v[218:221], v[84:87]
	s_mov_b32 m0, s47
	v_lshl_add_u64 v[174:175], v[240:241], 0, s[30:31]
	s_barrier
	ds_read_b128 v[170:173], v192 offset:49152
	ds_read_b128 v[194:197], v192 offset:50176
	ds_read_b128 v[198:201], v192 offset:51200
	ds_read_b128 v[202:205], v192 offset:52224
	ds_read_b128 v[206:209], v192 offset:53248
	ds_read_b128 v[210:213], v192 offset:54272
	ds_read_b128 v[214:217], v192 offset:55296
	ds_read_b128 v[218:221], v192 offset:56320
	global_load_lds_dwordx4 v[174:175], off
	v_lshl_add_u64 v[174:175], v[242:243], 0, s[30:31]
	s_mov_b32 m0, s48
	s_nop 0
	global_load_lds_dwordx4 v[174:175], off
	s_barrier
; #define PG8_STAGE(bufoff, gbase, voff) do { _Pragma("unroll") for (int _i = 0; _i < 2; ++_i) \
;         __builtin_amdgcn_global_load_lds((const unsigned*)((const char*)(gbase) + (voff)[_i]), (LAS unsigned*)(lds + (bufoff) + ldsw + _i * 8192), 16, 0, 0); } while (0)
; #define PG8_WAIT_V(n) asm volatile("s_waitcnt vmcnt(" #n ")" ::: "memory")
; #define PG8_WAIT_L(n) asm volatile("s_waitcnt lgkmcnt(" #n ")" ::: "memory")
; #define PG8_BAR __builtin_amdgcn_s_barrier()
; template <class Epi>
; __device__ __forceinline__ void gemm_phase(LAS unsigned char* lds, const Gemm g, const StaticOrder& S, const Epi& E, const int tid) {
;     ...
;             PG8_BAR; PG8_WAIT_L(0); PG8_MMA(1, 0, At, B0); PG8_BAR; PG8_SCHED;
;             PG8_STAGE(PG8_SB(1, 1), b3 + hstepB, voffB);
;             PG8_WAIT_V(6); PG8_BAR; PG8_MMA(1, 1, At, B1); PG8_BAR;
;     __device__ __forceinline__ void operator()(const f32x4 (&acc)[2][2][4][2], const pg8::Unit& u, int wr, int wc, int fr, int fq) const {
;         const int row0 = u.pm * 256 + wr * 64 + fr, col0 = u.pn * 256 + wc * 32 + 8 * fq;
;         const float* gp = gate + (size_t)((u.pm * 256) >> 12) * 6144 + col0;
;         f32x4 gv[2][2];
; #pragma unroll
;         for (int bj = 0; bj < 2; ++bj)
; #pragma unroll
;             for (int n = 0; n < 2; ++n) gv[bj][n] = *(const f32x4*)(gp + bj * 128 + 4 * n);
; #pragma unroll
;         for (int ai = 0; ai < 2; ++ai)
; #pragma unroll
;             for (int m = 0; m < 4; ++m) { const size_t ro = (size_t)(row0 + ai * 128 + m * 16) * DM + col0;
; #pragma unroll
;                 for (int bj = 0; bj < 2; ++bj) {
;                     f32x4 x0, x1;
;                     if (XF32) { x0 = *(const f32x4*)(xin + ro + bj * 128); x1 = *(const f32x4*)(xin + ro + bj * 128 + 4); }
;                     else { const h8 xh = *(const h8*)(H + ro + bj * 128); x0 = (f32x4){(float)xh[0], (float)xh[1], (float)xh[2], (float)xh[3]}; x1 = (f32x4){(float)xh[4], (float)xh[5], (float)xh[6], (float)xh[7]}; }
;                     const f32x4 y0 = x0 + gv[bj][0] * acc[ai][bj][m][0], y1 = x1 + gv[bj][1] * acc[ai][bj][m][1];
;                     h8 o; o[0] = (half_t)y0[0]; o[1] = (half_t)y0[1]; o[2] = (half_t)y0[2]; o[3] = (half_t)y0[3]; o[4] = (half_t)y1[0]; o[5] = (half_t)y1[1]; o[6] = (half_t)y1[2]; o[7] = (half_t)y1[3];
;                     *(h8*)(H + ro + bj * 128) = o; } }
	s_waitcnt lgkmcnt(0)
	s_waitcnt lgkmcnt(0)
	v_mfma_f32_16x16x32_bf16 v[80:83], v[60:63], v[170:173], v[80:83]
	v_mfma_f32_16x16x32_bf16 v[76:79], v[68:71], v[170:173], v[76:79]
	v_mfma_f32_16x16x32_bf16 v[56:59], v[60:63], v[198:201], v[56:59]
	v_mfma_f32_16x16x32_bf16 v[52:55], v[68:71], v[198:201], v[52:55]
	v_mfma_f32_16x16x32_bf16 v[40:43], v[60:63], v[206:209], v[40:43]
	v_mfma_f32_16x16x32_bf16 v[36:39], v[68:71], v[206:209], v[36:39]
	v_mfma_f32_16x16x32_bf16 v[16:19], v[60:63], v[214:217], v[16:19]
	v_mfma_f32_16x16x32_bf16 v[12:15], v[68:71], v[214:217], v[12:15]
	v_mfma_f32_16x16x32_bf16 v[80:83], v[64:67], v[194:197], v[80:83]
	v_mfma_f32_16x16x32_bf16 v[76:79], v[72:75], v[194:197], v[76:79]
	v_mfma_f32_16x16x32_bf16 v[56:59], v[64:67], v[202:205], v[56:59]
	v_mfma_f32_16x16x32_bf16 v[52:55], v[72:75], v[202:205], v[52:55]
	v_mfma_f32_16x16x32_bf16 v[40:43], v[64:67], v[210:213], v[40:43]
	v_mfma_f32_16x16x32_bf16 v[36:39], v[72:75], v[210:213], v[36:39]
	v_mfma_f32_16x16x32_bf16 v[16:19], v[64:67], v[218:221], v[16:19]
	v_mfma_f32_16x16x32_bf16 v[12:15], v[72:75], v[218:221], v[12:15]
	s_barrier
	s_add_u32 s14, s14, 0x80080
	s_addc_u32 s15, s15, 0
	s_add_i32 s18, s18, s40
	v_lshl_add_u64 v[60:61], s[14:15], 0, v[2:3]
	s_mov_b32 m0, s18
	s_nop 0
	global_load_lds_dwordx4 v[60:61], off
	v_lshl_add_u64 v[60:61], s[14:15], 0, v[0:1]
	s_add_i32 m0, s18, 0x2000
	s_nop 0
	global_load_lds_dwordx4 v[60:61], off
	s_waitcnt vmcnt(6)
	s_barrier
	v_mfma_f32_16x16x32_bf16 v[28:31], v[222:225], v[170:173], v[28:31]
	v_mfma_f32_16x16x32_bf16 v[72:75], v[226:229], v[194:197], v[28:31]
	v_mfma_f32_16x16x32_bf16 v[28:31], v[230:233], v[170:173], v[32:35]
	v_mfma_f32_16x16x32_bf16 v[68:71], v[234:237], v[194:197], v[28:31]
	v_mfma_f32_16x16x32_bf16 v[28:31], v[222:225], v[198:201], v[48:51]
	v_mfma_f32_16x16x32_bf16 v[48:51], v[226:229], v[202:205], v[28:31]
	v_mfma_f32_16x16x32_bf16 v[28:31], v[230:233], v[198:201], v[44:47]
	v_mfma_f32_16x16x32_bf16 v[24:27], v[222:225], v[206:209], v[24:27]
	v_mfma_f32_16x16x32_bf16 v[20:23], v[230:233], v[206:209], v[20:23]
	v_mfma_f32_16x16x32_bf16 v[8:11], v[222:225], v[214:217], v[8:11]
	v_mfma_f32_16x16x32_bf16 v[4:7], v[230:233], v[214:217], v[4:7]
	v_mfma_f32_16x16x32_bf16 v[44:47], v[234:237], v[202:205], v[28:31]
	v_mfma_f32_16x16x32_bf16 v[24:27], v[226:229], v[210:213], v[24:27]
	v_mfma_f32_16x16x32_bf16 v[20:23], v[234:237], v[210:213], v[20:23]
	v_mfma_f32_16x16x32_bf16 v[8:11], v[226:229], v[218:221], v[8:11]
	v_mfma_f32_16x16x32_bf16 v[4:7], v[234:237], v[218:221], v[4:7]
	s_add_i32 s56, s56, 2
	s_add_u32 s12, s12, 0x100
	s_addc_u32 s13, s13, 0
	s_add_u32 s54, s54, 0x100
	s_addc_u32 s55, s55, 0
	s_cmp_gt_u32 s56, 29
	s_barrier
	s_cbranch_scc0 .LBB0_660
	s_ashr_i32 s1, s50, 4
	v_lshl_add_u32 v172, s50, 8, v189
	v_lshl_or_b32 v170, s51, 8, v191
	s_mul_hi_i32 s7, s1, 0x6000
	s_mulk_i32 s1, 0x6000
	v_ashrrev_i32_e32 v173, 31, v172
	s_add_u32 s12, s23, s1
	v_ashrrev_i32_e32 v171, 31, v170
	v_lshlrev_b64 v[174:175], 12, v[172:173]
	s_addc_u32 s13, s24, s7
	v_lshl_add_u64 v[194:195], s[16:17], 0, v[174:175]
	v_lshlrev_b64 v[174:175], 1, v[170:171]
	v_lshl_add_u64 v[32:33], v[170:171], 2, s[12:13]
	v_lshl_add_u64 v[170:171], v[194:195], 0, v[174:175]
	global_load_dwordx4 v[60:63], v[32:33], off offset:16
	global_load_dwordx4 v[64:67], v[32:33], off
	global_load_dwordx4 v[28:31], v[32:33], off offset:528
	s_nop 0
	global_load_dwordx4 v[32:35], v[32:33], off offset:512
	v_add_co_u32_e32 v242, vcc, 0, v170
	s_nop 1
	v_addc_co_u32_e32 v243, vcc, 0, v171, vcc
	global_load_dwordx4 v[202:205], v[242:243], off
	v_add_co_u32_e32 v242, vcc, 0, v170
	s_nop 1
	v_addc_co_u32_e32 v243, vcc, 0, v171, vcc
	global_load_dwordx4 v[206:209], v[242:243], off offset:256
	v_add_co_u32_e32 v242, vcc, 0x10000, v170
	s_nop 1
	v_addc_co_u32_e32 v243, vcc, 0, v171, vcc
	global_load_dwordx4 v[210:213], v[242:243], off
	v_add_co_u32_e32 v242, vcc, 0x10000, v170
	s_nop 1
	v_addc_co_u32_e32 v243, vcc, 0, v171, vcc
	global_load_dwordx4 v[214:217], v[242:243], off offset:256
	v_add_co_u32_e32 v242, vcc, 0x20000, v170
	s_nop 1
	v_addc_co_u32_e32 v243, vcc, 0, v171, vcc
	global_load_dwordx4 v[218:221], v[242:243], off
	v_add_co_u32_e32 v242, vcc, 0x20000, v170
	s_nop 1
	v_addc_co_u32_e32 v243, vcc, 0, v171, vcc
	global_load_dwordx4 v[222:225], v[242:243], off offset:256
	v_add_co_u32_e32 v242, vcc, 0x30000, v170
	s_nop 1
	v_addc_co_u32_e32 v243, vcc, 0, v171, vcc
	global_load_dwordx4 v[226:229], v[242:243], off
	v_add_co_u32_e32 v242, vcc, 0x30000, v170
	s_nop 1
	v_addc_co_u32_e32 v243, vcc, 0, v171, vcc
	global_load_dwordx4 v[230:233], v[242:243], off offset:256
	v_add_co_u32_e32 v242, vcc, 0x80000, v170
	s_nop 1
	v_addc_co_u32_e32 v243, vcc, 0, v171, vcc
	global_load_dwordx4 v[234:237], v[242:243], off
	v_add_co_u32_e32 v242, vcc, 0x80000, v170
	s_nop 1
	v_addc_co_u32_e32 v243, vcc, 0, v171, vcc
	global_load_dwordx4 v[238:241], v[242:243], off offset:256
	v_add_co_u32_e32 v242, vcc, 0x90000, v170
	s_nop 1
	v_addc_co_u32_e32 v243, vcc, 0, v171, vcc
	global_load_dwordx4 v[244:247], v[242:243], off
	s_mov_b32 s1, 0x80000
	s_nop 1
	s_waitcnt vmcnt(10)
;     __device__ __forceinline__ void operator()(const f32x4 (&acc)[2][2][4][2], const pg8::Unit& u, int wr, int wc, int fr, int fq) const {
;     ...
;         for (int ai = 0; ai < 2; ++ai)
; #pragma unroll
;             for (int m = 0; m < 4; ++m) { const size_t ro = (size_t)(row0 + ai * 128 + m * 16) * DM + col0;
; #pragma unroll
;                 for (int bj = 0; bj < 2; ++bj) {
;                     f32x4 x0, x1;
;                     if (XF32) { x0 = *(const f32x4*)(xin + ro + bj * 128); x1 = *(const f32x4*)(xin + ro + bj * 128 + 4); }
;                     else { const h8 xh = *(const h8*)(H + ro + bj * 128); x0 = (f32x4){(float)xh[0], (float)xh[1], (float)xh[2], (float)xh[3]}; x1 = (f32x4){(float)xh[4], (float)xh[5], (float)xh[6], (float)xh[7]}; }
;                     const f32x4 y0 = x0 + gv[bj][0] * acc[ai][bj][m][0], y1 = x1 + gv[bj][1] * acc[ai][bj][m][1];
;                     h8 o; o[0] = (half_t)y0[0]; o[1] = (half_t)y0[1]; o[2] = (half_t)y0[2]; o[3] = (half_t)y0[3]; o[4] = (half_t)y1[0]; o[5] = (half_t)y1[1]; o[6] = (half_t)y1[2]; o[7] = (half_t)y1[3];
;                     *(h8*)(H + ro + bj * 128) = o; } }
	v_mov_b32_e32 v194, v202
	v_mov_b32_e32 v195, v203
	v_mov_b32_e32 v196, v204
	v_mov_b32_e32 v197, v205
	v_add_co_u32_e32 v242, vcc, 0x90000, v170
	s_nop 1
	v_addc_co_u32_e32 v243, vcc, 0, v171, vcc
	global_load_dwordx4 v[202:205], v[242:243], off offset:256
	s_mov_b64 s[12:13], 0x80000
	s_mov_b32 s51, s0
	s_mov_b32 s50, s6
	s_mov_b64 s[14:15], s[10:11]
	v_readlane_b32 s59, v251, 43
	s_nop 0
	v_cvt_f32_f16_e32 v198, v194
	v_cvt_f32_f16_sdwa v199, v194 dst_sel:DWORD dst_unused:UNUSED_PAD src0_sel:WORD_1
	v_cvt_f32_f16_e32 v194, v195
	v_cvt_f32_f16_sdwa v195, v195 dst_sel:DWORD dst_unused:UNUSED_PAD src0_sel:WORD_1
	v_cvt_f32_f16_e32 v200, v196
	v_cvt_f32_f16_sdwa v201, v196 dst_sel:DWORD dst_unused:UNUSED_PAD src0_sel:WORD_1
	v_cvt_f32_f16_e32 v196, v197
	v_cvt_f32_f16_sdwa v197, v197 dst_sel:DWORD dst_unused:UNUSED_PAD src0_sel:WORD_1
	v_pk_fma_f32 v[146:147], v[146:147], v[66:67], v[194:195]
	v_pk_fma_f32 v[144:145], v[144:145], v[64:65], v[198:199]
	v_pk_fma_f32 v[140:141], v[140:141], v[60:61], v[200:201]
	v_pk_fma_f32 v[142:143], v[142:143], v[62:63], v[196:197]
	s_nop 0
	v_cvt_pk_f16_f32 v143, v142, v143
	v_cvt_pk_f16_f32 v142, v140, v141
	v_cvt_pk_f16_f32 v141, v146, v147
	v_cvt_pk_f16_f32 v140, v144, v145
	global_store_dwordx4 v[170:171], v[140:143], off
	s_nop 1
	s_waitcnt vmcnt(10)
	v_mov_b32_e32 v140, v206
	v_mov_b32_e32 v141, v207
	v_mov_b32_e32 v142, v208
	v_mov_b32_e32 v143, v209
	v_add_co_u32_e32 v242, vcc, 0xa0000, v170
	s_nop 1
	v_addc_co_u32_e32 v243, vcc, 0, v171, vcc
	global_load_dwordx4 v[206:209], v[242:243], off
	s_nop 0
	v_cvt_f32_f16_e32 v144, v140
	v_cvt_f32_f16_sdwa v145, v140 dst_sel:DWORD dst_unused:UNUSED_PAD src0_sel:WORD_1
	v_cvt_f32_f16_e32 v140, v141
	v_cvt_f32_f16_sdwa v141, v141 dst_sel:DWORD dst_unused:UNUSED_PAD src0_sel:WORD_1
	v_cvt_f32_f16_e32 v146, v142
	v_cvt_f32_f16_sdwa v147, v142 dst_sel:DWORD dst_unused:UNUSED_PAD src0_sel:WORD_1
	v_cvt_f32_f16_e32 v142, v143
	v_cvt_f32_f16_sdwa v143, v143 dst_sel:DWORD dst_unused:UNUSED_PAD src0_sel:WORD_1
	v_pk_fma_f32 v[138:139], v[138:139], v[34:35], v[140:141]
	v_pk_fma_f32 v[136:137], v[136:137], v[32:33], v[144:145]
	v_pk_fma_f32 v[132:133], v[132:133], v[28:29], v[146:147]
	v_pk_fma_f32 v[134:135], v[134:135], v[30:31], v[142:143]
	s_nop 0
	v_cvt_pk_f16_f32 v135, v134, v135
	v_cvt_pk_f16_f32 v134, v132, v133
	v_cvt_pk_f16_f32 v133, v138, v139
	v_cvt_pk_f16_f32 v132, v136, v137
	global_store_dwordx4 v[170:171], v[132:135], off offset:256
	s_nop 1
	v_or_b32_e32 v132, 16, v172
	v_ashrrev_i32_e32 v133, 31, v132
	v_lshlrev_b64 v[132:133], 12, v[132:133]
	v_lshl_add_u64 v[132:133], s[16:17], 0, v[132:133]
	v_lshl_add_u64 v[136:137], v[132:133], 0, v[174:175]
	s_nop 1
	s_waitcnt vmcnt(10)
	v_mov_b32_e32 v132, v210
	v_mov_b32_e32 v133, v211
	v_mov_b32_e32 v134, v212
	v_mov_b32_e32 v135, v213
	v_add_co_u32_e32 v242, vcc, 0xa0000, v170
	s_nop 1
	v_addc_co_u32_e32 v243, vcc, 0, v171, vcc
	global_load_dwordx4 v[210:213], v[242:243], off offset:256
	s_nop 0
	v_cvt_f32_f16_e32 v138, v132
	v_cvt_f32_f16_sdwa v139, v132 dst_sel:DWORD dst_unused:UNUSED_PAD src0_sel:WORD_1
	v_cvt_f32_f16_e32 v132, v133
	v_cvt_f32_f16_sdwa v133, v133 dst_sel:DWORD dst_unused:UNUSED_PAD src0_sel:WORD_1
	v_cvt_f32_f16_e32 v140, v134
	v_cvt_f32_f16_sdwa v141, v134 dst_sel:DWORD dst_unused:UNUSED_PAD src0_sel:WORD_1
	v_cvt_f32_f16_e32 v134, v135
	v_cvt_f32_f16_sdwa v135, v135 dst_sel:DWORD dst_unused:UNUSED_PAD src0_sel:WORD_1
	v_pk_fma_f32 v[130:131], v[130:131], v[66:67], v[132:133]
	v_pk_fma_f32 v[128:129], v[128:129], v[64:65], v[138:139]
	v_pk_fma_f32 v[124:125], v[124:125], v[60:61], v[140:141]
	v_pk_fma_f32 v[126:127], v[126:127], v[62:63], v[134:135]
	s_nop 0
	v_cvt_pk_f16_f32 v127, v126, v127
	v_cvt_pk_f16_f32 v126, v124, v125
	v_cvt_pk_f16_f32 v125, v130, v131
	v_cvt_pk_f16_f32 v124, v128, v129
	global_store_dwordx4 v[136:137], v[124:127], off
	s_nop 1
	s_waitcnt vmcnt(10)
	v_mov_b32_e32 v124, v214
	v_mov_b32_e32 v125, v215
	v_mov_b32_e32 v126, v216
	v_mov_b32_e32 v127, v217
	v_add_co_u32_e32 v242, vcc, 0xb0000, v170
	s_nop 1
	v_addc_co_u32_e32 v243, vcc, 0, v171, vcc
	global_load_dwordx4 v[214:217], v[242:243], off
	s_nop 0
	v_cvt_f32_f16_e32 v128, v124
	v_cvt_f32_f16_sdwa v129, v124 dst_sel:DWORD dst_unused:UNUSED_PAD src0_sel:WORD_1
	v_cvt_f32_f16_e32 v124, v125
	v_cvt_f32_f16_sdwa v125, v125 dst_sel:DWORD dst_unused:UNUSED_PAD src0_sel:WORD_1
	v_cvt_f32_f16_e32 v130, v126
	v_cvt_f32_f16_sdwa v131, v126 dst_sel:DWORD dst_unused:UNUSED_PAD src0_sel:WORD_1
	v_cvt_f32_f16_e32 v126, v127
	v_cvt_f32_f16_sdwa v127, v127 dst_sel:DWORD dst_unused:UNUSED_PAD src0_sel:WORD_1
	v_pk_fma_f32 v[122:123], v[122:123], v[34:35], v[124:125]
	v_pk_fma_f32 v[120:121], v[120:121], v[32:33], v[128:129]
	v_pk_fma_f32 v[116:117], v[116:117], v[28:29], v[130:131]
	v_pk_fma_f32 v[118:119], v[118:119], v[30:31], v[126:127]
	s_nop 0
	v_cvt_pk_f16_f32 v119, v118, v119
	v_cvt_pk_f16_f32 v118, v116, v117
	v_cvt_pk_f16_f32 v117, v122, v123
	v_cvt_pk_f16_f32 v116, v120, v121
	global_store_dwordx4 v[136:137], v[116:119], off offset:256
	s_nop 1
	v_or_b32_e32 v116, 32, v172
	v_ashrrev_i32_e32 v117, 31, v116
	v_lshlrev_b64 v[116:117], 12, v[116:117]
	v_lshl_add_u64 v[116:117], s[16:17], 0, v[116:117]
	v_lshl_add_u64 v[120:121], v[116:117], 0, v[174:175]
	s_nop 1
	s_waitcnt vmcnt(10)
;     __device__ __forceinline__ void operator()(const f32x4 (&acc)[2][2][4][2], const pg8::Unit& u, int wr, int wc, int fr, int fq) const {
;     ...
;         for (int ai = 0; ai < 2; ++ai)
; #pragma unroll
;             for (int m = 0; m < 4; ++m) { const size_t ro = (size_t)(row0 + ai * 128 + m * 16) * DM + col0;
; #pragma unroll
;                 for (int bj = 0; bj < 2; ++bj) {
;                     f32x4 x0, x1;
;                     if (XF32) { x0 = *(const f32x4*)(xin + ro + bj * 128); x1 = *(const f32x4*)(xin + ro + bj * 128 + 4); }
;                     else { const h8 xh = *(const h8*)(H + ro + bj * 128); x0 = (f32x4){(float)xh[0], (float)xh[1], (float)xh[2], (float)xh[3]}; x1 = (f32x4){(float)xh[4], (float)xh[5], (float)xh[6], (float)xh[7]}; }
;                     const f32x4 y0 = x0 + gv[bj][0] * acc[ai][bj][m][0], y1 = x1 + gv[bj][1] * acc[ai][bj][m][1];
;                     h8 o; o[0] = (half_t)y0[0]; o[1] = (half_t)y0[1]; o[2] = (half_t)y0[2]; o[3] = (half_t)y0[3]; o[4] = (half_t)y1[0]; o[5] = (half_t)y1[1]; o[6] = (half_t)y1[2]; o[7] = (half_t)y1[3];
;                     *(h8*)(H + ro + bj * 128) = o; } }
	v_mov_b32_e32 v116, v218
	v_mov_b32_e32 v117, v219
	v_mov_b32_e32 v118, v220
	v_mov_b32_e32 v119, v221
	v_add_co_u32_e32 v242, vcc, 0xb0000, v170
	s_nop 1
	v_addc_co_u32_e32 v243, vcc, 0, v171, vcc
	global_load_dwordx4 v[218:221], v[242:243], off offset:256
	s_nop 0
	v_cvt_f32_f16_e32 v122, v116
	v_cvt_f32_f16_sdwa v123, v116 dst_sel:DWORD dst_unused:UNUSED_PAD src0_sel:WORD_1
	v_cvt_f32_f16_e32 v116, v117
	v_cvt_f32_f16_sdwa v117, v117 dst_sel:DWORD dst_unused:UNUSED_PAD src0_sel:WORD_1
	v_cvt_f32_f16_e32 v124, v118
	v_cvt_f32_f16_sdwa v125, v118 dst_sel:DWORD dst_unused:UNUSED_PAD src0_sel:WORD_1
	v_cvt_f32_f16_e32 v118, v119
	v_cvt_f32_f16_sdwa v119, v119 dst_sel:DWORD dst_unused:UNUSED_PAD src0_sel:WORD_1
	v_pk_fma_f32 v[114:115], v[114:115], v[66:67], v[116:117]
	v_pk_fma_f32 v[112:113], v[112:113], v[64:65], v[122:123]
	v_pk_fma_f32 v[108:109], v[108:109], v[60:61], v[124:125]
	v_pk_fma_f32 v[110:111], v[110:111], v[62:63], v[118:119]
	s_nop 0
	v_cvt_pk_f16_f32 v111, v110, v111
	v_cvt_pk_f16_f32 v110, v108, v109
	v_cvt_pk_f16_f32 v109, v114, v115
	v_cvt_pk_f16_f32 v108, v112, v113
	global_store_dwordx4 v[120:121], v[108:111], off
	s_nop 1
	s_waitcnt vmcnt(10)
	v_mov_b32_e32 v108, v222
	v_mov_b32_e32 v109, v223
	v_mov_b32_e32 v110, v224
	v_mov_b32_e32 v111, v225
	s_nop 0
	v_cvt_f32_f16_e32 v112, v108
	v_cvt_f32_f16_sdwa v113, v108 dst_sel:DWORD dst_unused:UNUSED_PAD src0_sel:WORD_1
	v_cvt_f32_f16_e32 v108, v109
	v_cvt_f32_f16_sdwa v109, v109 dst_sel:DWORD dst_unused:UNUSED_PAD src0_sel:WORD_1
	v_cvt_f32_f16_e32 v114, v110
	v_cvt_f32_f16_sdwa v115, v110 dst_sel:DWORD dst_unused:UNUSED_PAD src0_sel:WORD_1
	v_cvt_f32_f16_e32 v110, v111
	v_cvt_f32_f16_sdwa v111, v111 dst_sel:DWORD dst_unused:UNUSED_PAD src0_sel:WORD_1
	v_pk_fma_f32 v[106:107], v[106:107], v[34:35], v[108:109]
	v_pk_fma_f32 v[104:105], v[104:105], v[32:33], v[112:113]
	v_pk_fma_f32 v[100:101], v[100:101], v[28:29], v[114:115]
	v_pk_fma_f32 v[102:103], v[102:103], v[30:31], v[110:111]
	s_nop 0
	v_cvt_pk_f16_f32 v103, v102, v103
	v_cvt_pk_f16_f32 v102, v100, v101
	v_cvt_pk_f16_f32 v101, v106, v107
	v_cvt_pk_f16_f32 v100, v104, v105
	global_store_dwordx4 v[120:121], v[100:103], off offset:256
	s_nop 1
	v_or_b32_e32 v100, 48, v172
	v_ashrrev_i32_e32 v101, 31, v100
	v_lshlrev_b64 v[100:101], 12, v[100:101]
	v_lshl_add_u64 v[100:101], s[16:17], 0, v[100:101]
	v_lshl_add_u64 v[104:105], v[100:101], 0, v[174:175]
	s_nop 1
	s_waitcnt vmcnt(9)
	v_mov_b32_e32 v100, v226
	v_mov_b32_e32 v101, v227
	v_mov_b32_e32 v102, v228
	v_mov_b32_e32 v103, v229
	s_nop 0
	v_cvt_f32_f16_e32 v106, v100
	v_cvt_f32_f16_sdwa v107, v100 dst_sel:DWORD dst_unused:UNUSED_PAD src0_sel:WORD_1
	v_cvt_f32_f16_e32 v100, v101
	v_cvt_f32_f16_sdwa v101, v101 dst_sel:DWORD dst_unused:UNUSED_PAD src0_sel:WORD_1
	v_cvt_f32_f16_e32 v108, v102
	v_cvt_f32_f16_sdwa v109, v102 dst_sel:DWORD dst_unused:UNUSED_PAD src0_sel:WORD_1
	v_cvt_f32_f16_e32 v102, v103
	v_cvt_f32_f16_sdwa v103, v103 dst_sel:DWORD dst_unused:UNUSED_PAD src0_sel:WORD_1
	v_pk_fma_f32 v[98:99], v[98:99], v[66:67], v[100:101]
	v_pk_fma_f32 v[96:97], v[96:97], v[64:65], v[106:107]
	v_pk_fma_f32 v[92:93], v[92:93], v[60:61], v[108:109]
	v_pk_fma_f32 v[94:95], v[94:95], v[62:63], v[102:103]
	s_nop 0
	v_cvt_pk_f16_f32 v95, v94, v95
	v_cvt_pk_f16_f32 v94, v92, v93
	v_cvt_pk_f16_f32 v93, v98, v99
	v_cvt_pk_f16_f32 v92, v96, v97
	global_store_dwordx4 v[104:105], v[92:95], off
	s_nop 1
	s_waitcnt vmcnt(8)
	v_mov_b32_e32 v92, v230
	v_mov_b32_e32 v93, v231
	v_mov_b32_e32 v94, v232
	v_mov_b32_e32 v95, v233
	s_nop 0
	v_cvt_f32_f16_e32 v96, v92
	v_cvt_f32_f16_sdwa v97, v92 dst_sel:DWORD dst_unused:UNUSED_PAD src0_sel:WORD_1
	v_cvt_f32_f16_e32 v92, v93
	v_cvt_f32_f16_sdwa v93, v93 dst_sel:DWORD dst_unused:UNUSED_PAD src0_sel:WORD_1
	v_cvt_f32_f16_e32 v98, v94
	v_cvt_f32_f16_sdwa v99, v94 dst_sel:DWORD dst_unused:UNUSED_PAD src0_sel:WORD_1
	v_cvt_f32_f16_e32 v94, v95
	v_cvt_f32_f16_sdwa v95, v95 dst_sel:DWORD dst_unused:UNUSED_PAD src0_sel:WORD_1
	v_pk_fma_f32 v[90:91], v[90:91], v[34:35], v[92:93]
	v_pk_fma_f32 v[84:85], v[84:85], v[28:29], v[98:99]
	v_pk_fma_f32 v[88:89], v[88:89], v[32:33], v[96:97]
	v_pk_fma_f32 v[86:87], v[86:87], v[30:31], v[94:95]
	s_nop 0
	v_cvt_pk_f16_f32 v87, v86, v87
	v_cvt_pk_f16_f32 v86, v84, v85
	v_cvt_pk_f16_f32 v85, v90, v91
	v_add_co_u32_e32 v90, vcc, s1, v170
	v_cvt_pk_f16_f32 v84, v88, v89
	s_nop 0
	v_addc_co_u32_e32 v91, vcc, 0, v171, vcc
	global_store_dwordx4 v[104:105], v[84:87], off offset:256
	s_nop 1
	s_waitcnt vmcnt(7)
	v_mov_b32_e32 v86, v234
	v_mov_b32_e32 v87, v235
	v_mov_b32_e32 v88, v236
	v_mov_b32_e32 v89, v237
	s_mov_b32 s1, 0x90000
	v_lshl_add_u64 v[84:85], v[170:171], 0, s[12:13]
	s_mov_b64 s[12:13], 0x90000
	s_nop 0
	v_cvt_f32_f16_e32 v92, v86
	v_cvt_f32_f16_sdwa v93, v86 dst_sel:DWORD dst_unused:UNUSED_PAD src0_sel:WORD_1
	v_cvt_f32_f16_e32 v86, v87
	v_cvt_f32_f16_sdwa v87, v87 dst_sel:DWORD dst_unused:UNUSED_PAD src0_sel:WORD_1
	v_cvt_f32_f16_e32 v94, v88
	v_cvt_f32_f16_sdwa v95, v88 dst_sel:DWORD dst_unused:UNUSED_PAD src0_sel:WORD_1
	v_cvt_f32_f16_e32 v88, v89
	v_cvt_f32_f16_sdwa v89, v89 dst_sel:DWORD dst_unused:UNUSED_PAD src0_sel:WORD_1
	v_pk_fma_f32 v[82:83], v[82:83], v[66:67], v[86:87]
	v_pk_fma_f32 v[80:81], v[80:81], v[64:65], v[92:93]
	v_pk_fma_f32 v[76:77], v[76:77], v[60:61], v[94:95]
	v_pk_fma_f32 v[78:79], v[78:79], v[62:63], v[88:89]
	s_nop 0
	v_cvt_pk_f16_f32 v79, v78, v79
	v_cvt_pk_f16_f32 v78, v76, v77
	v_cvt_pk_f16_f32 v77, v82, v83
	v_cvt_pk_f16_f32 v76, v80, v81
	global_store_dwordx4 v[90:91], v[76:79], off
	s_nop 1
	s_waitcnt vmcnt(6)
;     __device__ __forceinline__ void operator()(const f32x4 (&acc)[2][2][4][2], const pg8::Unit& u, int wr, int wc, int fr, int fq) const {
;     ...
;         for (int ai = 0; ai < 2; ++ai)
; #pragma unroll
;             for (int m = 0; m < 4; ++m) { const size_t ro = (size_t)(row0 + ai * 128 + m * 16) * DM + col0;
; #pragma unroll
;                 for (int bj = 0; bj < 2; ++bj) {
;                     f32x4 x0, x1;
;                     if (XF32) { x0 = *(const f32x4*)(xin + ro + bj * 128); x1 = *(const f32x4*)(xin + ro + bj * 128 + 4); }
;                     else { const h8 xh = *(const h8*)(H + ro + bj * 128); x0 = (f32x4){(float)xh[0], (float)xh[1], (float)xh[2], (float)xh[3]}; x1 = (f32x4){(float)xh[4], (float)xh[5], (float)xh[6], (float)xh[7]}; }
;                     const f32x4 y0 = x0 + gv[bj][0] * acc[ai][bj][m][0], y1 = x1 + gv[bj][1] * acc[ai][bj][m][1];
;                     h8 o; o[0] = (half_t)y0[0]; o[1] = (half_t)y0[1]; o[2] = (half_t)y0[2]; o[3] = (half_t)y0[3]; o[4] = (half_t)y1[0]; o[5] = (half_t)y1[1]; o[6] = (half_t)y1[2]; o[7] = (half_t)y1[3];
;                     *(h8*)(H + ro + bj * 128) = o; } }
	v_mov_b32_e32 v76, v238
	v_mov_b32_e32 v77, v239
	v_mov_b32_e32 v78, v240
	v_mov_b32_e32 v79, v241
	s_nop 0
	v_cvt_f32_f16_e32 v80, v76
	v_cvt_f32_f16_sdwa v81, v76 dst_sel:DWORD dst_unused:UNUSED_PAD src0_sel:WORD_1
	v_cvt_f32_f16_e32 v76, v77
	v_cvt_f32_f16_sdwa v77, v77 dst_sel:DWORD dst_unused:UNUSED_PAD src0_sel:WORD_1
	v_cvt_f32_f16_e32 v82, v78
	v_cvt_f32_f16_sdwa v83, v78 dst_sel:DWORD dst_unused:UNUSED_PAD src0_sel:WORD_1
	v_cvt_f32_f16_e32 v78, v79
	v_cvt_f32_f16_sdwa v79, v79 dst_sel:DWORD dst_unused:UNUSED_PAD src0_sel:WORD_1
	v_pk_fma_f32 v[74:75], v[74:75], v[34:35], v[76:77]
	v_pk_fma_f32 v[68:69], v[68:69], v[28:29], v[82:83]
	v_pk_fma_f32 v[72:73], v[72:73], v[32:33], v[80:81]
	v_pk_fma_f32 v[70:71], v[70:71], v[30:31], v[78:79]
	s_nop 0
	v_cvt_pk_f16_f32 v71, v70, v71
	v_cvt_pk_f16_f32 v70, v68, v69
	v_cvt_pk_f16_f32 v69, v74, v75
	v_add_co_u32_e32 v74, vcc, s1, v170
	v_cvt_pk_f16_f32 v68, v72, v73
	s_nop 0
	v_addc_co_u32_e32 v75, vcc, 0, v171, vcc
	global_store_dwordx4 v[84:85], v[68:71], off offset:256
	s_nop 1
	s_waitcnt vmcnt(5)
	v_mov_b32_e32 v70, v244
	v_mov_b32_e32 v71, v245
	v_mov_b32_e32 v72, v246
	v_mov_b32_e32 v73, v247
	s_mov_b32 s1, 0xa0000
	v_lshl_add_u64 v[68:69], v[170:171], 0, s[12:13]
	s_mov_b64 s[12:13], 0xa0000
	s_nop 0
	v_cvt_f32_f16_e32 v76, v70
	v_cvt_f32_f16_sdwa v77, v70 dst_sel:DWORD dst_unused:UNUSED_PAD src0_sel:WORD_1
	v_cvt_f32_f16_e32 v70, v71
	v_cvt_f32_f16_sdwa v71, v71 dst_sel:DWORD dst_unused:UNUSED_PAD src0_sel:WORD_1
	v_cvt_f32_f16_e32 v78, v72
	v_cvt_f32_f16_sdwa v79, v72 dst_sel:DWORD dst_unused:UNUSED_PAD src0_sel:WORD_1
	v_cvt_f32_f16_e32 v72, v73
	v_cvt_f32_f16_sdwa v73, v73 dst_sel:DWORD dst_unused:UNUSED_PAD src0_sel:WORD_1
	v_pk_fma_f32 v[58:59], v[58:59], v[66:67], v[70:71]
	v_pk_fma_f32 v[56:57], v[56:57], v[64:65], v[76:77]
	v_pk_fma_f32 v[52:53], v[52:53], v[60:61], v[78:79]
	v_pk_fma_f32 v[54:55], v[54:55], v[62:63], v[72:73]
	s_nop 0
	v_cvt_pk_f16_f32 v55, v54, v55
	v_cvt_pk_f16_f32 v54, v52, v53
	v_cvt_pk_f16_f32 v53, v58, v59
	v_cvt_pk_f16_f32 v52, v56, v57
	global_store_dwordx4 v[74:75], v[52:55], off
	s_nop 1
	s_waitcnt vmcnt(4)
	v_mov_b32_e32 v52, v202
	v_mov_b32_e32 v53, v203
	v_mov_b32_e32 v54, v204
	v_mov_b32_e32 v55, v205
	s_nop 0
	v_cvt_f32_f16_e32 v56, v52
	v_cvt_f32_f16_sdwa v57, v52 dst_sel:DWORD dst_unused:UNUSED_PAD src0_sel:WORD_1
	v_cvt_f32_f16_e32 v52, v53
	v_cvt_f32_f16_sdwa v53, v53 dst_sel:DWORD dst_unused:UNUSED_PAD src0_sel:WORD_1
	v_cvt_f32_f16_e32 v58, v54
	v_cvt_f32_f16_sdwa v59, v54 dst_sel:DWORD dst_unused:UNUSED_PAD src0_sel:WORD_1
	v_cvt_f32_f16_e32 v54, v55
	v_cvt_f32_f16_sdwa v55, v55 dst_sel:DWORD dst_unused:UNUSED_PAD src0_sel:WORD_1
	v_pk_fma_f32 v[50:51], v[50:51], v[34:35], v[52:53]
	v_pk_fma_f32 v[44:45], v[44:45], v[28:29], v[58:59]
	v_pk_fma_f32 v[48:49], v[48:49], v[32:33], v[56:57]
	v_pk_fma_f32 v[46:47], v[46:47], v[30:31], v[54:55]
	s_nop 0
	v_cvt_pk_f16_f32 v47, v46, v47
	v_cvt_pk_f16_f32 v46, v44, v45
	v_cvt_pk_f16_f32 v45, v50, v51
	v_add_co_u32_e32 v50, vcc, s1, v170
	v_cvt_pk_f16_f32 v44, v48, v49
	s_nop 0
	v_addc_co_u32_e32 v51, vcc, 0, v171, vcc
	global_store_dwordx4 v[68:69], v[44:47], off offset:256
	s_nop 1
	s_waitcnt vmcnt(3)
	v_mov_b32_e32 v46, v206
	v_mov_b32_e32 v47, v207
	v_mov_b32_e32 v48, v208
	v_mov_b32_e32 v49, v209
	s_mov_b32 s1, 0xb0000
	v_lshl_add_u64 v[44:45], v[170:171], 0, s[12:13]
	s_mov_b64 s[12:13], 0xb0000
	s_nop 0
	v_cvt_f32_f16_e32 v52, v46
	v_cvt_f32_f16_sdwa v53, v46 dst_sel:DWORD dst_unused:UNUSED_PAD src0_sel:WORD_1
	v_cvt_f32_f16_e32 v46, v47
	v_cvt_f32_f16_sdwa v47, v47 dst_sel:DWORD dst_unused:UNUSED_PAD src0_sel:WORD_1
	v_cvt_f32_f16_e32 v54, v48
	v_cvt_f32_f16_sdwa v55, v48 dst_sel:DWORD dst_unused:UNUSED_PAD src0_sel:WORD_1
	v_cvt_f32_f16_e32 v48, v49
	v_cvt_f32_f16_sdwa v49, v49 dst_sel:DWORD dst_unused:UNUSED_PAD src0_sel:WORD_1
	v_pk_fma_f32 v[42:43], v[42:43], v[66:67], v[46:47]
	v_pk_fma_f32 v[40:41], v[40:41], v[64:65], v[52:53]
	v_pk_fma_f32 v[36:37], v[36:37], v[60:61], v[54:55]
	v_pk_fma_f32 v[38:39], v[38:39], v[62:63], v[48:49]
	s_nop 0
	v_cvt_pk_f16_f32 v39, v38, v39
	v_cvt_pk_f16_f32 v38, v36, v37
	v_cvt_pk_f16_f32 v37, v42, v43
	v_cvt_pk_f16_f32 v36, v40, v41
	global_store_dwordx4 v[50:51], v[36:39], off
	s_nop 1
	s_waitcnt vmcnt(2)
; #define PG8_WAIT_V(n) asm volatile("s_waitcnt vmcnt(" #n ")" ::: "memory")
; #define PG8_BAR __builtin_amdgcn_s_barrier()
; template <class Epi>
; __device__ __forceinline__ void gemm_phase(LAS unsigned char* lds, const Gemm g, const StaticOrder& S, const Epi& E, const int tid) {
;     ...
;         if (!has_next) break;
; #pragma unroll
;         for (int a = 0; a < 2; ++a)
; #pragma unroll
;             for (int b = 0; b < 2; ++b)
; #pragma unroll
;                 for (int m = 0; m < 4; ++m)
; #pragma unroll
;                     for (int n = 0; n < 2; ++n) acc[a][b][m][n] = (f32x4){0.f, 0.f, 0.f, 0.f};
;         cur = nxt; cA = nA; cB = nB; ++ui;
;     }
;     PG8_WAIT_V(0);
;     if (wr == 0) PG8_BAR;
;     PG8_BAR;
;     __device__ __forceinline__ void operator()(const f32x4 (&acc)[2][2][4][2], const pg8::Unit& u, int wr, int wc, int fr, int fq) const {
;     ...
;         for (int ai = 0; ai < 2; ++ai)
; #pragma unroll
;             for (int m = 0; m < 4; ++m) { const size_t ro = (size_t)(row0 + ai * 128 + m * 16) * DM + col0;
; #pragma unroll
;                 for (int bj = 0; bj < 2; ++bj) {
;                     f32x4 x0, x1;
;                     if (XF32) { x0 = *(const f32x4*)(xin + ro + bj * 128); x1 = *(const f32x4*)(xin + ro + bj * 128 + 4); }
;                     else { const h8 xh = *(const h8*)(H + ro + bj * 128); x0 = (f32x4){(float)xh[0], (float)xh[1], (float)xh[2], (float)xh[3]}; x1 = (f32x4){(float)xh[4], (float)xh[5], (float)xh[6], (float)xh[7]}; }
;                     const f32x4 y0 = x0 + gv[bj][0] * acc[ai][bj][m][0], y1 = x1 + gv[bj][1] * acc[ai][bj][m][1];
;                     h8 o; o[0] = (half_t)y0[0]; o[1] = (half_t)y0[1]; o[2] = (half_t)y0[2]; o[3] = (half_t)y0[3]; o[4] = (half_t)y1[0]; o[5] = (half_t)y1[1]; o[6] = (half_t)y1[2]; o[7] = (half_t)y1[3];
;                     *(h8*)(H + ro + bj * 128) = o; } }
	v_mov_b32_e32 v36, v210
	v_mov_b32_e32 v37, v211
	v_mov_b32_e32 v38, v212
	v_mov_b32_e32 v39, v213
	s_nop 0
	v_cvt_f32_f16_e32 v40, v36
	v_cvt_f32_f16_sdwa v41, v36 dst_sel:DWORD dst_unused:UNUSED_PAD src0_sel:WORD_1
	v_cvt_f32_f16_e32 v36, v37
	v_cvt_f32_f16_sdwa v37, v37 dst_sel:DWORD dst_unused:UNUSED_PAD src0_sel:WORD_1
	v_cvt_f32_f16_e32 v42, v38
	v_cvt_f32_f16_sdwa v43, v38 dst_sel:DWORD dst_unused:UNUSED_PAD src0_sel:WORD_1
	v_cvt_f32_f16_e32 v38, v39
	v_cvt_f32_f16_sdwa v39, v39 dst_sel:DWORD dst_unused:UNUSED_PAD src0_sel:WORD_1
	v_pk_fma_f32 v[26:27], v[26:27], v[34:35], v[36:37]
	v_pk_fma_f32 v[20:21], v[20:21], v[28:29], v[42:43]
	v_pk_fma_f32 v[24:25], v[24:25], v[32:33], v[40:41]
	v_pk_fma_f32 v[22:23], v[22:23], v[30:31], v[38:39]
	s_nop 0
	v_cvt_pk_f16_f32 v23, v22, v23
	v_cvt_pk_f16_f32 v22, v20, v21
	v_cvt_pk_f16_f32 v21, v26, v27
	v_add_co_u32_e32 v26, vcc, s1, v170
	v_cvt_pk_f16_f32 v20, v24, v25
	s_nop 0
	v_addc_co_u32_e32 v27, vcc, 0, v171, vcc
	global_store_dwordx4 v[44:45], v[20:23], off offset:256
	s_nop 1
	s_waitcnt vmcnt(1)
	v_mov_b32_e32 v22, v214
	v_mov_b32_e32 v23, v215
	v_mov_b32_e32 v24, v216
	v_mov_b32_e32 v25, v217
	s_and_b64 vcc, exec, s[4:5]
	v_lshl_add_u64 v[20:21], v[170:171], 0, s[12:13]
	s_mov_b64 s[12:13], s[8:9]
	s_nop 0
	v_cvt_f32_f16_e32 v36, v22
	v_cvt_f32_f16_sdwa v37, v22 dst_sel:DWORD dst_unused:UNUSED_PAD src0_sel:WORD_1
	v_cvt_f32_f16_e32 v22, v23
	v_cvt_f32_f16_sdwa v23, v23 dst_sel:DWORD dst_unused:UNUSED_PAD src0_sel:WORD_1
	v_cvt_f32_f16_e32 v38, v24
	v_cvt_f32_f16_sdwa v39, v24 dst_sel:DWORD dst_unused:UNUSED_PAD src0_sel:WORD_1
	v_cvt_f32_f16_e32 v24, v25
	v_cvt_f32_f16_sdwa v25, v25 dst_sel:DWORD dst_unused:UNUSED_PAD src0_sel:WORD_1
	v_pk_fma_f32 v[18:19], v[18:19], v[66:67], v[22:23]
	v_pk_fma_f32 v[16:17], v[16:17], v[64:65], v[36:37]
	v_pk_fma_f32 v[12:13], v[12:13], v[60:61], v[38:39]
	v_pk_fma_f32 v[14:15], v[14:15], v[62:63], v[24:25]
	s_nop 0
	v_cvt_pk_f16_f32 v15, v14, v15
	v_cvt_pk_f16_f32 v14, v12, v13
	v_cvt_pk_f16_f32 v13, v18, v19
	v_cvt_pk_f16_f32 v12, v16, v17
	global_store_dwordx4 v[26:27], v[12:15], off
	s_nop 1
	s_waitcnt vmcnt(0)
	v_mov_b32_e32 v12, v218
	v_mov_b32_e32 v13, v219
	v_mov_b32_e32 v14, v220
	v_mov_b32_e32 v15, v221
	s_nop 0
	v_cvt_f32_f16_e32 v16, v12
	v_cvt_f32_f16_sdwa v17, v12 dst_sel:DWORD dst_unused:UNUSED_PAD src0_sel:WORD_1
	v_cvt_f32_f16_e32 v12, v13
	v_cvt_f32_f16_sdwa v13, v13 dst_sel:DWORD dst_unused:UNUSED_PAD src0_sel:WORD_1
	v_cvt_f32_f16_e32 v18, v14
	v_cvt_f32_f16_sdwa v19, v14 dst_sel:DWORD dst_unused:UNUSED_PAD src0_sel:WORD_1
	v_cvt_f32_f16_e32 v14, v15
	v_cvt_f32_f16_sdwa v15, v15 dst_sel:DWORD dst_unused:UNUSED_PAD src0_sel:WORD_1
	v_pk_fma_f32 v[10:11], v[10:11], v[34:35], v[12:13]
	v_pk_fma_f32 v[8:9], v[8:9], v[32:33], v[16:17]
	v_pk_fma_f32 v[4:5], v[4:5], v[28:29], v[18:19]
	v_pk_fma_f32 v[6:7], v[6:7], v[30:31], v[14:15]
	s_nop 0
	v_cvt_pk_f16_f32 v7, v6, v7
	v_cvt_pk_f16_f32 v6, v4, v5
	v_cvt_pk_f16_f32 v5, v10, v11
	v_cvt_pk_f16_f32 v4, v8, v9
	global_store_dwordx4 v[20:21], v[4:7], off offset:256
	s_cbranch_vccz .LBB0_653
	s_waitcnt vmcnt(0)
	v_readlane_b32 s48, v251, 13
	s_cmpk_gt_u32 s25, 0xff
	v_readlane_b32 s49, v251, 14
	s_cbranch_scc1 .LBB0_664
	s_barrier

; #define PG8_STAGE(bufoff, gbase, voff) do { _Pragma("unroll") for (int _i = 0; _i < 2; ++_i) \
;         __builtin_amdgcn_global_load_lds((const unsigned*)((const char*)(gbase) + (voff)[_i]), (LAS unsigned*)(lds + (bufoff) + ldsw + _i * 8192), 16, 0, 0); } while (0)
; #define PG8_LDA(dst, b, h) do { _Pragma("unroll") for (int m = 0; m < 4; ++m) _Pragma("unroll") for (int k = 0; k < 2; ++k) dst[m][k] = *(const LAS h8*)(lds + PG8_SA(b, h) + aoff + m * 2048 + k * 1024); } while (0)
; #define PG8_LDB(dst, b, h) do { _Pragma("unroll") for (int n = 0; n < 2; ++n) _Pragma("unroll") for (int k = 0; k < 2; ++k) dst[n][k] = *(const LAS h8*)(lds + PG8_SB(b, h) + boff + n * 2048 + k * 1024); } while (0)
; #define PG8_WAIT_L(n) asm volatile("s_waitcnt lgkmcnt(" #n ")" ::: "memory")
; #define PG8_BAR __builtin_amdgcn_s_barrier()
; #define PG8_SCHED __builtin_amdgcn_sched_barrier(0)
; template <class Epi>
; __device__ __forceinline__ void gemm_phase(LAS unsigned char* lds, const Gemm g, const StaticOrder& S, const Epi& E, const int tid) {
;     ...
;         for (int t = 0; t < nt; t += 2) {
;             const bool last = (t == nt - 2);
;             const char* a1 = cA + (size_t)(t + 1) * kstep;
;             const char* a2 = last ? nA : cA + (size_t)(t + 2) * kstep; const char* b2 = last ? nB : cB + (size_t)(t + 2) * kstep;
;             const char* a3 = a2 + kstep; const char* b3 = b2 + kstep;
;             if constexpr (Epi::HAS_MID) { if (t == (nt >> 1)) E.mid(acc, cur, wr, wc, fr, fq); }
;             PG8_LDB(B0, 0, 0); PG8_SCHED; PG8_LDA(At, 0, 0); PG8_STAGE(PG8_SA(1, 1), a1 + hstep, voffA);
;             PG8_WAIT_L(8); PG8_BAR; PG8_WAIT_L(0); PG8_MMA(0, 0, At, B0); PG8_BAR; PG8_SCHED;
;             PG8_LDB(B1, 0, 1); PG8_STAGE(PG8_SB(0, 0), b2, voffB);
;             PG8_BAR; PG8_WAIT_L(0); PG8_MMA(0, 1, At, B1); PG8_BAR;
.LBB0_678:
	s_add_u32 s14, s12, 0xfff80080
	s_addc_u32 s15, s13, -1
	s_add_i32 s55, 0, 0x10000
	v_add_u32_e32 v88, s55, v176
	ds_read_b128 v[68:71], v88
	ds_read_b128 v[72:75], v88 offset:1024
	ds_read_b128 v[84:87], v88 offset:2048
	ds_read_b128 v[88:91], v88 offset:3072
	s_cmp_eq_u32 s54, 28
	s_cselect_b32 s19, s7, s15
	s_cselect_b32 s18, s50, s14
	s_cselect_b32 s15, s1, s53
	s_cselect_b32 s14, s51, s52
	v_lshl_add_u64 v[174:175], s[12:13], 0, v[166:167]
	s_add_i32 m0, s39, 0xc000
	ds_read_b128 v[170:173], v177
	ds_read_b128 v[190:193], v177 offset:1024
	ds_read_b128 v[194:197], v177 offset:2048
	ds_read_b128 v[198:201], v177 offset:3072
	ds_read_b128 v[202:205], v177 offset:4096
	ds_read_b128 v[206:209], v177 offset:5120
	ds_read_b128 v[210:213], v177 offset:6144
	ds_read_b128 v[214:217], v177 offset:7168
	global_load_lds_dwordx4 v[174:175], off
	v_lshl_add_u64 v[174:175], s[12:13], 0, v[168:169]
	s_add_i32 m0, s39, 0xe000
	s_nop 0
	global_load_lds_dwordx4 v[174:175], off
	s_waitcnt lgkmcnt(8)
	s_barrier
	s_waitcnt lgkmcnt(0)
	s_waitcnt lgkmcnt(0)
	v_mfma_f32_16x16x32_bf16 v[144:147], v[68:71], v[170:173], v[144:147]
	v_mfma_f32_16x16x32_bf16 v[140:143], v[84:87], v[170:173], v[140:143]
	v_mfma_f32_16x16x32_bf16 v[128:131], v[68:71], v[194:197], v[128:131]
	v_mfma_f32_16x16x32_bf16 v[124:127], v[84:87], v[194:197], v[124:127]
	v_mfma_f32_16x16x32_bf16 v[112:115], v[68:71], v[202:205], v[112:115]
	v_mfma_f32_16x16x32_bf16 v[108:111], v[84:87], v[202:205], v[108:111]
	v_mfma_f32_16x16x32_bf16 v[96:99], v[68:71], v[210:213], v[96:99]
	v_mfma_f32_16x16x32_bf16 v[92:95], v[84:87], v[210:213], v[92:95]
	v_mfma_f32_16x16x32_bf16 v[144:147], v[72:75], v[190:193], v[144:147]
	v_mfma_f32_16x16x32_bf16 v[140:143], v[88:91], v[190:193], v[140:143]
	v_mfma_f32_16x16x32_bf16 v[128:131], v[72:75], v[198:201], v[128:131]
	v_mfma_f32_16x16x32_bf16 v[124:127], v[88:91], v[198:201], v[124:127]
	v_mfma_f32_16x16x32_bf16 v[112:115], v[72:75], v[206:209], v[112:115]
	v_mfma_f32_16x16x32_bf16 v[108:111], v[88:91], v[206:209], v[108:111]
	v_mfma_f32_16x16x32_bf16 v[96:99], v[72:75], v[214:217], v[96:99]
	v_mfma_f32_16x16x32_bf16 v[92:95], v[88:91], v[214:217], v[92:95]
	s_barrier
	s_add_i32 s58, 0, 0x14000
	v_add_u32_e32 v174, s58, v176
	s_add_i32 s55, s55, s38
	ds_read_b128 v[218:221], v174
	ds_read_b128 v[222:225], v174 offset:1024
	ds_read_b128 v[226:229], v174 offset:2048
	ds_read_b128 v[230:233], v174 offset:3072
	v_lshl_add_u64 v[174:175], s[14:15], 0, v[2:3]
	s_mov_b32 m0, s55
	v_lshl_add_u64 v[234:235], s[14:15], 0, v[0:1]
	global_load_lds_dwordx4 v[174:175], off
	s_add_i32 m0, s55, 0x2000
	s_nop 0
	global_load_lds_dwordx4 v[234:235], off
	s_barrier
	s_waitcnt lgkmcnt(0)
	s_waitcnt lgkmcnt(0)
	v_mfma_f32_16x16x32_bf16 v[136:139], v[218:221], v[170:173], v[136:139]
	v_mfma_f32_16x16x32_bf16 v[132:135], v[226:229], v[170:173], v[132:135]
	v_mfma_f32_16x16x32_bf16 v[120:123], v[218:221], v[194:197], v[120:123]
	v_mfma_f32_16x16x32_bf16 v[116:119], v[226:229], v[194:197], v[116:119]
	v_mfma_f32_16x16x32_bf16 v[104:107], v[218:221], v[202:205], v[104:107]
	v_mfma_f32_16x16x32_bf16 v[100:103], v[226:229], v[202:205], v[100:103]
	v_mfma_f32_16x16x32_bf16 v[80:83], v[218:221], v[210:213], v[80:83]
	v_mfma_f32_16x16x32_bf16 v[76:79], v[226:229], v[210:213], v[76:79]
	v_mfma_f32_16x16x32_bf16 v[136:139], v[222:225], v[190:193], v[136:139]
	v_mfma_f32_16x16x32_bf16 v[132:135], v[230:233], v[190:193], v[132:135]
	v_mfma_f32_16x16x32_bf16 v[120:123], v[222:225], v[198:201], v[120:123]
	v_mfma_f32_16x16x32_bf16 v[116:119], v[230:233], v[198:201], v[116:119]
	v_mfma_f32_16x16x32_bf16 v[104:107], v[222:225], v[206:209], v[104:107]
	v_mfma_f32_16x16x32_bf16 v[100:103], v[230:233], v[206:209], v[100:103]
	v_mfma_f32_16x16x32_bf16 v[80:83], v[222:225], v[214:217], v[80:83]
	v_mfma_f32_16x16x32_bf16 v[76:79], v[230:233], v[214:217], v[76:79]
	s_mov_b32 m0, s39
	v_lshl_add_u64 v[236:237], s[18:19], 0, v[164:165]
	s_barrier
	ds_read_b128 v[170:173], v177 offset:16384
	ds_read_b128 v[190:193], v177 offset:17408
	ds_read_b128 v[194:197], v177 offset:18432
	ds_read_b128 v[198:201], v177 offset:19456
	ds_read_b128 v[202:205], v177 offset:20480
	ds_read_b128 v[206:209], v177 offset:21504
	ds_read_b128 v[210:213], v177 offset:22528
	ds_read_b128 v[214:217], v177 offset:23552
	global_load_lds_dwordx4 v[236:237], off
	v_lshl_add_u64 v[238:239], s[18:19], 0, v[162:163]
	s_mov_b32 m0, s40
	s_nop 0
	global_load_lds_dwordx4 v[238:239], off
	s_barrier
	s_waitcnt lgkmcnt(0)
	s_waitcnt lgkmcnt(0)
	v_mfma_f32_16x16x32_bf16 v[64:67], v[68:71], v[170:173], v[64:67]
	v_mfma_f32_16x16x32_bf16 v[60:63], v[84:87], v[170:173], v[60:63]
	v_mfma_f32_16x16x32_bf16 v[48:51], v[68:71], v[194:197], v[48:51]
	v_mfma_f32_16x16x32_bf16 v[44:47], v[84:87], v[194:197], v[44:47]
	v_mfma_f32_16x16x32_bf16 v[32:35], v[68:71], v[202:205], v[32:35]
	v_mfma_f32_16x16x32_bf16 v[28:31], v[84:87], v[202:205], v[28:31]
	v_mfma_f32_16x16x32_bf16 v[16:19], v[68:71], v[210:213], v[16:19]
	v_mfma_f32_16x16x32_bf16 v[12:15], v[84:87], v[210:213], v[12:15]
	v_mfma_f32_16x16x32_bf16 v[64:67], v[72:75], v[190:193], v[64:67]
	v_mfma_f32_16x16x32_bf16 v[60:63], v[88:91], v[190:193], v[60:63]
	v_mfma_f32_16x16x32_bf16 v[48:51], v[72:75], v[198:201], v[48:51]
	v_mfma_f32_16x16x32_bf16 v[44:47], v[88:91], v[198:201], v[44:47]
	v_mfma_f32_16x16x32_bf16 v[32:35], v[72:75], v[206:209], v[32:35]
	v_mfma_f32_16x16x32_bf16 v[28:31], v[88:91], v[206:209], v[28:31]
	v_mfma_f32_16x16x32_bf16 v[16:19], v[72:75], v[214:217], v[16:19]
	v_mfma_f32_16x16x32_bf16 v[12:15], v[88:91], v[214:217], v[12:15]
	s_barrier
; #define PG8_STAGE(bufoff, gbase, voff) do { _Pragma("unroll") for (int _i = 0; _i < 2; ++_i) \
;         __builtin_amdgcn_global_load_lds((const unsigned*)((const char*)(gbase) + (voff)[_i]), (LAS unsigned*)(lds + (bufoff) + ldsw + _i * 8192), 16, 0, 0); } while (0)
; #define PG8_LDA(dst, b, h) do { _Pragma("unroll") for (int m = 0; m < 4; ++m) _Pragma("unroll") for (int k = 0; k < 2; ++k) dst[m][k] = *(const LAS h8*)(lds + PG8_SA(b, h) + aoff + m * 2048 + k * 1024); } while (0)
; #define PG8_LDB(dst, b, h) do { _Pragma("unroll") for (int n = 0; n < 2; ++n) _Pragma("unroll") for (int k = 0; k < 2; ++k) dst[n][k] = *(const LAS h8*)(lds + PG8_SB(b, h) + boff + n * 2048 + k * 1024); } while (0)
; #define PG8_WAIT_V(n) asm volatile("s_waitcnt vmcnt(" #n ")" ::: "memory")
; #define PG8_WAIT_L(n) asm volatile("s_waitcnt lgkmcnt(" #n ")" ::: "memory")
; #define PG8_BAR __builtin_amdgcn_s_barrier()
; #define PG8_SCHED __builtin_amdgcn_sched_barrier(0)
; template <class Epi>
; __device__ __forceinline__ void gemm_phase(LAS unsigned char* lds, const Gemm g, const StaticOrder& S, const Epi& E, const int tid) {
;     ...
;             PG8_STAGE(PG8_SB(0, 1), b2 + hstepB, voffB);
;             PG8_WAIT_V(6); PG8_BAR; PG8_MMA(1, 1, At, B1); PG8_BAR;
;             PG8_LDB(B0, 1, 0); PG8_SCHED; PG8_LDA(At, 1, 0); PG8_STAGE(PG8_SA(0, 1), a2 + hstep, voffA);
;             PG8_WAIT_L(8); PG8_BAR; PG8_WAIT_L(0); PG8_MMA(0, 0, At, B0); PG8_BAR; PG8_SCHED;
;             PG8_LDB(B1, 1, 1); PG8_STAGE(PG8_SB(1, 0), b3, voffB);
;             PG8_BAR; PG8_WAIT_L(0); PG8_MMA(0, 1, At, B1); PG8_BAR;
;             PG8_LDA(At, 1, 1); PG8_STAGE(PG8_SA(1, 0), a3, voffA);
;             PG8_BAR; PG8_WAIT_L(0); PG8_MMA(1, 0, At, B0); PG8_BAR; PG8_SCHED;
;             PG8_STAGE(PG8_SB(1, 1), b3 + hstepB, voffB);
	s_add_u32 s56, s14, 0x80000
	s_addc_u32 s57, s15, 0
	s_add_i32 s55, s58, s38
	v_lshl_add_u64 v[68:69], s[56:57], 0, v[2:3]
	s_mov_b32 m0, s55
	s_nop 0
	global_load_lds_dwordx4 v[68:69], off
	v_lshl_add_u64 v[68:69], s[56:57], 0, v[0:1]
	s_add_i32 m0, s55, 0x2000
	s_nop 0
	global_load_lds_dwordx4 v[68:69], off
	s_waitcnt vmcnt(6)
	s_barrier
	v_mfma_f32_16x16x32_bf16 v[56:59], v[218:221], v[170:173], v[56:59]
	v_mfma_f32_16x16x32_bf16 v[52:55], v[226:229], v[170:173], v[52:55]
	v_mfma_f32_16x16x32_bf16 v[40:43], v[218:221], v[194:197], v[40:43]
	v_mfma_f32_16x16x32_bf16 v[36:39], v[226:229], v[194:197], v[36:39]
	v_mfma_f32_16x16x32_bf16 v[24:27], v[218:221], v[202:205], v[24:27]
	v_mfma_f32_16x16x32_bf16 v[20:23], v[226:229], v[202:205], v[20:23]
	v_mfma_f32_16x16x32_bf16 v[8:11], v[218:221], v[210:213], v[8:11]
	v_mfma_f32_16x16x32_bf16 v[4:7], v[226:229], v[210:213], v[4:7]
	v_mfma_f32_16x16x32_bf16 v[56:59], v[222:225], v[190:193], v[56:59]
	v_mfma_f32_16x16x32_bf16 v[52:55], v[230:233], v[190:193], v[52:55]
	v_mfma_f32_16x16x32_bf16 v[40:43], v[222:225], v[198:201], v[40:43]
	v_mfma_f32_16x16x32_bf16 v[36:39], v[230:233], v[198:201], v[36:39]
	v_mfma_f32_16x16x32_bf16 v[24:27], v[222:225], v[206:209], v[24:27]
	v_mfma_f32_16x16x32_bf16 v[20:23], v[230:233], v[206:209], v[20:23]
	v_mfma_f32_16x16x32_bf16 v[8:11], v[222:225], v[214:217], v[8:11]
	v_mfma_f32_16x16x32_bf16 v[4:7], v[230:233], v[214:217], v[4:7]
	s_add_i32 s55, 0, 0x18000
	v_add_u32_e32 v88, s55, v176
	s_barrier
	ds_read_b128 v[68:71], v88
	ds_read_b128 v[72:75], v88 offset:1024
	ds_read_b128 v[84:87], v88 offset:2048
	ds_read_b128 v[88:91], v88 offset:3072
	s_add_u32 s18, s18, 0x80000
	s_addc_u32 s19, s19, 0
	s_mov_b32 m0, s41
	v_lshl_add_u64 v[218:219], s[18:19], 0, v[164:165]
	ds_read_b128 v[170:173], v177 offset:32768
	ds_read_b128 v[190:193], v177 offset:33792
	ds_read_b128 v[194:197], v177 offset:34816
	ds_read_b128 v[198:201], v177 offset:35840
	ds_read_b128 v[202:205], v177 offset:36864
	ds_read_b128 v[206:209], v177 offset:37888
	ds_read_b128 v[210:213], v177 offset:38912
	ds_read_b128 v[214:217], v177 offset:39936
	global_load_lds_dwordx4 v[218:219], off
	v_lshl_add_u64 v[218:219], s[18:19], 0, v[162:163]
	s_mov_b32 m0, s42
	s_nop 0
	global_load_lds_dwordx4 v[218:219], off
	s_waitcnt lgkmcnt(8)
	s_barrier
	s_waitcnt lgkmcnt(0)
	s_waitcnt lgkmcnt(0)
	v_mfma_f32_16x16x32_bf16 v[144:147], v[68:71], v[170:173], v[144:147]
	v_mfma_f32_16x16x32_bf16 v[140:143], v[84:87], v[170:173], v[140:143]
	v_mfma_f32_16x16x32_bf16 v[128:131], v[68:71], v[194:197], v[128:131]
	v_mfma_f32_16x16x32_bf16 v[124:127], v[84:87], v[194:197], v[124:127]
	v_mfma_f32_16x16x32_bf16 v[112:115], v[68:71], v[202:205], v[112:115]
	v_mfma_f32_16x16x32_bf16 v[108:111], v[84:87], v[202:205], v[108:111]
	v_mfma_f32_16x16x32_bf16 v[96:99], v[68:71], v[210:213], v[96:99]
	v_mfma_f32_16x16x32_bf16 v[92:95], v[84:87], v[210:213], v[92:95]
	v_mfma_f32_16x16x32_bf16 v[144:147], v[72:75], v[190:193], v[144:147]
	v_mfma_f32_16x16x32_bf16 v[140:143], v[88:91], v[190:193], v[140:143]
	v_mfma_f32_16x16x32_bf16 v[128:131], v[72:75], v[198:201], v[128:131]
	v_mfma_f32_16x16x32_bf16 v[124:127], v[88:91], v[198:201], v[124:127]
	v_mfma_f32_16x16x32_bf16 v[112:115], v[72:75], v[206:209], v[112:115]
	v_mfma_f32_16x16x32_bf16 v[108:111], v[88:91], v[206:209], v[108:111]
	v_mfma_f32_16x16x32_bf16 v[96:99], v[72:75], v[214:217], v[96:99]
	v_mfma_f32_16x16x32_bf16 v[92:95], v[88:91], v[214:217], v[92:95]
	s_barrier
	s_add_i32 s18, 0, 0x1c000
	s_add_i32 s19, s55, s38
	v_add_u32_e32 v178, s18, v176
	v_lshl_add_u64 v[174:175], v[174:175], 0, s[30:31]
	s_mov_b32 m0, s19
	ds_read_b128 v[218:221], v178
	ds_read_b128 v[222:225], v178 offset:1024
	ds_read_b128 v[226:229], v178 offset:2048
	ds_read_b128 v[230:233], v178 offset:3072
	global_load_lds_dwordx4 v[174:175], off
	v_lshl_add_u64 v[174:175], v[234:235], 0, s[30:31]
	s_add_i32 m0, s19, 0x2000
	s_nop 0
	global_load_lds_dwordx4 v[174:175], off
	s_barrier
	s_waitcnt lgkmcnt(0)
	s_waitcnt lgkmcnt(0)
	v_mfma_f32_16x16x32_bf16 v[136:139], v[218:221], v[170:173], v[136:139]
	v_mfma_f32_16x16x32_bf16 v[132:135], v[226:229], v[170:173], v[132:135]
	v_mfma_f32_16x16x32_bf16 v[120:123], v[218:221], v[194:197], v[120:123]
	v_mfma_f32_16x16x32_bf16 v[116:119], v[226:229], v[194:197], v[116:119]
	v_mfma_f32_16x16x32_bf16 v[104:107], v[218:221], v[202:205], v[104:107]
	v_mfma_f32_16x16x32_bf16 v[100:103], v[226:229], v[202:205], v[100:103]
	v_mfma_f32_16x16x32_bf16 v[80:83], v[218:221], v[210:213], v[80:83]
	v_mfma_f32_16x16x32_bf16 v[76:79], v[226:229], v[210:213], v[76:79]
	v_mfma_f32_16x16x32_bf16 v[136:139], v[222:225], v[190:193], v[136:139]
	v_mfma_f32_16x16x32_bf16 v[132:135], v[230:233], v[190:193], v[132:135]
	v_mfma_f32_16x16x32_bf16 v[120:123], v[222:225], v[198:201], v[120:123]
	v_mfma_f32_16x16x32_bf16 v[116:119], v[230:233], v[198:201], v[116:119]
	v_mfma_f32_16x16x32_bf16 v[104:107], v[222:225], v[206:209], v[104:107]
	v_mfma_f32_16x16x32_bf16 v[100:103], v[230:233], v[206:209], v[100:103]
	v_mfma_f32_16x16x32_bf16 v[80:83], v[222:225], v[214:217], v[80:83]
	v_mfma_f32_16x16x32_bf16 v[76:79], v[230:233], v[214:217], v[76:79]
	s_mov_b32 m0, s43
	v_lshl_add_u64 v[174:175], v[236:237], 0, s[30:31]
	s_barrier
	ds_read_b128 v[170:173], v177 offset:49152
	ds_read_b128 v[190:193], v177 offset:50176
	ds_read_b128 v[194:197], v177 offset:51200
	ds_read_b128 v[198:201], v177 offset:52224
	ds_read_b128 v[202:205], v177 offset:53248
	ds_read_b128 v[206:209], v177 offset:54272
	ds_read_b128 v[210:213], v177 offset:55296
	ds_read_b128 v[214:217], v177 offset:56320
	global_load_lds_dwordx4 v[174:175], off
	v_lshl_add_u64 v[174:175], v[238:239], 0, s[30:31]
	s_mov_b32 m0, s46
	s_nop 0
	global_load_lds_dwordx4 v[174:175], off
	s_barrier
; #define PG8_STAGE(bufoff, gbase, voff) do { _Pragma("unroll") for (int _i = 0; _i < 2; ++_i) \
;         __builtin_amdgcn_global_load_lds((const unsigned*)((const char*)(gbase) + (voff)[_i]), (LAS unsigned*)(lds + (bufoff) + ldsw + _i * 8192), 16, 0, 0); } while (0)
; #define PG8_WAIT_V(n) asm volatile("s_waitcnt vmcnt(" #n ")" ::: "memory")
; template <class Epi>
; __device__ __forceinline__ void gemm_phase(LAS unsigned char* lds, const Gemm g, const StaticOrder& S, const Epi& E, const int tid) {
;     ...
;             PG8_BAR; PG8_WAIT_L(0); PG8_MMA(0, 1, At, B1); PG8_BAR;
;             PG8_LDA(At, 1, 1); PG8_STAGE(PG8_SA(1, 0), a3, voffA);
;             PG8_BAR; PG8_WAIT_L(0); PG8_MMA(1, 0, At, B0); PG8_BAR; PG8_SCHED;
;             PG8_STAGE(PG8_SB(1, 1), b3 + hstepB, voffB);
;             PG8_WAIT_V(6); PG8_BAR; PG8_MMA(1, 1, At, B1); PG8_BAR;
;     __device__ __forceinline__ void operator()(const f32x4 (&acc)[2][2][4][2], const pg8::Unit& u, int wr, int wc, int fr, int fq) const {
;         const int row0 = u.pm * 256 + wr * 64 + fr, col0 = u.pn * 256 + wc * 32 + 8 * fq;
;         const float* gp = gate + (size_t)((u.pm * 256) >> 12) * 6144 + col0;
;         f32x4 gv[2][2];
; #pragma unroll
;         for (int bj = 0; bj < 2; ++bj)
; #pragma unroll
;             for (int n = 0; n < 2; ++n) gv[bj][n] = *(const f32x4*)(gp + bj * 128 + 4 * n);
; #pragma unroll
;         for (int ai = 0; ai < 2; ++ai)
; #pragma unroll
;             for (int m = 0; m < 4; ++m) { const size_t ro = (size_t)(row0 + ai * 128 + m * 16) * DM + col0;
; #pragma unroll
;                 for (int bj = 0; bj < 2; ++bj) {
;                     f32x4 x0, x1;
;                     if (XF32) { x0 = *(const f32x4*)(xin + ro + bj * 128); x1 = *(const f32x4*)(xin + ro + bj * 128 + 4); }
;                     else { const h8 xh = *(const h8*)(H + ro + bj * 128); x0 = (f32x4){(float)xh[0], (float)xh[1], (float)xh[2], (float)xh[3]}; x1 = (f32x4){(float)xh[4], (float)xh[5], (float)xh[6], (float)xh[7]}; }
;                     const f32x4 y0 = x0 + gv[bj][0] * acc[ai][bj][m][0], y1 = x1 + gv[bj][1] * acc[ai][bj][m][1];
;                     h8 o; o[0] = (half_t)y0[0]; o[1] = (half_t)y0[1]; o[2] = (half_t)y0[2]; o[3] = (half_t)y0[3]; o[4] = (half_t)y1[0]; o[5] = (half_t)y1[1]; o[6] = (half_t)y1[2]; o[7] = (half_t)y1[3];
;                     *(h8*)(H + ro + bj * 128) = o; } }
	s_waitcnt lgkmcnt(0)
	s_waitcnt lgkmcnt(0)
	v_mfma_f32_16x16x32_bf16 v[64:67], v[68:71], v[170:173], v[64:67]
	v_mfma_f32_16x16x32_bf16 v[60:63], v[84:87], v[170:173], v[60:63]
	v_mfma_f32_16x16x32_bf16 v[48:51], v[68:71], v[194:197], v[48:51]
	v_mfma_f32_16x16x32_bf16 v[44:47], v[84:87], v[194:197], v[44:47]
	v_mfma_f32_16x16x32_bf16 v[32:35], v[68:71], v[202:205], v[32:35]
	v_mfma_f32_16x16x32_bf16 v[28:31], v[84:87], v[202:205], v[28:31]
	v_mfma_f32_16x16x32_bf16 v[16:19], v[68:71], v[210:213], v[16:19]
	v_mfma_f32_16x16x32_bf16 v[12:15], v[84:87], v[210:213], v[12:15]
	v_mfma_f32_16x16x32_bf16 v[64:67], v[72:75], v[190:193], v[64:67]
	v_mfma_f32_16x16x32_bf16 v[60:63], v[88:91], v[190:193], v[60:63]
	v_mfma_f32_16x16x32_bf16 v[48:51], v[72:75], v[198:201], v[48:51]
	v_mfma_f32_16x16x32_bf16 v[44:47], v[88:91], v[198:201], v[44:47]
	v_mfma_f32_16x16x32_bf16 v[32:35], v[72:75], v[206:209], v[32:35]
	v_mfma_f32_16x16x32_bf16 v[28:31], v[88:91], v[206:209], v[28:31]
	v_mfma_f32_16x16x32_bf16 v[16:19], v[72:75], v[214:217], v[16:19]
	v_mfma_f32_16x16x32_bf16 v[12:15], v[88:91], v[214:217], v[12:15]
	s_barrier
	s_add_u32 s14, s14, 0x80080
	s_addc_u32 s15, s15, 0
	s_add_i32 s18, s18, s38
	v_lshl_add_u64 v[68:69], s[14:15], 0, v[2:3]
	s_mov_b32 m0, s18
	s_nop 0
	global_load_lds_dwordx4 v[68:69], off
	v_lshl_add_u64 v[68:69], s[14:15], 0, v[0:1]
	s_add_i32 m0, s18, 0x2000
	s_nop 0
	global_load_lds_dwordx4 v[68:69], off
	s_waitcnt vmcnt(6)
	s_barrier
	v_mfma_f32_16x16x32_bf16 v[56:59], v[218:221], v[170:173], v[56:59]
	v_mfma_f32_16x16x32_bf16 v[52:55], v[226:229], v[170:173], v[52:55]
	v_mfma_f32_16x16x32_bf16 v[40:43], v[218:221], v[194:197], v[40:43]
	v_mfma_f32_16x16x32_bf16 v[36:39], v[226:229], v[194:197], v[36:39]
	v_mfma_f32_16x16x32_bf16 v[24:27], v[218:221], v[202:205], v[24:27]
	v_mfma_f32_16x16x32_bf16 v[20:23], v[226:229], v[202:205], v[20:23]
	v_mfma_f32_16x16x32_bf16 v[8:11], v[218:221], v[210:213], v[8:11]
	v_mfma_f32_16x16x32_bf16 v[4:7], v[226:229], v[210:213], v[4:7]
	v_mfma_f32_16x16x32_bf16 v[56:59], v[222:225], v[190:193], v[56:59]
	v_mfma_f32_16x16x32_bf16 v[52:55], v[230:233], v[190:193], v[52:55]
	v_mfma_f32_16x16x32_bf16 v[40:43], v[222:225], v[198:201], v[40:43]
	v_mfma_f32_16x16x32_bf16 v[36:39], v[230:233], v[198:201], v[36:39]
	v_mfma_f32_16x16x32_bf16 v[24:27], v[222:225], v[206:209], v[24:27]
	v_mfma_f32_16x16x32_bf16 v[20:23], v[230:233], v[206:209], v[20:23]
	v_mfma_f32_16x16x32_bf16 v[8:11], v[222:225], v[214:217], v[8:11]
	v_mfma_f32_16x16x32_bf16 v[4:7], v[230:233], v[214:217], v[4:7]
	s_add_i32 s54, s54, 2
	s_add_u32 s12, s12, 0x100
	s_addc_u32 s13, s13, 0
	s_add_u32 s52, s52, 0x100
	s_addc_u32 s53, s53, 0
	s_cmp_gt_u32 s54, 29
	s_barrier
	s_cbranch_scc0 .LBB0_678
	s_ashr_i32 s1, s48, 4
	v_lshl_add_u32 v174, s48, 8, v179
	v_lshl_or_b32 v172, s49, 8, v157
	s_mul_hi_i32 s7, s1, 0x6000
	s_mulk_i32 s1, 0x6000
	v_ashrrev_i32_e32 v175, 31, v174
	s_add_u32 s12, s23, s1
	v_ashrrev_i32_e32 v173, 31, v172
	v_lshlrev_b64 v[170:171], 11, v[174:175]
	s_addc_u32 s13, s24, s7
	v_lshl_add_u64 v[170:171], v[170:171], 0, v[172:173]
	v_lshl_add_u64 v[72:73], v[172:173], 2, s[12:13]
	v_lshl_add_u64 v[198:199], v[170:171], 2, s[80:81]
	global_load_dwordx4 v[84:87], v[72:73], off offset:16
	global_load_dwordx4 v[88:91], v[72:73], off
	global_load_dwordx4 v[68:71], v[72:73], off offset:528
	s_nop 0
	global_load_dwordx4 v[72:75], v[72:73], off offset:512
	s_mov_b64 s[98:99], 0x0
	v_lshl_add_u64 v[248:249], v[198:199], 0, s[98:99]
	global_load_dwordx4 v[200:203], v[248:249], off offset:16
	global_load_dwordx4 v[204:207], v[248:249], off
	s_mov_b64 s[98:99], 0x0
	v_lshl_add_u64 v[248:249], v[198:199], 0, s[98:99]
	global_load_dwordx4 v[208:211], v[248:249], off offset:528
	global_load_dwordx4 v[212:215], v[248:249], off offset:512
	s_mov_b64 s[98:99], 0x20000
	v_lshl_add_u64 v[248:249], v[198:199], 0, s[98:99]
	global_load_dwordx4 v[216:219], v[248:249], off offset:16
	global_load_dwordx4 v[220:223], v[248:249], off
	s_mov_b64 s[98:99], 0x20000
	v_lshl_add_u64 v[248:249], v[198:199], 0, s[98:99]
	global_load_dwordx4 v[224:227], v[248:249], off offset:528
	global_load_dwordx4 v[228:231], v[248:249], off offset:512
	s_mov_b64 s[98:99], 0x40000
	v_lshl_add_u64 v[248:249], v[198:199], 0, s[98:99]
	global_load_dwordx4 v[232:235], v[248:249], off offset:16
	global_load_dwordx4 v[236:239], v[248:249], off
	s_mov_b64 s[98:99], 0x40000
	v_lshl_add_u64 v[248:249], v[198:199], 0, s[98:99]
	global_load_dwordx4 v[240:243], v[248:249], off offset:528
	global_load_dwordx4 v[244:247], v[248:249], off offset:512
	s_nop 0
	s_nop 1
	s_waitcnt vmcnt(10)
	v_mov_b32_e32 v190, v200
	v_mov_b32_e32 v191, v201
	v_mov_b32_e32 v192, v202
	v_mov_b32_e32 v193, v203
	s_nop 1
	v_mov_b32_e32 v194, v204
	v_mov_b32_e32 v195, v205
	v_mov_b32_e32 v196, v206
	v_mov_b32_e32 v197, v207
	s_mov_b64 s[98:99], 0x60000
	v_lshl_add_u64 v[248:249], v[198:199], 0, s[98:99]
	global_load_dwordx4 v[200:203], v[248:249], off offset:16
	global_load_dwordx4 v[204:207], v[248:249], off
	s_mov_b64 s[12:13], 0x40000
	s_and_b64 vcc, exec, s[4:5]
	s_mov_b32 s49, s0
	s_mov_b32 s48, s6
	s_mov_b64 s[14:15], s[10:11]
	s_nop 0
	v_pk_fma_f32 v[142:143], v[142:143], v[86:87], v[192:193]
	v_pk_fma_f32 v[146:147], v[146:147], v[90:91], v[196:197]
	v_pk_fma_f32 v[144:145], v[144:145], v[88:89], v[194:195]
	v_pk_fma_f32 v[190:191], v[140:141], v[84:85], v[190:191]
	v_cvt_pk_f16_f32 v143, v142, v143
	v_cvt_pk_f16_f32 v141, v146, v147
	v_cvt_pk_f16_f32 v142, v190, v191
	v_cvt_pk_f16_f32 v140, v144, v145
	v_lshl_add_u64 v[190:191], v[170:171], 1, s[16:17]
	global_store_dwordx4 v[190:191], v[140:143], off
	s_nop 1
	s_waitcnt vmcnt(10)
;     __device__ __forceinline__ void operator()(const f32x4 (&acc)[2][2][4][2], const pg8::Unit& u, int wr, int wc, int fr, int fq) const {
;     ...
;         for (int ai = 0; ai < 2; ++ai)
; #pragma unroll
;             for (int m = 0; m < 4; ++m) { const size_t ro = (size_t)(row0 + ai * 128 + m * 16) * DM + col0;
; #pragma unroll
;                 for (int bj = 0; bj < 2; ++bj) {
;                     f32x4 x0, x1;
;                     if (XF32) { x0 = *(const f32x4*)(xin + ro + bj * 128); x1 = *(const f32x4*)(xin + ro + bj * 128 + 4); }
;                     else { const h8 xh = *(const h8*)(H + ro + bj * 128); x0 = (f32x4){(float)xh[0], (float)xh[1], (float)xh[2], (float)xh[3]}; x1 = (f32x4){(float)xh[4], (float)xh[5], (float)xh[6], (float)xh[7]}; }
;                     const f32x4 y0 = x0 + gv[bj][0] * acc[ai][bj][m][0], y1 = x1 + gv[bj][1] * acc[ai][bj][m][1];
;                     h8 o; o[0] = (half_t)y0[0]; o[1] = (half_t)y0[1]; o[2] = (half_t)y0[2]; o[3] = (half_t)y0[3]; o[4] = (half_t)y1[0]; o[5] = (half_t)y1[1]; o[6] = (half_t)y1[2]; o[7] = (half_t)y1[3];
;                     *(h8*)(H + ro + bj * 128) = o; } }
	v_mov_b32_e32 v140, v208
	v_mov_b32_e32 v141, v209
	v_mov_b32_e32 v142, v210
	v_mov_b32_e32 v143, v211
	s_nop 0
	s_nop 1
	v_mov_b32_e32 v144, v212
	v_mov_b32_e32 v145, v213
	v_mov_b32_e32 v146, v214
	v_mov_b32_e32 v147, v215
	s_mov_b64 s[98:99], 0x60000
	v_lshl_add_u64 v[248:249], v[198:199], 0, s[98:99]
	global_load_dwordx4 v[208:211], v[248:249], off offset:528
	global_load_dwordx4 v[212:215], v[248:249], off offset:512
	s_nop 0
	v_pk_fma_f32 v[134:135], v[134:135], v[70:71], v[142:143]
	v_pk_fma_f32 v[138:139], v[138:139], v[74:75], v[146:147]
	v_pk_fma_f32 v[136:137], v[136:137], v[72:73], v[144:145]
	v_pk_fma_f32 v[140:141], v[132:133], v[68:69], v[140:141]
	v_cvt_pk_f16_f32 v135, v134, v135
	v_cvt_pk_f16_f32 v133, v138, v139
	v_cvt_pk_f16_f32 v134, v140, v141
	v_cvt_pk_f16_f32 v132, v136, v137
	global_store_dwordx4 v[190:191], v[132:135], off offset:256
	s_nop 1
	v_or_b32_e32 v132, 16, v174
	v_ashrrev_i32_e32 v133, 31, v132
	v_lshlrev_b64 v[132:133], 11, v[132:133]
	v_lshl_add_u64 v[140:141], v[132:133], 0, v[172:173]
	v_lshl_add_u64 v[142:143], v[140:141], 2, s[80:81]
	s_nop 1
	s_waitcnt vmcnt(10)
	v_mov_b32_e32 v132, v216
	v_mov_b32_e32 v133, v217
	v_mov_b32_e32 v134, v218
	v_mov_b32_e32 v135, v219
	s_nop 1
	v_mov_b32_e32 v136, v220
	v_mov_b32_e32 v137, v221
	v_mov_b32_e32 v138, v222
	v_mov_b32_e32 v139, v223
	s_mov_b64 s[98:99], 0x100000
	v_lshl_add_u64 v[248:249], v[198:199], 0, s[98:99]
	global_load_dwordx4 v[216:219], v[248:249], off offset:16
	global_load_dwordx4 v[220:223], v[248:249], off
	s_nop 0
	v_pk_fma_f32 v[126:127], v[126:127], v[86:87], v[134:135]
	v_pk_fma_f32 v[130:131], v[130:131], v[90:91], v[138:139]
	v_pk_fma_f32 v[128:129], v[128:129], v[88:89], v[136:137]
	v_pk_fma_f32 v[132:133], v[124:125], v[84:85], v[132:133]
	v_cvt_pk_f16_f32 v127, v126, v127
	v_cvt_pk_f16_f32 v125, v130, v131
	v_cvt_pk_f16_f32 v126, v132, v133
	v_cvt_pk_f16_f32 v124, v128, v129
	v_lshl_add_u64 v[132:133], v[140:141], 1, s[16:17]
	global_store_dwordx4 v[132:133], v[124:127], off
	s_nop 1
	s_waitcnt vmcnt(10)
	v_mov_b32_e32 v124, v224
	v_mov_b32_e32 v125, v225
	v_mov_b32_e32 v126, v226
	v_mov_b32_e32 v127, v227
	s_nop 0
	s_nop 1
	v_mov_b32_e32 v128, v228
	v_mov_b32_e32 v129, v229
	v_mov_b32_e32 v130, v230
	v_mov_b32_e32 v131, v231
	s_mov_b64 s[98:99], 0x100000
	v_lshl_add_u64 v[248:249], v[198:199], 0, s[98:99]
	global_load_dwordx4 v[224:227], v[248:249], off offset:528
	global_load_dwordx4 v[228:231], v[248:249], off offset:512
	s_nop 0
	v_pk_fma_f32 v[118:119], v[118:119], v[70:71], v[126:127]
	v_pk_fma_f32 v[122:123], v[122:123], v[74:75], v[130:131]
	v_pk_fma_f32 v[120:121], v[120:121], v[72:73], v[128:129]
	v_pk_fma_f32 v[124:125], v[116:117], v[68:69], v[124:125]
	v_cvt_pk_f16_f32 v119, v118, v119
	v_cvt_pk_f16_f32 v117, v122, v123
	v_cvt_pk_f16_f32 v118, v124, v125
	v_cvt_pk_f16_f32 v116, v120, v121
	global_store_dwordx4 v[132:133], v[116:119], off offset:256
	s_nop 1
	v_or_b32_e32 v116, 32, v174
	v_ashrrev_i32_e32 v117, 31, v116
	v_lshlrev_b64 v[116:117], 11, v[116:117]
	v_lshl_add_u64 v[124:125], v[116:117], 0, v[172:173]
	v_lshl_add_u64 v[126:127], v[124:125], 2, s[80:81]
	s_nop 1
	s_waitcnt vmcnt(10)
	v_mov_b32_e32 v116, v232
	v_mov_b32_e32 v117, v233
	v_mov_b32_e32 v118, v234
	v_mov_b32_e32 v119, v235
	s_nop 1
	v_mov_b32_e32 v120, v236
	v_mov_b32_e32 v121, v237
	v_mov_b32_e32 v122, v238
	v_mov_b32_e32 v123, v239
	s_mov_b64 s[98:99], 0x120000
	v_lshl_add_u64 v[248:249], v[198:199], 0, s[98:99]
	global_load_dwordx4 v[232:235], v[248:249], off offset:16
	global_load_dwordx4 v[236:239], v[248:249], off
	s_nop 0
	v_pk_fma_f32 v[110:111], v[110:111], v[86:87], v[118:119]
	v_pk_fma_f32 v[114:115], v[114:115], v[90:91], v[122:123]
	v_pk_fma_f32 v[112:113], v[112:113], v[88:89], v[120:121]
	v_pk_fma_f32 v[116:117], v[108:109], v[84:85], v[116:117]
	v_cvt_pk_f16_f32 v111, v110, v111
	v_cvt_pk_f16_f32 v109, v114, v115
	v_cvt_pk_f16_f32 v110, v116, v117
	v_cvt_pk_f16_f32 v108, v112, v113
	v_lshl_add_u64 v[116:117], v[124:125], 1, s[16:17]
	global_store_dwordx4 v[116:117], v[108:111], off
	s_nop 1
	s_waitcnt vmcnt(10)
	v_mov_b32_e32 v108, v240
	v_mov_b32_e32 v109, v241
	v_mov_b32_e32 v110, v242
	v_mov_b32_e32 v111, v243
	s_nop 0
	s_nop 1
	v_mov_b32_e32 v112, v244
	v_mov_b32_e32 v113, v245
	v_mov_b32_e32 v114, v246
	v_mov_b32_e32 v115, v247
	s_mov_b64 s[98:99], 0x120000
	v_lshl_add_u64 v[248:249], v[198:199], 0, s[98:99]
	global_load_dwordx4 v[240:243], v[248:249], off offset:528
	global_load_dwordx4 v[244:247], v[248:249], off offset:512
	s_nop 0
	v_pk_fma_f32 v[102:103], v[102:103], v[70:71], v[110:111]
	v_pk_fma_f32 v[106:107], v[106:107], v[74:75], v[114:115]
	v_pk_fma_f32 v[104:105], v[104:105], v[72:73], v[112:113]
	v_pk_fma_f32 v[108:109], v[100:101], v[68:69], v[108:109]
	v_cvt_pk_f16_f32 v103, v102, v103
	v_cvt_pk_f16_f32 v101, v106, v107
	v_cvt_pk_f16_f32 v102, v108, v109
	v_cvt_pk_f16_f32 v100, v104, v105
	global_store_dwordx4 v[116:117], v[100:103], off offset:256
	s_nop 1
	v_or_b32_e32 v100, 48, v174
	v_ashrrev_i32_e32 v101, 31, v100
	v_lshlrev_b64 v[100:101], 11, v[100:101]
	v_lshl_add_u64 v[108:109], v[100:101], 0, v[172:173]
	v_lshl_add_u64 v[110:111], v[108:109], 2, s[80:81]
	s_nop 1
	s_waitcnt vmcnt(10)
;     __device__ __forceinline__ void operator()(const f32x4 (&acc)[2][2][4][2], const pg8::Unit& u, int wr, int wc, int fr, int fq) const {
;     ...
;         for (int ai = 0; ai < 2; ++ai)
; #pragma unroll
;             for (int m = 0; m < 4; ++m) { const size_t ro = (size_t)(row0 + ai * 128 + m * 16) * DM + col0;
; #pragma unroll
;                 for (int bj = 0; bj < 2; ++bj) {
;                     f32x4 x0, x1;
;                     if (XF32) { x0 = *(const f32x4*)(xin + ro + bj * 128); x1 = *(const f32x4*)(xin + ro + bj * 128 + 4); }
;                     else { const h8 xh = *(const h8*)(H + ro + bj * 128); x0 = (f32x4){(float)xh[0], (float)xh[1], (float)xh[2], (float)xh[3]}; x1 = (f32x4){(float)xh[4], (float)xh[5], (float)xh[6], (float)xh[7]}; }
;                     const f32x4 y0 = x0 + gv[bj][0] * acc[ai][bj][m][0], y1 = x1 + gv[bj][1] * acc[ai][bj][m][1];
;                     h8 o; o[0] = (half_t)y0[0]; o[1] = (half_t)y0[1]; o[2] = (half_t)y0[2]; o[3] = (half_t)y0[3]; o[4] = (half_t)y1[0]; o[5] = (half_t)y1[1]; o[6] = (half_t)y1[2]; o[7] = (half_t)y1[3];
;                     *(h8*)(H + ro + bj * 128) = o; } }
	v_mov_b32_e32 v100, v200
	v_mov_b32_e32 v101, v201
	v_mov_b32_e32 v102, v202
	v_mov_b32_e32 v103, v203
	s_nop 1
	v_mov_b32_e32 v104, v204
	v_mov_b32_e32 v105, v205
	v_mov_b32_e32 v106, v206
	v_mov_b32_e32 v107, v207
	s_mov_b64 s[98:99], 0x140000
	v_lshl_add_u64 v[248:249], v[198:199], 0, s[98:99]
	global_load_dwordx4 v[200:203], v[248:249], off offset:16
	global_load_dwordx4 v[204:207], v[248:249], off
	s_nop 0
	v_pk_fma_f32 v[94:95], v[94:95], v[86:87], v[102:103]
	v_pk_fma_f32 v[98:99], v[98:99], v[90:91], v[106:107]
	v_pk_fma_f32 v[96:97], v[96:97], v[88:89], v[104:105]
	v_pk_fma_f32 v[100:101], v[92:93], v[84:85], v[100:101]
	v_cvt_pk_f16_f32 v95, v94, v95
	v_cvt_pk_f16_f32 v93, v98, v99
	v_cvt_pk_f16_f32 v94, v100, v101
	v_cvt_pk_f16_f32 v92, v96, v97
	v_lshl_add_u64 v[100:101], v[108:109], 1, s[16:17]
	global_store_dwordx4 v[100:101], v[92:95], off
	s_nop 1
	s_waitcnt vmcnt(10)
	v_mov_b32_e32 v92, v208
	v_mov_b32_e32 v93, v209
	v_mov_b32_e32 v94, v210
	v_mov_b32_e32 v95, v211
	s_nop 0
	s_nop 1
	v_mov_b32_e32 v96, v212
	v_mov_b32_e32 v97, v213
	v_mov_b32_e32 v98, v214
	v_mov_b32_e32 v99, v215
	s_mov_b64 s[98:99], 0x140000
	v_lshl_add_u64 v[248:249], v[198:199], 0, s[98:99]
	global_load_dwordx4 v[208:211], v[248:249], off offset:528
	global_load_dwordx4 v[212:215], v[248:249], off offset:512
	s_nop 0
	v_pk_fma_f32 v[78:79], v[78:79], v[70:71], v[94:95]
	v_pk_fma_f32 v[82:83], v[82:83], v[74:75], v[98:99]
	v_pk_fma_f32 v[80:81], v[80:81], v[72:73], v[96:97]
	v_pk_fma_f32 v[92:93], v[76:77], v[68:69], v[92:93]
	v_cvt_pk_f16_f32 v79, v78, v79
	v_cvt_pk_f16_f32 v77, v82, v83
	v_cvt_pk_f16_f32 v78, v92, v93
	v_cvt_pk_f16_f32 v76, v80, v81
	v_lshl_add_u64 v[92:93], v[170:171], 0, s[12:13]
	global_store_dwordx4 v[100:101], v[76:79], off offset:256
	v_lshl_add_u64 v[94:95], v[92:93], 2, s[80:81]
	s_nop 1
	s_waitcnt vmcnt(10)
	v_mov_b32_e32 v76, v216
	v_mov_b32_e32 v77, v217
	v_mov_b32_e32 v78, v218
	v_mov_b32_e32 v79, v219
	s_nop 1
	v_mov_b32_e32 v80, v220
	v_mov_b32_e32 v81, v221
	v_mov_b32_e32 v82, v222
	v_mov_b32_e32 v83, v223
	s_mov_b64 s[98:99], 0x160000
	v_lshl_add_u64 v[248:249], v[198:199], 0, s[98:99]
	global_load_dwordx4 v[216:219], v[248:249], off offset:16
	global_load_dwordx4 v[220:223], v[248:249], off
	s_mov_b64 s[12:13], 0x48000
	s_nop 0
	v_pk_fma_f32 v[62:63], v[62:63], v[86:87], v[78:79]
	v_pk_fma_f32 v[66:67], v[66:67], v[90:91], v[82:83]
	v_pk_fma_f32 v[64:65], v[64:65], v[88:89], v[80:81]
	v_pk_fma_f32 v[76:77], v[60:61], v[84:85], v[76:77]
	v_cvt_pk_f16_f32 v63, v62, v63
	v_cvt_pk_f16_f32 v61, v66, v67
	v_cvt_pk_f16_f32 v62, v76, v77
	v_cvt_pk_f16_f32 v60, v64, v65
	v_lshl_add_u64 v[76:77], v[92:93], 1, s[16:17]
	global_store_dwordx4 v[76:77], v[60:63], off
	s_nop 1
	s_waitcnt vmcnt(10)
	v_mov_b32_e32 v60, v224
	v_mov_b32_e32 v61, v225
	v_mov_b32_e32 v62, v226
	v_mov_b32_e32 v63, v227
	s_nop 0
	s_nop 1
	v_mov_b32_e32 v64, v228
	v_mov_b32_e32 v65, v229
	v_mov_b32_e32 v66, v230
	v_mov_b32_e32 v67, v231
	s_mov_b64 s[98:99], 0x160000
	v_lshl_add_u64 v[248:249], v[198:199], 0, s[98:99]
	global_load_dwordx4 v[224:227], v[248:249], off offset:528
	global_load_dwordx4 v[228:231], v[248:249], off offset:512
	s_nop 0
	v_pk_fma_f32 v[54:55], v[54:55], v[70:71], v[62:63]
	v_pk_fma_f32 v[58:59], v[58:59], v[74:75], v[66:67]
	v_pk_fma_f32 v[56:57], v[56:57], v[72:73], v[64:65]
	v_pk_fma_f32 v[60:61], v[52:53], v[68:69], v[60:61]
	v_cvt_pk_f16_f32 v55, v54, v55
	v_cvt_pk_f16_f32 v53, v58, v59
	v_cvt_pk_f16_f32 v54, v60, v61
	v_cvt_pk_f16_f32 v52, v56, v57
	v_lshl_add_u64 v[60:61], v[170:171], 0, s[12:13]
	global_store_dwordx4 v[76:77], v[52:55], off offset:256
	v_lshl_add_u64 v[62:63], v[60:61], 2, s[80:81]
	s_nop 1
	s_waitcnt vmcnt(10)
	v_mov_b32_e32 v52, v232
	v_mov_b32_e32 v53, v233
	v_mov_b32_e32 v54, v234
	v_mov_b32_e32 v55, v235
	s_nop 1
	v_mov_b32_e32 v56, v236
	v_mov_b32_e32 v57, v237
	v_mov_b32_e32 v58, v238
	v_mov_b32_e32 v59, v239
	s_mov_b64 s[12:13], 0x50000
	s_nop 0
	v_pk_fma_f32 v[46:47], v[46:47], v[86:87], v[54:55]
	v_pk_fma_f32 v[50:51], v[50:51], v[90:91], v[58:59]
	v_pk_fma_f32 v[48:49], v[48:49], v[88:89], v[56:57]
	v_pk_fma_f32 v[52:53], v[44:45], v[84:85], v[52:53]
	v_cvt_pk_f16_f32 v47, v46, v47
	v_cvt_pk_f16_f32 v45, v50, v51
	v_cvt_pk_f16_f32 v46, v52, v53
	v_cvt_pk_f16_f32 v44, v48, v49
	v_lshl_add_u64 v[52:53], v[60:61], 1, s[16:17]
	global_store_dwordx4 v[52:53], v[44:47], off
	s_nop 1
	s_waitcnt vmcnt(8)
; #define PG8_WAIT_V(n) asm volatile("s_waitcnt vmcnt(" #n ")" ::: "memory")
; #define PG8_BAR __builtin_amdgcn_s_barrier()
; template <class Epi>
; __device__ __forceinline__ void gemm_phase(LAS unsigned char* lds, const Gemm g, const StaticOrder& S, const Epi& E, const int tid) {
;     ...
;         if (!has_next) break;
; #pragma unroll
;         for (int a = 0; a < 2; ++a)
; #pragma unroll
;             for (int b = 0; b < 2; ++b)
; #pragma unroll
;                 for (int m = 0; m < 4; ++m)
; #pragma unroll
;                     for (int n = 0; n < 2; ++n) acc[a][b][m][n] = (f32x4){0.f, 0.f, 0.f, 0.f};
;         cur = nxt; cA = nA; cB = nB; ++ui;
;     }
;     PG8_WAIT_V(0);
;     if (wr == 0) PG8_BAR;
;     PG8_BAR;
;     __device__ __forceinline__ void operator()(const f32x4 (&acc)[2][2][4][2], const pg8::Unit& u, int wr, int wc, int fr, int fq) const {
;     ...
;         for (int ai = 0; ai < 2; ++ai)
; #pragma unroll
;             for (int m = 0; m < 4; ++m) { const size_t ro = (size_t)(row0 + ai * 128 + m * 16) * DM + col0;
; #pragma unroll
;                 for (int bj = 0; bj < 2; ++bj) {
;                     f32x4 x0, x1;
;                     if (XF32) { x0 = *(const f32x4*)(xin + ro + bj * 128); x1 = *(const f32x4*)(xin + ro + bj * 128 + 4); }
;                     else { const h8 xh = *(const h8*)(H + ro + bj * 128); x0 = (f32x4){(float)xh[0], (float)xh[1], (float)xh[2], (float)xh[3]}; x1 = (f32x4){(float)xh[4], (float)xh[5], (float)xh[6], (float)xh[7]}; }
;                     const f32x4 y0 = x0 + gv[bj][0] * acc[ai][bj][m][0], y1 = x1 + gv[bj][1] * acc[ai][bj][m][1];
;                     h8 o; o[0] = (half_t)y0[0]; o[1] = (half_t)y0[1]; o[2] = (half_t)y0[2]; o[3] = (half_t)y0[3]; o[4] = (half_t)y1[0]; o[5] = (half_t)y1[1]; o[6] = (half_t)y1[2]; o[7] = (half_t)y1[3];
;                     *(h8*)(H + ro + bj * 128) = o; } }
	v_mov_b32_e32 v44, v240
	v_mov_b32_e32 v45, v241
	v_mov_b32_e32 v46, v242
	v_mov_b32_e32 v47, v243
	s_nop 0
	s_nop 1
	v_mov_b32_e32 v48, v244
	v_mov_b32_e32 v49, v245
	v_mov_b32_e32 v50, v246
	v_mov_b32_e32 v51, v247
	s_nop 0
	v_pk_fma_f32 v[38:39], v[38:39], v[70:71], v[46:47]
	v_pk_fma_f32 v[42:43], v[42:43], v[74:75], v[50:51]
	v_pk_fma_f32 v[40:41], v[40:41], v[72:73], v[48:49]
	v_pk_fma_f32 v[44:45], v[36:37], v[68:69], v[44:45]
	v_cvt_pk_f16_f32 v39, v38, v39
	v_cvt_pk_f16_f32 v37, v42, v43
	v_cvt_pk_f16_f32 v38, v44, v45
	v_cvt_pk_f16_f32 v36, v40, v41
	v_lshl_add_u64 v[44:45], v[170:171], 0, s[12:13]
	global_store_dwordx4 v[52:53], v[36:39], off offset:256
	v_lshl_add_u64 v[46:47], v[44:45], 2, s[80:81]
	s_nop 1
	s_waitcnt vmcnt(6)
	v_mov_b32_e32 v36, v200
	v_mov_b32_e32 v37, v201
	v_mov_b32_e32 v38, v202
	v_mov_b32_e32 v39, v203
	s_nop 1
	v_mov_b32_e32 v40, v204
	v_mov_b32_e32 v41, v205
	v_mov_b32_e32 v42, v206
	v_mov_b32_e32 v43, v207
	s_mov_b64 s[12:13], 0x58000
	s_nop 0
	v_pk_fma_f32 v[30:31], v[30:31], v[86:87], v[38:39]
	v_pk_fma_f32 v[34:35], v[34:35], v[90:91], v[42:43]
	v_pk_fma_f32 v[32:33], v[32:33], v[88:89], v[40:41]
	v_pk_fma_f32 v[36:37], v[28:29], v[84:85], v[36:37]
	v_cvt_pk_f16_f32 v31, v30, v31
	v_cvt_pk_f16_f32 v29, v34, v35
	v_cvt_pk_f16_f32 v30, v36, v37
	v_cvt_pk_f16_f32 v28, v32, v33
	v_lshl_add_u64 v[36:37], v[44:45], 1, s[16:17]
	global_store_dwordx4 v[36:37], v[28:31], off
	s_nop 1
	s_waitcnt vmcnt(4)
	v_mov_b32_e32 v28, v208
	v_mov_b32_e32 v29, v209
	v_mov_b32_e32 v30, v210
	v_mov_b32_e32 v31, v211
	s_nop 0
	s_nop 1
	v_mov_b32_e32 v32, v212
	v_mov_b32_e32 v33, v213
	v_mov_b32_e32 v34, v214
	v_mov_b32_e32 v35, v215
	s_nop 0
	v_pk_fma_f32 v[22:23], v[22:23], v[70:71], v[30:31]
	v_pk_fma_f32 v[26:27], v[26:27], v[74:75], v[34:35]
	v_pk_fma_f32 v[24:25], v[24:25], v[72:73], v[32:33]
	v_pk_fma_f32 v[28:29], v[20:21], v[68:69], v[28:29]
	v_cvt_pk_f16_f32 v23, v22, v23
	v_cvt_pk_f16_f32 v21, v26, v27
	v_cvt_pk_f16_f32 v22, v28, v29
	v_cvt_pk_f16_f32 v20, v24, v25
	v_lshl_add_u64 v[28:29], v[170:171], 0, s[12:13]
	global_store_dwordx4 v[36:37], v[20:23], off offset:256
	v_lshl_add_u64 v[30:31], v[28:29], 2, s[80:81]
	s_nop 1
	s_waitcnt vmcnt(2)
	v_mov_b32_e32 v20, v216
	v_mov_b32_e32 v21, v217
	v_mov_b32_e32 v22, v218
	v_mov_b32_e32 v23, v219
	s_nop 1
	v_mov_b32_e32 v24, v220
	v_mov_b32_e32 v25, v221
	v_mov_b32_e32 v26, v222
	v_mov_b32_e32 v27, v223
	s_mov_b64 s[12:13], s[8:9]
	s_nop 0
	v_pk_fma_f32 v[14:15], v[14:15], v[86:87], v[22:23]
	v_pk_fma_f32 v[18:19], v[18:19], v[90:91], v[26:27]
	v_pk_fma_f32 v[16:17], v[16:17], v[88:89], v[24:25]
	v_pk_fma_f32 v[20:21], v[12:13], v[84:85], v[20:21]
	v_cvt_pk_f16_f32 v15, v14, v15
	v_cvt_pk_f16_f32 v13, v18, v19
	v_cvt_pk_f16_f32 v14, v20, v21
	v_cvt_pk_f16_f32 v12, v16, v17
	v_lshl_add_u64 v[20:21], v[28:29], 1, s[16:17]
	global_store_dwordx4 v[20:21], v[12:15], off
	s_nop 1
	s_waitcnt vmcnt(0)
	v_mov_b32_e32 v12, v224
	v_mov_b32_e32 v13, v225
	v_mov_b32_e32 v14, v226
	v_mov_b32_e32 v15, v227
	s_nop 0
	s_nop 1
	v_mov_b32_e32 v16, v228
	v_mov_b32_e32 v17, v229
	v_mov_b32_e32 v18, v230
	v_mov_b32_e32 v19, v231
	s_nop 0
	v_pk_fma_f32 v[6:7], v[6:7], v[70:71], v[14:15]
	v_pk_fma_f32 v[10:11], v[10:11], v[74:75], v[18:19]
	v_pk_fma_f32 v[8:9], v[8:9], v[72:73], v[16:17]
	v_pk_fma_f32 v[12:13], v[4:5], v[68:69], v[12:13]
	v_cvt_pk_f16_f32 v7, v6, v7
	v_cvt_pk_f16_f32 v5, v10, v11
	v_cvt_pk_f16_f32 v6, v12, v13
	v_cvt_pk_f16_f32 v4, v8, v9
	global_store_dwordx4 v[20:21], v[4:7], off offset:256
	s_cbranch_vccz .LBB0_671
	s_waitcnt vmcnt(0)
	v_readlane_b32 s42, v251, 7
	v_readlane_b32 s46, v251, 9
	v_readlane_b32 s48, v251, 13
	s_cmpk_gt_u32 s25, 0xff
	v_readlane_b32 s43, v251, 8
	v_readlane_b32 s47, v251, 10
	v_readlane_b32 s49, v251, 14
	s_cbranch_scc1 .LBB0_682
	s_barrier
